# prompt attention tile loops: exact vmcnt(7..4) at each consume (other staging set stays in flight), dummy loads on no-load paths keep the counts exact
# speedup vs baseline: 1.0027x; 1.0027x over previous
; __device__ __forceinline__ unsigned cvtpk(float lo, float hi) { unsigned r; asm volatile("v_cvt_pk_bf16_f32 %0, %1, %2" : "=v"(r) : "v"(lo), "v"(hi)); return r; }
; __device__ __forceinline__ int crow(int r, int hi) { return (r & 3) + 8 * (r >> 2) + 4 * hi; }
; template <int MODE, bool SAMPLE>
; __device__ __forceinline__ void attn_unit(const Params& p, char* lds, int b, int h, int qb) {
;     ...
;     if (wact && var < 1) {
;         bf16_t* MIX = (bf16_t*)(p.ws + (var == 0 ? WS_MIX : WS_ACT));
;         const size_t rbase = SAMPLE ? (size_t)(MP + b * TS) : (size_t)(b * SEQ + qb * 256 + wid * 32);
;         constexpr int NIT = SAMPLE ? 4 : 8; const int er = lane >> 4, ec = (lane & 15) * 8;
;         float rli[16];
;         if (MODE == 0) { if (hi == 0) wsc[32 + r32] = l_reg; asm volatile("s_waitcnt lgkmcnt(0)" ::: "memory");
; #pragma unroll
;             for (int r = 0; r < 16; ++r) rli[r] = __builtin_amdgcn_rcpf(wsc[32 + crow(r, hi)]); }
; #pragma unroll
;         for (int r = 0; r < 16; ++r) { const int orow = crow(r, hi);
;             if (!SAMPLE || orow < TS) {
; #pragma unroll
;                 for (int d0 = 0; d0 < 4; ++d0) { float ov = o[d0][r]; if (MODE == 0) ov *= rli[r];
;                     const unsigned pk = cvtpk(ov, 0.f); *(bf16_t*)(Qs + orow * 256 + (d0 * 32 + r32) * 2) = (bf16_t)(pk & 0xffffu); } } }
;         asm volatile("s_waitcnt lgkmcnt(0)" ::: "memory");
;         bf16x8 gt[NIT];
; #pragma unroll
;         for (int it = 0; it < NIT; ++it) gt[it] = __builtin_nontemporal_load((const bf16x8*)(P1q + 24 * HB + (rbase + it * 4 + er) * 128 + ec));
; #pragma unroll
;         for (int it = 0; it < NIT; ++it) { const int row = it * 4 + er; const bf16x8 mx = *(const bf16x8*)(Qs + row * 256 + ec * 2); f32x8 y;
.LBB0_650:
	s_waitcnt vmcnt(0)
	v_add3_u32 v64, s12, v193, v192
	v_cvt_pk_bf16_f32 v48, v48, v129
	ds_write_b16 v64, v48
	v_cvt_pk_bf16_f32 v32, v32, v129
	ds_write_b16 v64, v32 offset:64
	v_cvt_pk_bf16_f32 v16, v16, v129
	ds_write_b16 v64, v16 offset:128
	v_cvt_pk_bf16_f32 v0, v0, v129
	s_nop 2
	ds_write_b16 v64, v0 offset:192
	v_cvt_pk_bf16_f32 v0, v49, v129
	ds_write_b16 v64, v0 offset:256
	v_cvt_pk_bf16_f32 v0, v33, v129
	ds_write_b16 v64, v0 offset:320
	v_cvt_pk_bf16_f32 v0, v17, v129
	ds_write_b16 v64, v0 offset:384
	v_cvt_pk_bf16_f32 v0, v1, v129
	ds_write_b16 v64, v0 offset:448
	v_cvt_pk_bf16_f32 v0, v50, v129
	ds_write_b16 v64, v0 offset:512
	v_cvt_pk_bf16_f32 v0, v34, v129
	ds_write_b16 v64, v0 offset:576
	v_cvt_pk_bf16_f32 v0, v18, v129
	ds_write_b16 v64, v0 offset:640
	v_cvt_pk_bf16_f32 v0, v2, v129
	ds_write_b16 v64, v0 offset:704
	v_cvt_pk_bf16_f32 v0, v51, v129
	ds_write_b16 v64, v0 offset:768
	v_cvt_pk_bf16_f32 v0, v35, v129
	ds_write_b16 v64, v0 offset:832
	v_cvt_pk_bf16_f32 v0, v19, v129
	ds_write_b16 v64, v0 offset:896
	v_cvt_pk_bf16_f32 v0, v3, v129
	ds_write_b16 v64, v0 offset:960
	v_cvt_pk_bf16_f32 v0, v52, v129
	ds_write_b16 v64, v0 offset:2048
	v_cvt_pk_bf16_f32 v0, v36, v129
	ds_write_b16 v64, v0 offset:2112
	v_cvt_pk_bf16_f32 v0, v20, v129
	ds_write_b16 v64, v0 offset:2176
	v_cvt_pk_bf16_f32 v0, v4, v129
	ds_write_b16 v64, v0 offset:2240
	v_cvt_pk_bf16_f32 v0, v53, v129
	ds_write_b16 v64, v0 offset:2304
	v_cvt_pk_bf16_f32 v0, v37, v129
	ds_write_b16 v64, v0 offset:2368
	v_cvt_pk_bf16_f32 v0, v21, v129
	ds_write_b16 v64, v0 offset:2432
	v_cvt_pk_bf16_f32 v0, v5, v129
	ds_write_b16 v64, v0 offset:2496
	v_cvt_pk_bf16_f32 v0, v54, v129
	ds_write_b16 v64, v0 offset:2560
	v_cvt_pk_bf16_f32 v0, v38, v129
	ds_write_b16 v64, v0 offset:2624
	v_cvt_pk_bf16_f32 v0, v22, v129
	ds_write_b16 v64, v0 offset:2688
	v_cvt_pk_bf16_f32 v0, v6, v129
	ds_write_b16 v64, v0 offset:2752
	v_cvt_pk_bf16_f32 v0, v55, v129
	ds_write_b16 v64, v0 offset:2816
	v_cvt_pk_bf16_f32 v0, v39, v129
	ds_write_b16 v64, v0 offset:2880
	v_cvt_pk_bf16_f32 v0, v23, v129
	ds_write_b16 v64, v0 offset:2944
	v_cvt_pk_bf16_f32 v0, v7, v129
	ds_write_b16 v64, v0 offset:3008
	v_cvt_pk_bf16_f32 v0, v56, v129
	ds_write_b16 v64, v0 offset:4096
	v_cvt_pk_bf16_f32 v0, v40, v129
	ds_write_b16 v64, v0 offset:4160
	v_cvt_pk_bf16_f32 v0, v24, v129
	ds_write_b16 v64, v0 offset:4224
	v_cvt_pk_bf16_f32 v0, v8, v129
	ds_write_b16 v64, v0 offset:4288
	v_cvt_pk_bf16_f32 v0, v57, v129
	ds_write_b16 v64, v0 offset:4352
	v_cvt_pk_bf16_f32 v0, v41, v129
	ds_write_b16 v64, v0 offset:4416
	v_cvt_pk_bf16_f32 v0, v25, v129
	ds_write_b16 v64, v0 offset:4480
	v_cvt_pk_bf16_f32 v0, v9, v129
	ds_write_b16 v64, v0 offset:4544
	v_cvt_pk_bf16_f32 v0, v58, v129
	ds_write_b16 v64, v0 offset:4608
	v_cvt_pk_bf16_f32 v0, v42, v129
	ds_write_b16 v64, v0 offset:4672
	v_cvt_pk_bf16_f32 v0, v26, v129
	ds_write_b16 v64, v0 offset:4736
	v_cvt_pk_bf16_f32 v0, v10, v129
	ds_write_b16 v64, v0 offset:4800
	v_cvt_pk_bf16_f32 v0, v59, v129
	ds_write_b16 v64, v0 offset:4864
	v_cvt_pk_bf16_f32 v0, v43, v129
	ds_write_b16 v64, v0 offset:4928
	v_cvt_pk_bf16_f32 v0, v27, v129
	ds_write_b16 v64, v0 offset:4992
	v_cvt_pk_bf16_f32 v0, v11, v129
	ds_write_b16 v64, v0 offset:5056
	v_cvt_pk_bf16_f32 v0, v60, v129
	ds_write_b16 v64, v0 offset:6144
	v_cvt_pk_bf16_f32 v0, v44, v129
	ds_write_b16 v64, v0 offset:6208
	v_cvt_pk_bf16_f32 v0, v28, v129
	ds_write_b16 v64, v0 offset:6272
	v_cvt_pk_bf16_f32 v0, v12, v129
	ds_write_b16 v64, v0 offset:6336
	v_cvt_pk_bf16_f32 v0, v61, v129
	ds_write_b16 v64, v0 offset:6400
	v_cvt_pk_bf16_f32 v0, v45, v129
	ds_write_b16 v64, v0 offset:6464
	v_cvt_pk_bf16_f32 v0, v29, v129
	ds_write_b16 v64, v0 offset:6528
	v_cvt_pk_bf16_f32 v0, v13, v129
	ds_write_b16 v64, v0 offset:6592
	v_cvt_pk_bf16_f32 v0, v62, v129
	ds_write_b16 v64, v0 offset:6656
	v_cvt_pk_bf16_f32 v0, v46, v129
	ds_write_b16 v64, v0 offset:6720
	v_cvt_pk_bf16_f32 v0, v30, v129
	ds_write_b16 v64, v0 offset:6784
	v_cvt_pk_bf16_f32 v0, v14, v129
	ds_write_b16 v64, v0 offset:6848
	v_cvt_pk_bf16_f32 v0, v63, v129
	ds_write_b16 v64, v0 offset:6912
	v_cvt_pk_bf16_f32 v0, v47, v129
	ds_write_b16 v64, v0 offset:6976
	v_cvt_pk_bf16_f32 v0, v31, v129
	ds_write_b16 v64, v0 offset:7040
	v_cvt_pk_bf16_f32 v0, v15, v129
	v_mov_b32_e32 v145, v129
	ds_write_b16 v64, v0 offset:7104
	v_or_b32_e32 v34, s11, v130
	v_lshl_add_u64 v[0:1], s[82:83], 0, v[144:145]
	s_mov_b64 s[0:1], 0x10200000
	v_mov_b32_e32 v35, v129
	v_lshl_add_u64 v[4:5], v[0:1], 0, s[0:1]
	v_lshlrev_b64 v[0:1], 8, v[34:35]
	s_waitcnt lgkmcnt(0)
	v_lshl_add_u64 v[0:1], v[4:5], 0, v[0:1]
	global_load_dwordx4 v[0:3], v[0:1], off nt
	v_or_b32_e32 v6, 4, v34
	v_mov_b32_e32 v7, v129
	v_lshlrev_b64 v[6:7], 8, v[6:7]
	v_lshl_add_u64 v[8:9], v[4:5], 0, v[6:7]
	v_or_b32_e32 v6, 8, v34
	v_mov_b32_e32 v7, v129
	v_lshlrev_b64 v[6:7], 8, v[6:7]
	v_lshl_add_u64 v[10:11], v[4:5], 0, v[6:7]
	v_or_b32_e32 v6, 12, v34
	v_mov_b32_e32 v7, v129
	v_lshlrev_b64 v[6:7], 8, v[6:7]
	global_load_dwordx4 v[22:25], v[8:9], off nt
	v_lshl_add_u64 v[12:13], v[4:5], 0, v[6:7]
	v_or_b32_e32 v6, 16, v34
	v_mov_b32_e32 v7, v129
	v_lshlrev_b64 v[6:7], 8, v[6:7]
	v_lshl_add_u64 v[14:15], v[4:5], 0, v[6:7]
	v_or_b32_e32 v6, 20, v34
	v_mov_b32_e32 v7, v129
	v_lshlrev_b64 v[6:7], 8, v[6:7]
	v_lshl_add_u64 v[30:31], v[4:5], 0, v[6:7]
	v_or_b32_e32 v6, 24, v34
	v_mov_b32_e32 v7, v129
	v_lshlrev_b64 v[6:7], 8, v[6:7]
	v_lshl_add_u64 v[32:33], v[4:5], 0, v[6:7]
	v_or_b32_e32 v6, 28, v34
	v_mov_b32_e32 v7, v129
	v_lshlrev_b64 v[6:7], 8, v[6:7]
	v_add_u32_e32 v20, s12, v132
	v_lshl_add_u64 v[36:37], v[4:5], 0, v[6:7]
	v_add_u32_e32 v4, v20, v194
	ds_read_b128 v[4:7], v4
	v_lshlrev_b64 v[34:35], 12, v[34:35]
	v_lshl_add_u64 v[34:35], s[92:93], 0, v[34:35]
	s_lshl_b32 s4, s10, 1
	v_lshl_add_u64 v[34:35], v[34:35], 0, s[4:5]
	s_waitcnt lgkmcnt(0)
; __device__ __forceinline__ float bf2f(short s) { return __uint_as_float(((unsigned)(unsigned short)s) << 16); }
; __device__ __forceinline__ float silu_fast(float g) { return g * __builtin_amdgcn_rcpf(1.f + __builtin_amdgcn_exp2f(-g * LOG2E)); }
; __device__ __forceinline__ bf16x8 tobf8(f32x8 x) { u32x4 w = {cvtpk(x[0], x[1]), cvtpk(x[2], x[3]), cvtpk(x[4], x[5]), cvtpk(x[6], x[7])}; return *reinterpret_cast<bf16x8*>(&w); }
; template <int MODE, bool SAMPLE>
; __device__ __forceinline__ void attn_unit(const Params& p, char* lds, int b, int h, int qb) {
;     ...
;         for (int it = 0; it < NIT; ++it) gt[it] = __builtin_nontemporal_load((const bf16x8*)(P1q + 24 * HB + (rbase + it * 4 + er) * 128 + ec));
; #pragma unroll
;         for (int it = 0; it < NIT; ++it) { const int row = it * 4 + er; const bf16x8 mx = *(const bf16x8*)(Qs + row * 256 + ec * 2); f32x8 y;
; #pragma unroll
;             for (int i = 0; i < 8; ++i) y[i] = bf2f(mx[i]) * silu_fast(bf2f(gt[it][i]));
;             *(bf16x8*)(MIX + (rbase + row) * DM + MODE * 1024 + h * HD + ec) = tobf8(y); }
	v_lshlrev_b32_e32 v17, 16, v4
	v_and_b32_e32 v4, 0xffff0000, v4
	v_lshl_add_u64 v[34:35], v[34:35], 0, v[144:145]
	v_add_co_u32_e32 v34, vcc, s8, v34
	v_readlane_b32 s0, v253, 9
	s_nop 0
	v_addc_co_u32_e32 v35, vcc, 0, v35, vcc
	s_add_i32 s9, s9, s0
	s_cmpk_gt_i32 s9, 0xff
	v_readlane_b32 s1, v253, 10
	s_waitcnt vmcnt(1)
	v_lshlrev_b32_e32 v8, 16, v0
	v_and_b32_e32 v0, 0xffff0000, v0
	v_mul_f32_e32 v16, 0xbfb8aa3b, v0
	v_exp_f32_e32 v16, v16
	v_mul_f32_e32 v9, 0xbfb8aa3b, v8
	v_exp_f32_e32 v9, v9
	v_add_f32_e32 v16, 1.0, v16
	v_rcp_f32_e32 v16, v16
	v_add_f32_e32 v9, 1.0, v9
	v_rcp_f32_e32 v9, v9
	v_mul_f32_e32 v0, v16, v0
	v_mul_f32_e32 v38, v0, v4
	v_lshlrev_b32_e32 v0, 16, v1
	v_mul_f32_e32 v8, v9, v8
	v_mul_f32_e32 v4, 0xbfb8aa3b, v0
	v_and_b32_e32 v1, 0xffff0000, v1
	v_mul_f32_e32 v21, v8, v17
	v_exp_f32_e32 v4, v4
	v_mul_f32_e32 v8, 0xbfb8aa3b, v1
	v_exp_f32_e32 v8, v8
	v_lshlrev_b32_e32 v9, 16, v5
	v_add_f32_e32 v4, 1.0, v4
	v_rcp_f32_e32 v4, v4
	v_add_f32_e32 v8, 1.0, v8
	v_rcp_f32_e32 v8, v8
	v_mul_f32_e32 v0, v4, v0
	v_mul_f32_e32 v39, v0, v9
	v_and_b32_e32 v0, 0xffff0000, v5
	v_mul_f32_e32 v1, v8, v1
	v_mul_f32_e32 v40, v1, v0
	v_lshlrev_b32_e32 v0, 16, v2
	v_mul_f32_e32 v1, 0xbfb8aa3b, v0
	v_and_b32_e32 v2, 0xffff0000, v2
	v_exp_f32_e32 v1, v1
	v_mul_f32_e32 v4, 0xbfb8aa3b, v2
	v_exp_f32_e32 v4, v4
	v_lshlrev_b32_e32 v5, 16, v6
	v_add_f32_e32 v1, 1.0, v1
	v_rcp_f32_e32 v1, v1
	v_add_f32_e32 v4, 1.0, v4
	v_rcp_f32_e32 v4, v4
	v_mul_f32_e32 v0, v1, v0
	v_mul_f32_e32 v41, v0, v5
	v_and_b32_e32 v0, 0xffff0000, v6
	v_mul_f32_e32 v1, v4, v2
	v_mul_f32_e32 v42, v1, v0
	v_lshlrev_b32_e32 v0, 16, v3
	v_mul_f32_e32 v1, 0xbfb8aa3b, v0
	v_and_b32_e32 v2, 0xffff0000, v3
	v_exp_f32_e32 v1, v1
	v_mul_f32_e32 v3, 0xbfb8aa3b, v2
	v_exp_f32_e32 v3, v3
	v_lshlrev_b32_e32 v4, 16, v7
	v_add_f32_e32 v1, 1.0, v1
	v_rcp_f32_e32 v1, v1
	v_add_f32_e32 v3, 1.0, v3
	v_rcp_f32_e32 v3, v3
	v_mul_f32_e32 v0, v1, v0
	v_mul_f32_e32 v43, v0, v4
	v_and_b32_e32 v0, 0xffff0000, v7
	v_mul_f32_e32 v1, v3, v2
	v_mul_f32_e32 v44, v1, v0
	global_load_dwordx4 v[26:29], v[10:11], off nt
	global_load_dwordx4 v[16:19], v[12:13], off nt
	s_nop 0
	global_load_dwordx4 v[12:15], v[14:15], off nt
	s_nop 0
	global_load_dwordx4 v[8:11], v[30:31], off nt
	global_load_dwordx4 v[4:7], v[32:33], off nt
	global_load_dwordx4 v[0:3], v[36:37], off nt
	v_cvt_pk_bf16_f32 v30, v21, v38
	v_cvt_pk_bf16_f32 v31, v39, v40
	v_cvt_pk_bf16_f32 v32, v41, v42
	v_cvt_pk_bf16_f32 v33, v43, v44
	v_add_u32_e32 v21, v20, v195
	global_store_dwordx4 v[34:35], v[30:33], off offset:2048
	ds_read_b128 v[30:33], v21
	s_waitcnt vmcnt(7)
	v_lshlrev_b32_e32 v21, 16, v22
	v_and_b32_e32 v22, 0xffff0000, v22
	v_mul_f32_e32 v35, 0xbfb8aa3b, v22
	v_exp_f32_e32 v35, v35
	v_mul_f32_e32 v34, 0xbfb8aa3b, v21
	v_exp_f32_e32 v34, v34
	s_waitcnt lgkmcnt(0)
	v_lshlrev_b32_e32 v36, 16, v30
	v_add_f32_e32 v35, 1.0, v35
	v_rcp_f32_e32 v35, v35
	v_and_b32_e32 v30, 0xffff0000, v30
	v_add_f32_e32 v34, 1.0, v34
	v_rcp_f32_e32 v34, v34
	v_mul_f32_e32 v22, v35, v22
	v_mul_f32_e32 v22, v22, v30
	v_lshlrev_b32_e32 v30, 16, v23
	v_and_b32_e32 v23, 0xffff0000, v23
	v_mul_f32_e32 v35, 0xbfb8aa3b, v23
	v_exp_f32_e32 v35, v35
	v_mul_f32_e32 v21, v34, v21
	v_mul_f32_e32 v34, 0xbfb8aa3b, v30
	v_exp_f32_e32 v34, v34
	v_add_f32_e32 v35, 1.0, v35
	v_rcp_f32_e32 v35, v35
	v_mul_f32_e32 v21, v21, v36
	v_add_f32_e32 v34, 1.0, v34
	v_lshlrev_b32_e32 v36, 16, v31
	v_and_b32_e32 v31, 0xffff0000, v31
	v_mul_f32_e32 v23, v35, v23
	v_rcp_f32_e32 v34, v34
	v_mul_f32_e32 v23, v23, v31
	v_lshlrev_b32_e32 v31, 16, v24
	v_and_b32_e32 v24, 0xffff0000, v24
	v_mul_f32_e32 v35, 0xbfb8aa3b, v24
	v_exp_f32_e32 v35, v35
	v_mul_f32_e32 v30, v34, v30
	v_mul_f32_e32 v34, 0xbfb8aa3b, v31
	v_exp_f32_e32 v34, v34
	v_add_f32_e32 v35, 1.0, v35
	v_rcp_f32_e32 v35, v35
	v_mul_f32_e32 v30, v30, v36
	v_add_f32_e32 v34, 1.0, v34
	v_rcp_f32_e32 v34, v34
	v_lshlrev_b32_e32 v36, 16, v32
	v_and_b32_e32 v32, 0xffff0000, v32
	v_mul_f32_e32 v24, v35, v24
	v_mul_f32_e32 v24, v24, v32
	v_lshlrev_b32_e32 v32, 16, v25
	v_and_b32_e32 v25, 0xffff0000, v25
	v_mul_f32_e32 v35, 0xbfb8aa3b, v25
	v_mul_f32_e32 v31, v34, v31
	v_mul_f32_e32 v34, 0xbfb8aa3b, v32
	v_exp_f32_e32 v35, v35
	v_exp_f32_e32 v34, v34
	v_mul_f32_e32 v31, v31, v36
	v_cvt_pk_bf16_f32 v22, v21, v22
	v_add_f32_e32 v35, 1.0, v35
	v_add_f32_e32 v34, 1.0, v34
	v_rcp_f32_e32 v35, v35
	v_cvt_pk_bf16_f32 v23, v30, v23
	v_cvt_pk_bf16_f32 v24, v31, v24
	v_or_b32_e32 v30, s11, v136
	v_mov_b32_e32 v31, v129
	v_rcp_f32_e32 v34, v34
	v_lshlrev_b64 v[30:31], 12, v[30:31]
	v_lshl_add_u64 v[30:31], s[92:93], 0, v[30:31]
	v_lshl_add_u64 v[30:31], v[30:31], 0, s[4:5]
	v_lshlrev_b32_e32 v36, 16, v33
	v_and_b32_e32 v33, 0xffff0000, v33
	v_mul_f32_e32 v25, v35, v25
	v_lshl_add_u64 v[30:31], v[30:31], 0, v[144:145]
	v_mul_f32_e32 v32, v34, v32
	v_mul_f32_e32 v25, v25, v33
	v_add_co_u32_e32 v30, vcc, s8, v30
	v_mul_f32_e32 v32, v32, v36
	v_cvt_pk_bf16_f32 v25, v32, v25
	s_nop 0
	v_addc_co_u32_e32 v31, vcc, 0, v31, vcc
	v_add_u32_e32 v21, v20, v196
	global_store_dwordx4 v[30:31], v[22:25], off offset:2048
	ds_read_b128 v[22:25], v21
	s_waitcnt vmcnt(7)
	v_lshlrev_b32_e32 v21, 16, v26
	v_and_b32_e32 v26, 0xffff0000, v26
	v_mul_f32_e32 v31, 0xbfb8aa3b, v26
	v_exp_f32_e32 v31, v31
	v_mul_f32_e32 v30, 0xbfb8aa3b, v21
	v_exp_f32_e32 v30, v30
	s_waitcnt lgkmcnt(0)
; __device__ __forceinline__ float bf2f(short s) { return __uint_as_float(((unsigned)(unsigned short)s) << 16); }
; __device__ __forceinline__ float silu_fast(float g) { return g * __builtin_amdgcn_rcpf(1.f + __builtin_amdgcn_exp2f(-g * LOG2E)); }
; __device__ __forceinline__ bf16x8 tobf8(f32x8 x) { u32x4 w = {cvtpk(x[0], x[1]), cvtpk(x[2], x[3]), cvtpk(x[4], x[5]), cvtpk(x[6], x[7])}; return *reinterpret_cast<bf16x8*>(&w); }
; template <int MODE, bool SAMPLE>
; __device__ __forceinline__ void attn_unit(const Params& p, char* lds, int b, int h, int qb) {
;     ...
;         for (int it = 0; it < NIT; ++it) gt[it] = __builtin_nontemporal_load((const bf16x8*)(P1q + 24 * HB + (rbase + it * 4 + er) * 128 + ec));
; #pragma unroll
;         for (int it = 0; it < NIT; ++it) { const int row = it * 4 + er; const bf16x8 mx = *(const bf16x8*)(Qs + row * 256 + ec * 2); f32x8 y;
; #pragma unroll
;             for (int i = 0; i < 8; ++i) y[i] = bf2f(mx[i]) * silu_fast(bf2f(gt[it][i]));
;             *(bf16x8*)(MIX + (rbase + row) * DM + MODE * 1024 + h * HD + ec) = tobf8(y); }
	v_lshlrev_b32_e32 v32, 16, v22
	v_add_f32_e32 v31, 1.0, v31
	v_rcp_f32_e32 v31, v31
	v_and_b32_e32 v22, 0xffff0000, v22
	v_add_f32_e32 v30, 1.0, v30
	v_rcp_f32_e32 v30, v30
	v_mul_f32_e32 v26, v31, v26
	v_mul_f32_e32 v22, v26, v22
	v_lshlrev_b32_e32 v26, 16, v27
	v_and_b32_e32 v27, 0xffff0000, v27
	v_mul_f32_e32 v31, 0xbfb8aa3b, v27
	v_exp_f32_e32 v31, v31
	v_mul_f32_e32 v21, v30, v21
	v_mul_f32_e32 v30, 0xbfb8aa3b, v26
	v_exp_f32_e32 v30, v30
	v_add_f32_e32 v31, 1.0, v31
	v_rcp_f32_e32 v31, v31
	v_mul_f32_e32 v21, v21, v32
	v_add_f32_e32 v30, 1.0, v30
	v_lshlrev_b32_e32 v32, 16, v23
	v_and_b32_e32 v23, 0xffff0000, v23
	v_mul_f32_e32 v27, v31, v27
	v_rcp_f32_e32 v30, v30
	v_mul_f32_e32 v23, v27, v23
	v_lshlrev_b32_e32 v27, 16, v28
	v_and_b32_e32 v28, 0xffff0000, v28
	v_mul_f32_e32 v31, 0xbfb8aa3b, v28
	v_exp_f32_e32 v31, v31
	v_mul_f32_e32 v26, v30, v26
	v_mul_f32_e32 v30, 0xbfb8aa3b, v27
	v_exp_f32_e32 v30, v30
	v_add_f32_e32 v31, 1.0, v31
	v_rcp_f32_e32 v31, v31
	v_mul_f32_e32 v26, v26, v32
	v_add_f32_e32 v30, 1.0, v30
	v_rcp_f32_e32 v30, v30
	v_lshlrev_b32_e32 v32, 16, v24
	v_and_b32_e32 v24, 0xffff0000, v24
	v_mul_f32_e32 v28, v31, v28
	v_mul_f32_e32 v24, v28, v24
	v_lshlrev_b32_e32 v28, 16, v29
	v_and_b32_e32 v29, 0xffff0000, v29
	v_mul_f32_e32 v31, 0xbfb8aa3b, v29
	v_mul_f32_e32 v27, v30, v27
	v_mul_f32_e32 v30, 0xbfb8aa3b, v28
	v_exp_f32_e32 v31, v31
	v_exp_f32_e32 v30, v30
	v_mul_f32_e32 v27, v27, v32
	v_cvt_pk_bf16_f32 v22, v21, v22
	v_add_f32_e32 v31, 1.0, v31
	v_add_f32_e32 v30, 1.0, v30
	v_rcp_f32_e32 v31, v31
	v_cvt_pk_bf16_f32 v23, v26, v23
	v_cvt_pk_bf16_f32 v24, v27, v24
	v_or_b32_e32 v26, s11, v138
	v_mov_b32_e32 v27, v129
	v_rcp_f32_e32 v30, v30
	v_lshlrev_b64 v[26:27], 12, v[26:27]
	v_lshl_add_u64 v[26:27], s[92:93], 0, v[26:27]
	v_lshl_add_u64 v[26:27], v[26:27], 0, s[4:5]
	v_lshlrev_b32_e32 v32, 16, v25
	v_and_b32_e32 v25, 0xffff0000, v25
	v_mul_f32_e32 v29, v31, v29
	v_lshl_add_u64 v[26:27], v[26:27], 0, v[144:145]
	v_mul_f32_e32 v28, v30, v28
	v_mul_f32_e32 v25, v29, v25
	v_add_co_u32_e32 v26, vcc, s8, v26
	v_mul_f32_e32 v28, v28, v32
	v_cvt_pk_bf16_f32 v25, v28, v25
	s_nop 0
	v_addc_co_u32_e32 v27, vcc, 0, v27, vcc
	v_add_u32_e32 v21, v20, v197
	global_store_dwordx4 v[26:27], v[22:25], off offset:2048
	ds_read_b128 v[22:25], v21
	s_waitcnt vmcnt(7)
	v_lshlrev_b32_e32 v21, 16, v16
	v_and_b32_e32 v16, 0xffff0000, v16
	v_mul_f32_e32 v27, 0xbfb8aa3b, v16
	v_exp_f32_e32 v27, v27
	v_mul_f32_e32 v26, 0xbfb8aa3b, v21
	v_exp_f32_e32 v26, v26
	s_waitcnt lgkmcnt(0)
	v_lshlrev_b32_e32 v28, 16, v22
	v_add_f32_e32 v27, 1.0, v27
	v_rcp_f32_e32 v27, v27
	v_and_b32_e32 v22, 0xffff0000, v22
	v_add_f32_e32 v26, 1.0, v26
	v_rcp_f32_e32 v26, v26
	v_mul_f32_e32 v16, v27, v16
	v_mul_f32_e32 v16, v16, v22
	v_lshlrev_b32_e32 v22, 16, v17
	v_and_b32_e32 v17, 0xffff0000, v17
	v_mul_f32_e32 v27, 0xbfb8aa3b, v17
	v_exp_f32_e32 v27, v27
	v_mul_f32_e32 v21, v26, v21
	v_mul_f32_e32 v26, 0xbfb8aa3b, v22
	v_exp_f32_e32 v26, v26
	v_add_f32_e32 v27, 1.0, v27
	v_rcp_f32_e32 v27, v27
	v_mul_f32_e32 v21, v21, v28
	v_add_f32_e32 v26, 1.0, v26
	v_lshlrev_b32_e32 v28, 16, v23
	v_and_b32_e32 v23, 0xffff0000, v23
	v_mul_f32_e32 v17, v27, v17
	v_rcp_f32_e32 v26, v26
	v_mul_f32_e32 v17, v17, v23
	v_lshlrev_b32_e32 v23, 16, v18
	v_and_b32_e32 v18, 0xffff0000, v18
	v_mul_f32_e32 v27, 0xbfb8aa3b, v18
	v_exp_f32_e32 v27, v27
	v_mul_f32_e32 v22, v26, v22
	v_mul_f32_e32 v26, 0xbfb8aa3b, v23
	v_exp_f32_e32 v26, v26
	v_add_f32_e32 v27, 1.0, v27
	v_rcp_f32_e32 v27, v27
	v_mul_f32_e32 v22, v22, v28
	v_add_f32_e32 v26, 1.0, v26
	v_rcp_f32_e32 v26, v26
	v_lshlrev_b32_e32 v28, 16, v24
	v_and_b32_e32 v24, 0xffff0000, v24
	v_mul_f32_e32 v18, v27, v18
	v_mul_f32_e32 v18, v18, v24
	v_lshlrev_b32_e32 v24, 16, v19
	v_and_b32_e32 v19, 0xffff0000, v19
	v_mul_f32_e32 v27, 0xbfb8aa3b, v19
	v_mul_f32_e32 v23, v26, v23
	v_mul_f32_e32 v26, 0xbfb8aa3b, v24
	v_exp_f32_e32 v27, v27
	v_exp_f32_e32 v26, v26
	v_mul_f32_e32 v23, v23, v28
	v_cvt_pk_bf16_f32 v16, v21, v16
	v_add_f32_e32 v27, 1.0, v27
	v_cvt_pk_bf16_f32 v17, v22, v17
	v_cvt_pk_bf16_f32 v18, v23, v18
	v_or_b32_e32 v22, s11, v140
	v_mov_b32_e32 v23, v129
	v_add_f32_e32 v26, 1.0, v26
	v_rcp_f32_e32 v27, v27
	v_lshlrev_b64 v[22:23], 12, v[22:23]
	v_rcp_f32_e32 v26, v26
	v_lshl_add_u64 v[22:23], s[92:93], 0, v[22:23]
	v_lshl_add_u64 v[22:23], v[22:23], 0, s[4:5]
	v_lshl_add_u64 v[22:23], v[22:23], 0, v[144:145]
	v_lshlrev_b32_e32 v28, 16, v25
	v_and_b32_e32 v25, 0xffff0000, v25
	v_mul_f32_e32 v19, v27, v19
	v_add_co_u32_e32 v22, vcc, s8, v22
	v_mul_f32_e32 v24, v26, v24
	v_mul_f32_e32 v19, v19, v25
	v_addc_co_u32_e32 v23, vcc, 0, v23, vcc
	s_waitcnt vmcnt(6)
	v_lshlrev_b32_e32 v21, 16, v12
	v_and_b32_e32 v12, 0xffff0000, v12
	v_mul_f32_e32 v24, v24, v28
	v_cvt_pk_bf16_f32 v19, v24, v19
	global_store_dwordx4 v[22:23], v[16:19], off offset:2048
	v_mul_f32_e32 v23, 0xbfb8aa3b, v12
	v_exp_f32_e32 v23, v23
	v_add_u32_e32 v16, v20, v171
	ds_read_b128 v[16:19], v16
	v_mul_f32_e32 v22, 0xbfb8aa3b, v21
	v_add_f32_e32 v23, 1.0, v23
	v_rcp_f32_e32 v23, v23
	v_exp_f32_e32 v22, v22
	s_waitcnt lgkmcnt(0)
; __device__ __forceinline__ float bf2f(short s) { return __uint_as_float(((unsigned)(unsigned short)s) << 16); }
; __device__ __forceinline__ float silu_fast(float g) { return g * __builtin_amdgcn_rcpf(1.f + __builtin_amdgcn_exp2f(-g * LOG2E)); }
; __device__ __forceinline__ bf16x8 tobf8(f32x8 x) { u32x4 w = {cvtpk(x[0], x[1]), cvtpk(x[2], x[3]), cvtpk(x[4], x[5]), cvtpk(x[6], x[7])}; return *reinterpret_cast<bf16x8*>(&w); }
; template <int MODE, bool SAMPLE>
; __device__ __forceinline__ void attn_unit(const Params& p, char* lds, int b, int h, int qb) {
;     ...
;         for (int it = 0; it < NIT; ++it) gt[it] = __builtin_nontemporal_load((const bf16x8*)(P1q + 24 * HB + (rbase + it * 4 + er) * 128 + ec));
; #pragma unroll
;         for (int it = 0; it < NIT; ++it) { const int row = it * 4 + er; const bf16x8 mx = *(const bf16x8*)(Qs + row * 256 + ec * 2); f32x8 y;
; #pragma unroll
;             for (int i = 0; i < 8; ++i) y[i] = bf2f(mx[i]) * silu_fast(bf2f(gt[it][i]));
;             *(bf16x8*)(MIX + (rbase + row) * DM + MODE * 1024 + h * HD + ec) = tobf8(y); }
	v_lshlrev_b32_e32 v24, 16, v16
	v_and_b32_e32 v16, 0xffff0000, v16
	v_mul_f32_e32 v12, v23, v12
	v_mul_f32_e32 v12, v12, v16
	v_lshlrev_b32_e32 v16, 16, v13
	v_and_b32_e32 v13, 0xffff0000, v13
	v_add_f32_e32 v22, 1.0, v22
	v_mul_f32_e32 v23, 0xbfb8aa3b, v13
	v_rcp_f32_e32 v22, v22
	v_exp_f32_e32 v23, v23
	v_mul_f32_e32 v21, v22, v21
	v_mul_f32_e32 v22, 0xbfb8aa3b, v16
	v_add_f32_e32 v23, 1.0, v23
	v_exp_f32_e32 v22, v22
	v_rcp_f32_e32 v23, v23
	v_mul_f32_e32 v21, v21, v24
	v_lshlrev_b32_e32 v24, 16, v17
	v_add_f32_e32 v22, 1.0, v22
	v_and_b32_e32 v17, 0xffff0000, v17
	v_mul_f32_e32 v13, v23, v13
	v_rcp_f32_e32 v22, v22
	v_mul_f32_e32 v13, v13, v17
	v_lshlrev_b32_e32 v17, 16, v14
	v_and_b32_e32 v14, 0xffff0000, v14
	v_mul_f32_e32 v23, 0xbfb8aa3b, v14
	v_exp_f32_e32 v23, v23
	v_mul_f32_e32 v16, v22, v16
	v_mul_f32_e32 v22, 0xbfb8aa3b, v17
	v_exp_f32_e32 v22, v22
	v_add_f32_e32 v23, 1.0, v23
	v_rcp_f32_e32 v23, v23
	v_mul_f32_e32 v16, v16, v24
	v_add_f32_e32 v22, 1.0, v22
	v_rcp_f32_e32 v22, v22
	v_lshlrev_b32_e32 v24, 16, v18
	v_and_b32_e32 v18, 0xffff0000, v18
	v_mul_f32_e32 v14, v23, v14
	v_mul_f32_e32 v14, v14, v18
	v_lshlrev_b32_e32 v18, 16, v15
	v_and_b32_e32 v15, 0xffff0000, v15
	v_mul_f32_e32 v23, 0xbfb8aa3b, v15
	v_mul_f32_e32 v17, v22, v17
	v_mul_f32_e32 v22, 0xbfb8aa3b, v18
	v_exp_f32_e32 v23, v23
	v_exp_f32_e32 v22, v22
	v_mul_f32_e32 v17, v17, v24
	v_cvt_pk_bf16_f32 v12, v21, v12
	v_add_f32_e32 v23, 1.0, v23
	v_cvt_pk_bf16_f32 v13, v16, v13
	v_cvt_pk_bf16_f32 v14, v17, v14
	v_or_b32_e32 v16, s11, v148
	v_mov_b32_e32 v17, v129
	v_add_f32_e32 v22, 1.0, v22
	v_rcp_f32_e32 v23, v23
	v_lshlrev_b64 v[16:17], 12, v[16:17]
	v_rcp_f32_e32 v22, v22
	v_lshl_add_u64 v[16:17], s[92:93], 0, v[16:17]
	v_lshl_add_u64 v[16:17], v[16:17], 0, s[4:5]
	v_lshl_add_u64 v[16:17], v[16:17], 0, v[144:145]
	v_lshlrev_b32_e32 v24, 16, v19
	v_and_b32_e32 v19, 0xffff0000, v19
	v_mul_f32_e32 v15, v23, v15
	v_add_co_u32_e32 v16, vcc, s8, v16
	v_mul_f32_e32 v18, v22, v18
	v_mul_f32_e32 v15, v15, v19
	v_addc_co_u32_e32 v17, vcc, 0, v17, vcc
	v_mul_f32_e32 v18, v18, v24
	v_cvt_pk_bf16_f32 v15, v18, v15
	global_store_dwordx4 v[16:17], v[12:15], off offset:2048
	s_waitcnt vmcnt(7)
	v_lshlrev_b32_e32 v16, 16, v8
	v_and_b32_e32 v8, 0xffff0000, v8
	v_mul_f32_e32 v18, 0xbfb8aa3b, v8
	v_exp_f32_e32 v18, v18
	v_add_u32_e32 v12, v20, v210
	ds_read_b128 v[12:15], v12
	v_mul_f32_e32 v17, 0xbfb8aa3b, v16
	v_add_f32_e32 v18, 1.0, v18
	v_rcp_f32_e32 v18, v18
	v_exp_f32_e32 v17, v17
	s_waitcnt lgkmcnt(0)
	v_lshlrev_b32_e32 v19, 16, v12
	v_and_b32_e32 v12, 0xffff0000, v12
	v_mul_f32_e32 v8, v18, v8
	v_mul_f32_e32 v8, v8, v12
	v_lshlrev_b32_e32 v12, 16, v9
	v_and_b32_e32 v9, 0xffff0000, v9
	v_add_f32_e32 v17, 1.0, v17
	v_mul_f32_e32 v18, 0xbfb8aa3b, v9
	v_rcp_f32_e32 v17, v17
	v_exp_f32_e32 v18, v18
	v_mul_f32_e32 v16, v17, v16
	v_mul_f32_e32 v17, 0xbfb8aa3b, v12
	v_add_f32_e32 v18, 1.0, v18
	v_exp_f32_e32 v17, v17
	v_rcp_f32_e32 v18, v18
	v_mul_f32_e32 v16, v16, v19
	v_lshlrev_b32_e32 v19, 16, v13
	v_add_f32_e32 v17, 1.0, v17
	v_and_b32_e32 v13, 0xffff0000, v13
	v_mul_f32_e32 v9, v18, v9
	v_rcp_f32_e32 v17, v17
	v_mul_f32_e32 v9, v9, v13
	v_lshlrev_b32_e32 v13, 16, v10
	v_and_b32_e32 v10, 0xffff0000, v10
	v_mul_f32_e32 v18, 0xbfb8aa3b, v10
	v_exp_f32_e32 v18, v18
	v_mul_f32_e32 v12, v17, v12
	v_mul_f32_e32 v17, 0xbfb8aa3b, v13
	v_exp_f32_e32 v17, v17
	v_add_f32_e32 v18, 1.0, v18
	v_rcp_f32_e32 v18, v18
	v_mul_f32_e32 v12, v12, v19
	v_add_f32_e32 v17, 1.0, v17
	v_rcp_f32_e32 v17, v17
	v_lshlrev_b32_e32 v19, 16, v14
	v_and_b32_e32 v14, 0xffff0000, v14
	v_mul_f32_e32 v10, v18, v10
	v_mul_f32_e32 v10, v10, v14
	v_lshlrev_b32_e32 v14, 16, v11
	v_and_b32_e32 v11, 0xffff0000, v11
	v_mul_f32_e32 v18, 0xbfb8aa3b, v11
	v_mul_f32_e32 v13, v17, v13
	v_mul_f32_e32 v17, 0xbfb8aa3b, v14
	v_exp_f32_e32 v18, v18
	v_exp_f32_e32 v17, v17
	v_mul_f32_e32 v13, v13, v19
	v_cvt_pk_bf16_f32 v8, v16, v8
	v_add_f32_e32 v18, 1.0, v18
	v_cvt_pk_bf16_f32 v9, v12, v9
	v_cvt_pk_bf16_f32 v10, v13, v10
	v_or_b32_e32 v12, s11, v150
	v_mov_b32_e32 v13, v129
	v_add_f32_e32 v17, 1.0, v17
	v_rcp_f32_e32 v18, v18
	v_lshlrev_b64 v[12:13], 12, v[12:13]
	v_rcp_f32_e32 v17, v17
	v_lshl_add_u64 v[12:13], s[92:93], 0, v[12:13]
	v_lshl_add_u64 v[12:13], v[12:13], 0, s[4:5]
	v_lshl_add_u64 v[12:13], v[12:13], 0, v[144:145]
	v_lshlrev_b32_e32 v19, 16, v15
	v_and_b32_e32 v15, 0xffff0000, v15
	v_mul_f32_e32 v11, v18, v11
	v_add_co_u32_e32 v12, vcc, s8, v12
	v_mul_f32_e32 v14, v17, v14
	v_mul_f32_e32 v11, v11, v15
	v_addc_co_u32_e32 v13, vcc, 0, v13, vcc
	v_mul_f32_e32 v14, v14, v19
	v_cvt_pk_bf16_f32 v11, v14, v11
	global_store_dwordx4 v[12:13], v[8:11], off offset:2048
	s_waitcnt vmcnt(7)
; __device__ __forceinline__ float bf2f(short s) { return __uint_as_float(((unsigned)(unsigned short)s) << 16); }
; __device__ __forceinline__ float silu_fast(float g) { return g * __builtin_amdgcn_rcpf(1.f + __builtin_amdgcn_exp2f(-g * LOG2E)); }
; __device__ __forceinline__ bf16x8 tobf8(f32x8 x) { u32x4 w = {cvtpk(x[0], x[1]), cvtpk(x[2], x[3]), cvtpk(x[4], x[5]), cvtpk(x[6], x[7])}; return *reinterpret_cast<bf16x8*>(&w); }
; template <int MODE, bool SAMPLE>
; __device__ __forceinline__ void attn_unit(const Params& p, char* lds, int b, int h, int qb) {
;     ...
;         for (int it = 0; it < NIT; ++it) gt[it] = __builtin_nontemporal_load((const bf16x8*)(P1q + 24 * HB + (rbase + it * 4 + er) * 128 + ec));
; #pragma unroll
;         for (int it = 0; it < NIT; ++it) { const int row = it * 4 + er; const bf16x8 mx = *(const bf16x8*)(Qs + row * 256 + ec * 2); f32x8 y;
; #pragma unroll
;             for (int i = 0; i < 8; ++i) y[i] = bf2f(mx[i]) * silu_fast(bf2f(gt[it][i]));
;             *(bf16x8*)(MIX + (rbase + row) * DM + MODE * 1024 + h * HD + ec) = tobf8(y); }
;     }
;     __syncthreads();
	v_lshlrev_b32_e32 v12, 16, v4
	v_and_b32_e32 v4, 0xffff0000, v4
	v_mul_f32_e32 v14, 0xbfb8aa3b, v4
	v_exp_f32_e32 v14, v14
	v_add_u32_e32 v8, v20, v211
	ds_read_b128 v[8:11], v8
	v_mul_f32_e32 v13, 0xbfb8aa3b, v12
	v_add_f32_e32 v14, 1.0, v14
	v_rcp_f32_e32 v14, v14
	v_exp_f32_e32 v13, v13
	s_waitcnt lgkmcnt(0)
	v_lshlrev_b32_e32 v15, 16, v8
	v_and_b32_e32 v8, 0xffff0000, v8
	v_mul_f32_e32 v4, v14, v4
	v_mul_f32_e32 v4, v4, v8
	v_lshlrev_b32_e32 v8, 16, v5
	v_and_b32_e32 v5, 0xffff0000, v5
	v_add_f32_e32 v13, 1.0, v13
	v_mul_f32_e32 v14, 0xbfb8aa3b, v5
	v_rcp_f32_e32 v13, v13
	v_exp_f32_e32 v14, v14
	v_mul_f32_e32 v12, v13, v12
	v_mul_f32_e32 v13, 0xbfb8aa3b, v8
	v_add_f32_e32 v14, 1.0, v14
	v_exp_f32_e32 v13, v13
	v_rcp_f32_e32 v14, v14
	v_mul_f32_e32 v12, v12, v15
	v_lshlrev_b32_e32 v15, 16, v9
	v_add_f32_e32 v13, 1.0, v13
	v_and_b32_e32 v9, 0xffff0000, v9
	v_mul_f32_e32 v5, v14, v5
	v_rcp_f32_e32 v13, v13
	v_mul_f32_e32 v5, v5, v9
	v_lshlrev_b32_e32 v9, 16, v6
	v_and_b32_e32 v6, 0xffff0000, v6
	v_mul_f32_e32 v14, 0xbfb8aa3b, v6
	v_exp_f32_e32 v14, v14
	v_mul_f32_e32 v8, v13, v8
	v_mul_f32_e32 v13, 0xbfb8aa3b, v9
	v_exp_f32_e32 v13, v13
	v_add_f32_e32 v14, 1.0, v14
	v_rcp_f32_e32 v14, v14
	v_mul_f32_e32 v8, v8, v15
	v_add_f32_e32 v13, 1.0, v13
	v_rcp_f32_e32 v13, v13
	v_lshlrev_b32_e32 v15, 16, v10
	v_and_b32_e32 v10, 0xffff0000, v10
	v_mul_f32_e32 v6, v14, v6
	v_mul_f32_e32 v6, v6, v10
	v_lshlrev_b32_e32 v10, 16, v7
	v_and_b32_e32 v7, 0xffff0000, v7
	v_mul_f32_e32 v14, 0xbfb8aa3b, v7
	v_mul_f32_e32 v9, v13, v9
	v_mul_f32_e32 v13, 0xbfb8aa3b, v10
	v_exp_f32_e32 v14, v14
	v_exp_f32_e32 v13, v13
	v_mul_f32_e32 v9, v9, v15
	v_cvt_pk_bf16_f32 v4, v12, v4
	v_add_f32_e32 v14, 1.0, v14
	v_cvt_pk_bf16_f32 v5, v8, v5
	v_cvt_pk_bf16_f32 v6, v9, v6
	v_or_b32_e32 v8, s11, v152
	v_mov_b32_e32 v9, v129
	v_add_f32_e32 v13, 1.0, v13
	v_rcp_f32_e32 v14, v14
	v_lshlrev_b64 v[8:9], 12, v[8:9]
	v_rcp_f32_e32 v13, v13
	v_lshl_add_u64 v[8:9], s[92:93], 0, v[8:9]
	v_lshl_add_u64 v[8:9], v[8:9], 0, s[4:5]
	v_lshl_add_u64 v[8:9], v[8:9], 0, v[144:145]
	v_lshlrev_b32_e32 v15, 16, v11
	v_and_b32_e32 v11, 0xffff0000, v11
	v_mul_f32_e32 v7, v14, v7
	v_add_co_u32_e32 v8, vcc, s8, v8
	v_mul_f32_e32 v10, v13, v10
	v_mul_f32_e32 v7, v7, v11
	v_addc_co_u32_e32 v9, vcc, 0, v9, vcc
	v_mul_f32_e32 v10, v10, v15
	v_cvt_pk_bf16_f32 v7, v10, v7
	global_store_dwordx4 v[8:9], v[4:7], off offset:2048
	s_waitcnt vmcnt(7)
	v_lshlrev_b32_e32 v8, 16, v0
	v_and_b32_e32 v0, 0xffff0000, v0
	v_mul_f32_e32 v10, 0xbfb8aa3b, v0
	v_exp_f32_e32 v10, v10
	v_add_u32_e32 v4, v20, v212
	ds_read_b128 v[4:7], v4
	v_mul_f32_e32 v9, 0xbfb8aa3b, v8
	v_add_f32_e32 v10, 1.0, v10
	v_rcp_f32_e32 v10, v10
	v_exp_f32_e32 v9, v9
	s_waitcnt lgkmcnt(0)
	v_lshlrev_b32_e32 v11, 16, v4
	v_and_b32_e32 v4, 0xffff0000, v4
	v_mul_f32_e32 v0, v10, v0
	v_mul_f32_e32 v0, v0, v4
	v_lshlrev_b32_e32 v4, 16, v1
	v_and_b32_e32 v1, 0xffff0000, v1
	v_add_f32_e32 v9, 1.0, v9
	v_mul_f32_e32 v10, 0xbfb8aa3b, v1
	v_rcp_f32_e32 v9, v9
	v_exp_f32_e32 v10, v10
	v_mul_f32_e32 v8, v9, v8
	v_mul_f32_e32 v9, 0xbfb8aa3b, v4
	v_add_f32_e32 v10, 1.0, v10
	v_exp_f32_e32 v9, v9
	v_rcp_f32_e32 v10, v10
	v_mul_f32_e32 v8, v8, v11
	v_lshlrev_b32_e32 v11, 16, v5
	v_add_f32_e32 v9, 1.0, v9
	v_and_b32_e32 v5, 0xffff0000, v5
	v_mul_f32_e32 v1, v10, v1
	v_rcp_f32_e32 v9, v9
	v_mul_f32_e32 v1, v1, v5
	v_lshlrev_b32_e32 v5, 16, v2
	v_and_b32_e32 v2, 0xffff0000, v2
	v_mul_f32_e32 v10, 0xbfb8aa3b, v2
	v_exp_f32_e32 v10, v10
	v_mul_f32_e32 v4, v9, v4
	v_mul_f32_e32 v9, 0xbfb8aa3b, v5
	v_exp_f32_e32 v9, v9
	v_add_f32_e32 v10, 1.0, v10
	v_rcp_f32_e32 v10, v10
	v_mul_f32_e32 v4, v4, v11
	v_add_f32_e32 v9, 1.0, v9
	v_rcp_f32_e32 v9, v9
	v_lshlrev_b32_e32 v11, 16, v6
	v_and_b32_e32 v6, 0xffff0000, v6
	v_mul_f32_e32 v2, v10, v2
	v_mul_f32_e32 v2, v2, v6
	v_lshlrev_b32_e32 v6, 16, v3
	v_and_b32_e32 v3, 0xffff0000, v3
	v_mul_f32_e32 v10, 0xbfb8aa3b, v3
	v_mul_f32_e32 v5, v9, v5
	v_mul_f32_e32 v9, 0xbfb8aa3b, v6
	v_exp_f32_e32 v10, v10
	v_exp_f32_e32 v9, v9
	v_mul_f32_e32 v5, v5, v11
	v_cvt_pk_bf16_f32 v0, v8, v0
	v_add_f32_e32 v10, 1.0, v10
	v_cvt_pk_bf16_f32 v1, v4, v1
	v_cvt_pk_bf16_f32 v2, v5, v2
	v_or_b32_e32 v4, s11, v154
	v_mov_b32_e32 v5, v129
	v_add_f32_e32 v9, 1.0, v9
	v_rcp_f32_e32 v10, v10
	v_lshlrev_b64 v[4:5], 12, v[4:5]
	v_rcp_f32_e32 v9, v9
	v_lshl_add_u64 v[4:5], s[92:93], 0, v[4:5]
	v_lshl_add_u64 v[4:5], v[4:5], 0, s[4:5]
	v_lshl_add_u64 v[4:5], v[4:5], 0, v[144:145]
	v_lshlrev_b32_e32 v11, 16, v7
	v_and_b32_e32 v7, 0xffff0000, v7
	v_mul_f32_e32 v3, v10, v3
	v_add_co_u32_e32 v4, vcc, 0x11300000, v4
	v_mul_f32_e32 v6, v9, v6
	v_mul_f32_e32 v3, v3, v7
	v_addc_co_u32_e32 v5, vcc, 0, v5, vcc
	v_mul_f32_e32 v6, v6, v11
	v_cvt_pk_bf16_f32 v3, v6, v3
	global_store_dwordx4 v[4:5], v[0:3], off offset:2048
	s_barrier
	s_cbranch_scc1 .LBB0_721

; template <int MODE, bool SAMPLE>
; __device__ __forceinline__ void attn_unit(const Params& p, char* lds, int b, int h, int qb) {
;     ...
; #pragma unroll
;     ...
;         const int j = 2 * jj + par;
;         if (j > jfirst) continue;
;         const int buf = par;
;         WRITET(buf, stg2[NS == 2 ? par : 0]);
;         if (j >= NS) LOADT(j - NS, stg2[NS == 2 ? par : 0]);
.LBB0_682:
	s_cmp_lt_i32 s20, s27
	s_cbranch_scc0 .Lph_0
	s_cmp_eq_u32 s17, 0
	s_waitcnt vmcnt(7)
	ds_write_b128 v133, v[96:99] offset:16384
	s_waitcnt vmcnt(6)
	ds_write_b128 v198, v[100:103] offset:16384
	s_waitcnt vmcnt(5)
	ds_write_b128 v199, v[104:107] offset:49152
	s_waitcnt vmcnt(4)
	ds_write_b128 v200, v[108:111] offset:49152
	s_cbranch_scc1 .Lpd_0
	s_add_i32 s4, s16, s28
	s_sub_i32 s4, s4, 64
	s_lshl_b64 s[18:19], s[4:5], 8
	v_lshl_add_u64 v[64:65], v[164:165], 0, s[18:19]
	v_mov_b32_e32 v161, v129
	v_lshl_add_u64 v[66:67], v[64:65], 0, v[128:129]
	v_lshl_add_u64 v[68:69], v[64:65], 0, v[160:161]
	v_lshl_add_u64 v[64:65], v[64:65], 0, s[96:97]
	global_load_dwordx4 v[96:99], v[66:67], off
	global_load_dwordx4 v[100:103], v[68:69], off
	v_lshl_add_u64 v[66:67], v[64:65], 0, v[128:129]
	v_lshl_add_u64 v[64:65], v[64:65], 0, v[160:161]
	global_load_dwordx4 v[104:107], v[66:67], off
	global_load_dwordx4 v[108:111], v[64:65], off
	s_branch .LBB0_685
.Lph_0:
	global_load_dword v255, v183, s[92:93]
	global_load_dword v255, v183, s[92:93]
	global_load_dword v255, v183, s[92:93]
	global_load_dword v255, v183, s[92:93]
	s_branch .LBB0_693
.Lpd_0:
	global_load_dword v255, v183, s[92:93]
	global_load_dword v255, v183, s[92:93]
	global_load_dword v255, v183, s[92:93]
	global_load_dword v255, v183, s[92:93]

; template <int MODE, bool SAMPLE>
; __device__ __forceinline__ void attn_unit(const Params& p, char* lds, int b, int h, int qb) {
;     ...
; #pragma unroll
;     ...
;         const int j = 2 * jj + par;
;         if (j > jfirst) continue;
;         const int buf = par;
;         WRITET(buf, stg2[NS == 2 ? par : 0]);
;         if (j >= NS) LOADT(j - NS, stg2[NS == 2 ? par : 0]);
.LBB0_693:
	s_cmp_gt_i32 s20, s27
	s_cbranch_scc1 .LBB0_681
	s_cmp_eq_u32 s17, 0
	s_waitcnt vmcnt(7)
	ds_write_b128 v133, v[112:115]
	s_waitcnt vmcnt(6)
	ds_write_b128 v198, v[116:119]
	s_waitcnt vmcnt(5)
	ds_write_b128 v199, v[120:123] offset:32768
	s_waitcnt vmcnt(4)
	ds_write_b128 v200, v[124:127] offset:32768
	s_cbranch_scc1 .LBB0_696
	s_add_i32 s4, s16, s28
	s_addk_i32 s4, 0xff80
	s_lshl_b64 s[18:19], s[4:5], 8
	v_lshl_add_u64 v[64:65], v[164:165], 0, s[18:19]
	v_mov_b32_e32 v161, v129
	v_lshl_add_u64 v[66:67], v[64:65], 0, v[128:129]
	v_lshl_add_u64 v[68:69], v[64:65], 0, v[160:161]
	v_lshl_add_u64 v[64:65], v[64:65], 0, s[96:97]
	global_load_dwordx4 v[112:115], v[66:67], off
	global_load_dwordx4 v[116:119], v[68:69], off
	v_lshl_add_u64 v[66:67], v[64:65], 0, v[128:129]
	v_lshl_add_u64 v[64:65], v[64:65], 0, v[160:161]
	global_load_dwordx4 v[120:123], v[66:67], off
	global_load_dwordx4 v[124:127], v[64:65], off

; __device__ __forceinline__ unsigned cvtpk(float lo, float hi) { unsigned r; asm volatile("v_cvt_pk_bf16_f32 %0, %1, %2" : "=v"(r) : "v"(lo), "v"(hi)); return r; }
; __device__ __forceinline__ int crow(int r, int hi) { return (r & 3) + 8 * (r >> 2) + 4 * hi; }
; template <int MODE, bool SAMPLE>
; __device__ __forceinline__ void attn_unit(const Params& p, char* lds, int b, int h, int qb) {
;     ...
;         if (MODE == 0) { if (hi == 0) wsc[32 + r32] = l_reg; asm volatile("s_waitcnt lgkmcnt(0)" ::: "memory");
; #pragma unroll
;             for (int r = 0; r < 16; ++r) rli[r] = __builtin_amdgcn_rcpf(wsc[32 + crow(r, hi)]); }
; #pragma unroll
;         for (int r = 0; r < 16; ++r) { const int orow = crow(r, hi);
;             if (!SAMPLE || orow < TS) {
; #pragma unroll
;                 for (int d0 = 0; d0 < 4; ++d0) { float ov = o[d0][r]; if (MODE == 0) ov *= rli[r];
;                     const unsigned pk = cvtpk(ov, 0.f); *(bf16_t*)(Qs + orow * 256 + (d0 * 32 + r32) * 2) = (bf16_t)(pk & 0xffffu); } } }
;         asm volatile("s_waitcnt lgkmcnt(0)" ::: "memory");
;         bf16x8 gt[NIT];
; #pragma unroll
;         for (int it = 0; it < NIT; ++it) gt[it] = __builtin_nontemporal_load((const bf16x8*)(P1q + 24 * HB + (rbase + it * 4 + er) * 128 + ec));
.LBB0_703:
	s_waitcnt vmcnt(0)
	s_and_saveexec_b64 s[18:19], s[14:15]
	ds_write_b32 v147, v219 offset:128
	s_or_b64 exec, exec, s[18:19]
	s_waitcnt lgkmcnt(0)
	v_add_u32_e32 v72, s12, v137
	ds_read_b128 v[64:67], v72 offset:128
	ds_read_b128 v[68:71], v72 offset:160
	s_ashr_i32 s4, s10, 31
	v_mov_b32_e32 v145, v129
	v_mov_b32_e32 v147, v129
	s_waitcnt lgkmcnt(1)
	v_rcp_f32_e32 v73, v64
	v_rcp_f32_e32 v74, v65
	v_rcp_f32_e32 v75, v66
	v_rcp_f32_e32 v76, v67
	v_mul_f32_e32 v16, v16, v73
	s_waitcnt lgkmcnt(0)
	v_rcp_f32_e32 v77, v68
	ds_read_b128 v[64:67], v72 offset:192
	v_rcp_f32_e32 v78, v69
	v_rcp_f32_e32 v79, v70
	v_rcp_f32_e32 v80, v71
	ds_read_b128 v[68:71], v72 offset:224
	v_add3_u32 v72, s26, v193, v192
	v_cvt_pk_bf16_f32 v16, v16, v129
	ds_write_b16 v72, v16
	v_mul_f32_e32 v16, v48, v73
	v_cvt_pk_bf16_f32 v16, v16, v129
	ds_write_b16 v72, v16 offset:64
	v_mul_f32_e32 v16, v32, v73
	v_mul_f32_e32 v0, v0, v73
	v_cvt_pk_bf16_f32 v16, v16, v129
	ds_write_b16 v72, v16 offset:128
	v_cvt_pk_bf16_f32 v0, v0, v129
	ds_write_b16 v72, v0 offset:192
	v_mul_f32_e32 v0, v17, v74
	v_cvt_pk_bf16_f32 v0, v0, v129
	ds_write_b16 v72, v0 offset:256
	v_mul_f32_e32 v0, v49, v74
	v_cvt_pk_bf16_f32 v0, v0, v129
	ds_write_b16 v72, v0 offset:320
	v_mul_f32_e32 v0, v33, v74
	v_cvt_pk_bf16_f32 v0, v0, v129
	ds_write_b16 v72, v0 offset:384
	v_mul_f32_e32 v0, v1, v74
	v_cvt_pk_bf16_f32 v0, v0, v129
	ds_write_b16 v72, v0 offset:448
	v_mul_f32_e32 v0, v18, v75
	v_cvt_pk_bf16_f32 v0, v0, v129
	ds_write_b16 v72, v0 offset:512
	v_mul_f32_e32 v0, v50, v75
	v_cvt_pk_bf16_f32 v0, v0, v129
	ds_write_b16 v72, v0 offset:576
	v_mul_f32_e32 v0, v34, v75
	v_cvt_pk_bf16_f32 v0, v0, v129
	ds_write_b16 v72, v0 offset:640
	v_mul_f32_e32 v0, v2, v75
	v_cvt_pk_bf16_f32 v0, v0, v129
	ds_write_b16 v72, v0 offset:704
	v_mul_f32_e32 v0, v19, v76
	v_cvt_pk_bf16_f32 v0, v0, v129
	ds_write_b16 v72, v0 offset:768
	v_mul_f32_e32 v0, v51, v76
	v_cvt_pk_bf16_f32 v0, v0, v129
	ds_write_b16 v72, v0 offset:832
	v_mul_f32_e32 v0, v35, v76
	v_cvt_pk_bf16_f32 v0, v0, v129
	ds_write_b16 v72, v0 offset:896
	v_mul_f32_e32 v0, v3, v76
	v_cvt_pk_bf16_f32 v0, v0, v129
	ds_write_b16 v72, v0 offset:960
	v_mul_f32_e32 v0, v20, v77
	v_cvt_pk_bf16_f32 v0, v0, v129
	ds_write_b16 v72, v0 offset:2048
	v_mul_f32_e32 v0, v52, v77
	v_cvt_pk_bf16_f32 v0, v0, v129
	ds_write_b16 v72, v0 offset:2112
	v_mul_f32_e32 v0, v36, v77
	v_cvt_pk_bf16_f32 v0, v0, v129
	ds_write_b16 v72, v0 offset:2176
	v_mul_f32_e32 v0, v4, v77
	v_cvt_pk_bf16_f32 v0, v0, v129
	ds_write_b16 v72, v0 offset:2240
	v_mul_f32_e32 v0, v21, v78
	v_cvt_pk_bf16_f32 v0, v0, v129
	ds_write_b16 v72, v0 offset:2304
	v_mul_f32_e32 v0, v53, v78
	v_cvt_pk_bf16_f32 v0, v0, v129
	ds_write_b16 v72, v0 offset:2368
	v_mul_f32_e32 v0, v37, v78
	v_cvt_pk_bf16_f32 v0, v0, v129
	ds_write_b16 v72, v0 offset:2432
	v_mul_f32_e32 v0, v5, v78
	v_cvt_pk_bf16_f32 v0, v0, v129
	ds_write_b16 v72, v0 offset:2496
	v_mul_f32_e32 v0, v22, v79
	v_cvt_pk_bf16_f32 v0, v0, v129
	ds_write_b16 v72, v0 offset:2560
	v_mul_f32_e32 v0, v54, v79
	v_cvt_pk_bf16_f32 v0, v0, v129
	ds_write_b16 v72, v0 offset:2624
	v_mul_f32_e32 v0, v38, v79
	v_cvt_pk_bf16_f32 v0, v0, v129
	ds_write_b16 v72, v0 offset:2688
	v_mul_f32_e32 v0, v6, v79
	v_cvt_pk_bf16_f32 v0, v0, v129
	ds_write_b16 v72, v0 offset:2752
	v_mul_f32_e32 v0, v23, v80
	v_cvt_pk_bf16_f32 v0, v0, v129
	ds_write_b16 v72, v0 offset:2816
	v_mul_f32_e32 v0, v55, v80
	v_cvt_pk_bf16_f32 v0, v0, v129
	s_waitcnt lgkmcnt(14)
	v_rcp_f32_e32 v64, v64
	ds_write_b16 v72, v0 offset:2880
	v_mul_f32_e32 v0, v39, v80
	v_cvt_pk_bf16_f32 v0, v0, v129
	ds_write_b16 v72, v0 offset:2944
	v_mul_f32_e32 v0, v7, v80
	v_cvt_pk_bf16_f32 v0, v0, v129
	ds_write_b16 v72, v0 offset:3008
	v_mul_f32_e32 v0, v24, v64
	v_cvt_pk_bf16_f32 v0, v0, v129
	ds_write_b16 v72, v0 offset:4096
	v_mul_f32_e32 v0, v56, v64
	v_cvt_pk_bf16_f32 v0, v0, v129
	v_rcp_f32_e32 v65, v65
	ds_write_b16 v72, v0 offset:4160
	v_mul_f32_e32 v0, v40, v64
	v_cvt_pk_bf16_f32 v0, v0, v129
	ds_write_b16 v72, v0 offset:4224
	v_mul_f32_e32 v0, v8, v64
	v_cvt_pk_bf16_f32 v0, v0, v129
	ds_write_b16 v72, v0 offset:4288
	v_mul_f32_e32 v0, v25, v65
	v_cvt_pk_bf16_f32 v0, v0, v129
	ds_write_b16 v72, v0 offset:4352
	v_mul_f32_e32 v0, v57, v65
	v_cvt_pk_bf16_f32 v0, v0, v129
	v_rcp_f32_e32 v66, v66
	ds_write_b16 v72, v0 offset:4416
	v_mul_f32_e32 v0, v41, v65
	v_cvt_pk_bf16_f32 v0, v0, v129
	ds_write_b16 v72, v0 offset:4480
	v_mul_f32_e32 v0, v9, v65
	v_cvt_pk_bf16_f32 v0, v0, v129
	ds_write_b16 v72, v0 offset:4544
	v_mul_f32_e32 v0, v26, v66
	v_cvt_pk_bf16_f32 v0, v0, v129
	ds_write_b16 v72, v0 offset:4608
	v_mul_f32_e32 v0, v58, v66
	v_cvt_pk_bf16_f32 v0, v0, v129
	v_rcp_f32_e32 v67, v67
	ds_write_b16 v72, v0 offset:4672
	v_mul_f32_e32 v0, v42, v66
	v_cvt_pk_bf16_f32 v0, v0, v129
	ds_write_b16 v72, v0 offset:4736
	v_mul_f32_e32 v0, v10, v66
	v_cvt_pk_bf16_f32 v0, v0, v129
	ds_write_b16 v72, v0 offset:4800
	v_mul_f32_e32 v0, v27, v67
	v_cvt_pk_bf16_f32 v0, v0, v129
	ds_write_b16 v72, v0 offset:4864
	v_mul_f32_e32 v0, v59, v67
	v_cvt_pk_bf16_f32 v0, v0, v129
	v_rcp_f32_e32 v68, v68
	ds_write_b16 v72, v0 offset:4928
	v_mul_f32_e32 v0, v43, v67
	v_cvt_pk_bf16_f32 v0, v0, v129
	ds_write_b16 v72, v0 offset:4992
	v_mul_f32_e32 v0, v11, v67
	v_cvt_pk_bf16_f32 v0, v0, v129
	ds_write_b16 v72, v0 offset:5056
	v_mul_f32_e32 v0, v28, v68
	v_cvt_pk_bf16_f32 v0, v0, v129
	ds_write_b16 v72, v0 offset:6144
	v_mul_f32_e32 v0, v60, v68
	v_cvt_pk_bf16_f32 v0, v0, v129
	v_rcp_f32_e32 v69, v69
	ds_write_b16 v72, v0 offset:6208
	v_mul_f32_e32 v0, v44, v68
	v_cvt_pk_bf16_f32 v0, v0, v129
	ds_write_b16 v72, v0 offset:6272
	v_mul_f32_e32 v0, v12, v68
; __device__ __forceinline__ unsigned cvtpk(float lo, float hi) { unsigned r; asm volatile("v_cvt_pk_bf16_f32 %0, %1, %2" : "=v"(r) : "v"(lo), "v"(hi)); return r; }
; __device__ __forceinline__ float bf2f(short s) { return __uint_as_float(((unsigned)(unsigned short)s) << 16); }
; __device__ __forceinline__ float silu_fast(float g) { return g * __builtin_amdgcn_rcpf(1.f + __builtin_amdgcn_exp2f(-g * LOG2E)); }
; __device__ __forceinline__ int crow(int r, int hi) { return (r & 3) + 8 * (r >> 2) + 4 * hi; }
; __device__ __forceinline__ bf16x8 tobf8(f32x8 x) { u32x4 w = {cvtpk(x[0], x[1]), cvtpk(x[2], x[3]), cvtpk(x[4], x[5]), cvtpk(x[6], x[7])}; return *reinterpret_cast<bf16x8*>(&w); }
; template <int MODE, bool SAMPLE>
; __device__ __forceinline__ void attn_unit(const Params& p, char* lds, int b, int h, int qb) {
;     ...
;         for (int r = 0; r < 16; ++r) { const int orow = crow(r, hi);
;             if (!SAMPLE || orow < TS) {
; #pragma unroll
;                 for (int d0 = 0; d0 < 4; ++d0) { float ov = o[d0][r]; if (MODE == 0) ov *= rli[r];
;                     const unsigned pk = cvtpk(ov, 0.f); *(bf16_t*)(Qs + orow * 256 + (d0 * 32 + r32) * 2) = (bf16_t)(pk & 0xffffu); } } }
;         asm volatile("s_waitcnt lgkmcnt(0)" ::: "memory");
;         bf16x8 gt[NIT];
; #pragma unroll
;         for (int it = 0; it < NIT; ++it) gt[it] = __builtin_nontemporal_load((const bf16x8*)(P1q + 24 * HB + (rbase + it * 4 + er) * 128 + ec));
; #pragma unroll
;         for (int it = 0; it < NIT; ++it) { const int row = it * 4 + er; const bf16x8 mx = *(const bf16x8*)(Qs + row * 256 + ec * 2); f32x8 y;
; #pragma unroll
;             for (int i = 0; i < 8; ++i) y[i] = bf2f(mx[i]) * silu_fast(bf2f(gt[it][i]));
;             *(bf16x8*)(MIX + (rbase + row) * DM + MODE * 1024 + h * HD + ec) = tobf8(y); }
	v_cvt_pk_bf16_f32 v0, v0, v129
	ds_write_b16 v72, v0 offset:6336
	v_mul_f32_e32 v0, v29, v69
	v_cvt_pk_bf16_f32 v0, v0, v129
	ds_write_b16 v72, v0 offset:6400
	v_mul_f32_e32 v0, v61, v69
	v_cvt_pk_bf16_f32 v0, v0, v129
	v_rcp_f32_e32 v70, v70
	ds_write_b16 v72, v0 offset:6464
	v_mul_f32_e32 v0, v45, v69
	v_cvt_pk_bf16_f32 v0, v0, v129
	ds_write_b16 v72, v0 offset:6528
	v_mul_f32_e32 v0, v13, v69
	v_cvt_pk_bf16_f32 v0, v0, v129
	ds_write_b16 v72, v0 offset:6592
	v_mul_f32_e32 v0, v30, v70
	v_cvt_pk_bf16_f32 v0, v0, v129
	ds_write_b16 v72, v0 offset:6656
	v_mul_f32_e32 v0, v62, v70
	v_cvt_pk_bf16_f32 v0, v0, v129
	v_rcp_f32_e32 v71, v71
	ds_write_b16 v72, v0 offset:6720
	v_mul_f32_e32 v0, v46, v70
	v_cvt_pk_bf16_f32 v0, v0, v129
	ds_write_b16 v72, v0 offset:6784
	v_mul_f32_e32 v0, v14, v70
	v_cvt_pk_bf16_f32 v0, v0, v129
	ds_write_b16 v72, v0 offset:6848
	v_mul_f32_e32 v0, v31, v71
	v_cvt_pk_bf16_f32 v0, v0, v129
	ds_write_b16 v72, v0 offset:6912
	v_mul_f32_e32 v0, v63, v71
	v_cvt_pk_bf16_f32 v0, v0, v129
	ds_write_b16 v72, v0 offset:6976
	v_mul_f32_e32 v0, v47, v71
	v_cvt_pk_bf16_f32 v0, v0, v129
	ds_write_b16 v72, v0 offset:7040
	v_mul_f32_e32 v0, v15, v71
	v_cvt_pk_bf16_f32 v0, v0, v129
	ds_write_b16 v72, v0 offset:7104
	v_lshl_add_u64 v[0:1], s[0:1], 0, v[144:145]
	s_mov_b64 s[0:1], 0x3300000
	v_mov_b32_e32 v51, s4
	v_or_b32_e32 v50, s10, v130
	v_lshl_add_u64 v[4:5], v[0:1], 0, s[0:1]
	v_lshlrev_b64 v[0:1], 8, v[50:51]
	s_waitcnt lgkmcnt(0)
	v_lshl_add_u64 v[0:1], v[4:5], 0, v[0:1]
	global_load_dwordx4 v[0:3], v[0:1], off nt
	v_mov_b32_e32 v35, s4
	v_or_b32_e32 v34, s10, v136
	v_lshlrev_b64 v[6:7], 8, v[34:35]
	v_lshl_add_u64 v[8:9], v[4:5], 0, v[6:7]
	global_load_dwordx4 v[38:41], v[8:9], off nt
	v_mov_b32_e32 v33, s4
	v_or_b32_e32 v32, s10, v138
	v_lshlrev_b64 v[6:7], 8, v[32:33]
	v_mov_b32_e32 v31, s4
	v_or_b32_e32 v30, s10, v140
	v_lshl_add_u64 v[10:11], v[4:5], 0, v[6:7]
	v_lshlrev_b64 v[6:7], 8, v[30:31]
	v_mov_b32_e32 v29, s4
	v_or_b32_e32 v28, s10, v148
	v_lshl_add_u64 v[12:13], v[4:5], 0, v[6:7]
	v_lshlrev_b64 v[6:7], 8, v[28:29]
	v_mov_b32_e32 v27, s4
	v_or_b32_e32 v26, s10, v150
	v_lshl_add_u64 v[14:15], v[4:5], 0, v[6:7]
	v_lshlrev_b64 v[6:7], 8, v[26:27]
	v_mov_b32_e32 v25, s4
	v_or_b32_e32 v24, s10, v152
	v_lshl_add_u64 v[46:47], v[4:5], 0, v[6:7]
	v_lshlrev_b64 v[6:7], 8, v[24:25]
	v_mov_b32_e32 v21, s4
	v_or_b32_e32 v20, s10, v154
	v_lshl_add_u64 v[48:49], v[4:5], 0, v[6:7]
	v_lshlrev_b64 v[6:7], 8, v[20:21]
	v_add_u32_e32 v36, s26, v132
	v_lshl_add_u64 v[52:53], v[4:5], 0, v[6:7]
	v_add_u32_e32 v4, v36, v194
	ds_read_b128 v[4:7], v4
	s_lshl_b32 s4, s11, 8
	v_lshl_add_u64 v[22:23], v[142:143], 0, s[4:5]
	v_lshlrev_b64 v[50:51], 12, v[50:51]
	v_lshl_add_u64 v[50:51], v[22:23], 0, v[50:51]
	s_waitcnt lgkmcnt(0)
	v_lshlrev_b32_e32 v17, 16, v4
	v_and_b32_e32 v4, 0xffff0000, v4
	v_lshlrev_b64 v[34:35], 12, v[34:35]
	v_lshl_add_u64 v[34:35], v[22:23], 0, v[34:35]
	v_lshlrev_b64 v[32:33], 12, v[32:33]
	v_lshl_add_u64 v[32:33], v[22:23], 0, v[32:33]
	v_lshlrev_b64 v[30:31], 12, v[30:31]
	v_lshl_add_u64 v[30:31], v[22:23], 0, v[30:31]
	v_readfirstlane_b32 s0, v183
	s_lshl_b32 s10, s11, 7
	s_sub_i32 s4, 7, s23
	s_lshr_b32 s6, s0, 6
	s_add_u32 s82, s92, s24
	s_addc_u32 s83, s93, 0
	s_lshl_b32 s17, s4, 8
	s_lshl_b32 s0, s6, 5
	s_add_i32 s20, s0, s17
	s_add_i32 s11, s20, s22
	s_mov_b32 s0, 0xcf00000
	s_lshr_b32 s13, s20, 6
	v_mov_b32_e32 v161, v129
	s_waitcnt vmcnt(1)
	v_lshlrev_b32_e32 v8, 16, v0
	v_and_b32_e32 v0, 0xffff0000, v0
	v_mul_f32_e32 v16, 0xbfb8aa3b, v0
	v_exp_f32_e32 v16, v16
	v_mul_f32_e32 v9, 0xbfb8aa3b, v8
	v_exp_f32_e32 v9, v9
	v_add_f32_e32 v16, 1.0, v16
	v_rcp_f32_e32 v16, v16
	v_add_f32_e32 v9, 1.0, v9
	v_rcp_f32_e32 v9, v9
	v_mul_f32_e32 v0, v16, v0
	v_mul_f32_e32 v54, v0, v4
	v_lshlrev_b32_e32 v0, 16, v1
	v_mul_f32_e32 v8, v9, v8
	v_mul_f32_e32 v4, 0xbfb8aa3b, v0
	v_and_b32_e32 v1, 0xffff0000, v1
	v_mul_f32_e32 v37, v8, v17
	v_exp_f32_e32 v4, v4
	v_mul_f32_e32 v8, 0xbfb8aa3b, v1
	v_exp_f32_e32 v8, v8
	v_lshlrev_b32_e32 v9, 16, v5
	v_add_f32_e32 v4, 1.0, v4
	v_rcp_f32_e32 v4, v4
	v_add_f32_e32 v8, 1.0, v8
	v_rcp_f32_e32 v8, v8
	v_mul_f32_e32 v0, v4, v0
	v_mul_f32_e32 v55, v0, v9
	v_and_b32_e32 v0, 0xffff0000, v5
	v_mul_f32_e32 v1, v8, v1
	v_mul_f32_e32 v56, v1, v0
	v_lshlrev_b32_e32 v0, 16, v2
	v_mul_f32_e32 v1, 0xbfb8aa3b, v0
	v_and_b32_e32 v2, 0xffff0000, v2
	v_exp_f32_e32 v1, v1
	v_mul_f32_e32 v4, 0xbfb8aa3b, v2
	v_exp_f32_e32 v4, v4
	v_lshlrev_b32_e32 v5, 16, v6
	v_add_f32_e32 v1, 1.0, v1
	v_rcp_f32_e32 v1, v1
	v_add_f32_e32 v4, 1.0, v4
	v_rcp_f32_e32 v4, v4
	v_mul_f32_e32 v0, v1, v0
	v_mul_f32_e32 v57, v0, v5
	v_and_b32_e32 v0, 0xffff0000, v6
	v_mul_f32_e32 v1, v4, v2
	v_mul_f32_e32 v58, v1, v0
	v_lshlrev_b32_e32 v0, 16, v3
	v_mul_f32_e32 v1, 0xbfb8aa3b, v0
	v_and_b32_e32 v2, 0xffff0000, v3
	v_exp_f32_e32 v1, v1
	v_mul_f32_e32 v3, 0xbfb8aa3b, v2
	v_exp_f32_e32 v3, v3
	v_lshlrev_b32_e32 v4, 16, v7
	v_add_f32_e32 v1, 1.0, v1
	v_rcp_f32_e32 v1, v1
	v_add_f32_e32 v3, 1.0, v3
	v_rcp_f32_e32 v3, v3
	v_mul_f32_e32 v0, v1, v0
	v_mul_f32_e32 v59, v0, v4
	v_and_b32_e32 v0, 0xffff0000, v7
	v_mul_f32_e32 v1, v3, v2
	v_mul_f32_e32 v60, v1, v0
	global_load_dwordx4 v[42:45], v[10:11], off nt
	global_load_dwordx4 v[16:19], v[12:13], off nt
	s_nop 0
	global_load_dwordx4 v[12:15], v[14:15], off nt
	s_nop 0
	global_load_dwordx4 v[8:11], v[46:47], off nt
	global_load_dwordx4 v[4:7], v[48:49], off nt
	global_load_dwordx4 v[0:3], v[52:53], off nt
	v_cvt_pk_bf16_f32 v46, v37, v54
	v_cvt_pk_bf16_f32 v47, v55, v56
	v_cvt_pk_bf16_f32 v48, v57, v58
	v_cvt_pk_bf16_f32 v49, v59, v60
	v_add_u32_e32 v37, v36, v195
	global_store_dwordx4 v[50:51], v[46:49], off
	ds_read_b128 v[46:49], v37
	s_waitcnt vmcnt(7)
; __device__ __forceinline__ float bf2f(short s) { return __uint_as_float(((unsigned)(unsigned short)s) << 16); }
; __device__ __forceinline__ float silu_fast(float g) { return g * __builtin_amdgcn_rcpf(1.f + __builtin_amdgcn_exp2f(-g * LOG2E)); }
; __device__ __forceinline__ bf16x8 tobf8(f32x8 x) { u32x4 w = {cvtpk(x[0], x[1]), cvtpk(x[2], x[3]), cvtpk(x[4], x[5]), cvtpk(x[6], x[7])}; return *reinterpret_cast<bf16x8*>(&w); }
; template <int MODE, bool SAMPLE>
; __device__ __forceinline__ void attn_unit(const Params& p, char* lds, int b, int h, int qb) {
;     ...
;         for (int it = 0; it < NIT; ++it) { const int row = it * 4 + er; const bf16x8 mx = *(const bf16x8*)(Qs + row * 256 + ec * 2); f32x8 y;
; #pragma unroll
;             for (int i = 0; i < 8; ++i) y[i] = bf2f(mx[i]) * silu_fast(bf2f(gt[it][i]));
;             *(bf16x8*)(MIX + (rbase + row) * DM + MODE * 1024 + h * HD + ec) = tobf8(y); }
;     }
;     __syncthreads();
	v_lshlrev_b32_e32 v37, 16, v38
	v_and_b32_e32 v38, 0xffff0000, v38
	v_mul_f32_e32 v51, 0xbfb8aa3b, v38
	v_exp_f32_e32 v51, v51
	v_mul_f32_e32 v50, 0xbfb8aa3b, v37
	v_exp_f32_e32 v50, v50
	s_waitcnt lgkmcnt(0)
	v_lshlrev_b32_e32 v52, 16, v46
	v_add_f32_e32 v51, 1.0, v51
	v_rcp_f32_e32 v51, v51
	v_and_b32_e32 v46, 0xffff0000, v46
	v_add_f32_e32 v50, 1.0, v50
	v_rcp_f32_e32 v50, v50
	v_mul_f32_e32 v38, v51, v38
	v_mul_f32_e32 v38, v38, v46
	v_lshlrev_b32_e32 v46, 16, v39
	v_and_b32_e32 v39, 0xffff0000, v39
	v_mul_f32_e32 v51, 0xbfb8aa3b, v39
	v_exp_f32_e32 v51, v51
	v_mul_f32_e32 v37, v50, v37
	v_mul_f32_e32 v50, 0xbfb8aa3b, v46
	v_exp_f32_e32 v50, v50
	v_add_f32_e32 v51, 1.0, v51
	v_rcp_f32_e32 v51, v51
	v_mul_f32_e32 v37, v37, v52
	v_add_f32_e32 v50, 1.0, v50
	v_lshlrev_b32_e32 v52, 16, v47
	v_and_b32_e32 v47, 0xffff0000, v47
	v_mul_f32_e32 v39, v51, v39
	v_rcp_f32_e32 v50, v50
	v_mul_f32_e32 v39, v39, v47
	v_lshlrev_b32_e32 v47, 16, v40
	v_and_b32_e32 v40, 0xffff0000, v40
	v_mul_f32_e32 v51, 0xbfb8aa3b, v40
	v_exp_f32_e32 v51, v51
	v_mul_f32_e32 v46, v50, v46
	v_mul_f32_e32 v50, 0xbfb8aa3b, v47
	v_exp_f32_e32 v50, v50
	v_add_f32_e32 v51, 1.0, v51
	v_rcp_f32_e32 v51, v51
	v_mul_f32_e32 v46, v46, v52
	v_add_f32_e32 v50, 1.0, v50
	v_rcp_f32_e32 v50, v50
	v_lshlrev_b32_e32 v52, 16, v48
	v_and_b32_e32 v48, 0xffff0000, v48
	v_mul_f32_e32 v40, v51, v40
	v_mul_f32_e32 v40, v40, v48
	v_lshlrev_b32_e32 v48, 16, v41
	v_and_b32_e32 v41, 0xffff0000, v41
	v_mul_f32_e32 v51, 0xbfb8aa3b, v41
	v_mul_f32_e32 v47, v50, v47
	v_mul_f32_e32 v50, 0xbfb8aa3b, v48
	v_exp_f32_e32 v51, v51
	v_exp_f32_e32 v50, v50
	v_mul_f32_e32 v47, v47, v52
	v_lshlrev_b32_e32 v52, 16, v49
	v_add_f32_e32 v51, 1.0, v51
	v_add_f32_e32 v50, 1.0, v50
	v_rcp_f32_e32 v51, v51
	v_rcp_f32_e32 v50, v50
	v_and_b32_e32 v49, 0xffff0000, v49
	v_cvt_pk_bf16_f32 v38, v37, v38
	v_mul_f32_e32 v41, v51, v41
	v_mul_f32_e32 v48, v50, v48
	v_mul_f32_e32 v41, v41, v49
	v_mul_f32_e32 v48, v48, v52
	v_cvt_pk_bf16_f32 v39, v46, v39
	v_cvt_pk_bf16_f32 v40, v47, v40
	v_cvt_pk_bf16_f32 v41, v48, v41
	global_store_dwordx4 v[34:35], v[38:41], off
	v_add_u32_e32 v34, v36, v196
	ds_read_b128 v[38:41], v34
	s_waitcnt vmcnt(7)
	v_lshlrev_b32_e32 v34, 16, v42
	v_and_b32_e32 v37, 0xffff0000, v42
	v_mul_f32_e32 v35, 0xbfb8aa3b, v34
	v_mul_f32_e32 v42, 0xbfb8aa3b, v37
	v_exp_f32_e32 v35, v35
	v_exp_f32_e32 v42, v42
	s_waitcnt lgkmcnt(0)
	v_lshlrev_b32_e32 v46, 16, v38
	v_add_f32_e32 v35, 1.0, v35
	v_add_f32_e32 v42, 1.0, v42
	v_rcp_f32_e32 v35, v35
	v_rcp_f32_e32 v42, v42
	v_mul_f32_e32 v34, v35, v34
	v_and_b32_e32 v35, 0xffff0000, v38
	v_mul_f32_e32 v37, v42, v37
	v_mul_f32_e32 v35, v37, v35
	v_lshlrev_b32_e32 v37, 16, v43
	v_and_b32_e32 v42, 0xffff0000, v43
	v_mul_f32_e32 v38, 0xbfb8aa3b, v37
	v_mul_f32_e32 v43, 0xbfb8aa3b, v42
	v_exp_f32_e32 v38, v38
	v_exp_f32_e32 v43, v43
	v_mul_f32_e32 v34, v34, v46
	v_lshlrev_b32_e32 v46, 16, v39
	v_add_f32_e32 v38, 1.0, v38
	v_add_f32_e32 v43, 1.0, v43
	v_rcp_f32_e32 v38, v38
	v_rcp_f32_e32 v43, v43
	v_mul_f32_e32 v37, v38, v37
	v_and_b32_e32 v38, 0xffff0000, v39
	v_mul_f32_e32 v39, v43, v42
	v_mul_f32_e32 v39, v39, v38
	v_lshlrev_b32_e32 v38, 16, v44
	v_mul_f32_e32 v42, 0xbfb8aa3b, v38
	v_and_b32_e32 v43, 0xffff0000, v44
	v_exp_f32_e32 v42, v42
	v_mul_f32_e32 v44, 0xbfb8aa3b, v43
	v_exp_f32_e32 v44, v44
	v_mul_f32_e32 v37, v37, v46
	v_add_f32_e32 v42, 1.0, v42
	v_rcp_f32_e32 v42, v42
	v_add_f32_e32 v44, 1.0, v44
	v_rcp_f32_e32 v44, v44
	v_lshlrev_b32_e32 v46, 16, v40
	v_mul_f32_e32 v38, v42, v38
	v_mul_f32_e32 v42, v38, v46
	v_and_b32_e32 v38, 0xffff0000, v40
	v_mul_f32_e32 v40, v44, v43
	v_mul_f32_e32 v40, v40, v38
	v_lshlrev_b32_e32 v38, 16, v45
	v_mul_f32_e32 v43, 0xbfb8aa3b, v38
	v_and_b32_e32 v44, 0xffff0000, v45
	v_exp_f32_e32 v43, v43
	v_mul_f32_e32 v45, 0xbfb8aa3b, v44
	v_exp_f32_e32 v45, v45
	v_lshlrev_b32_e32 v46, 16, v41
	v_add_f32_e32 v43, 1.0, v43
	v_rcp_f32_e32 v43, v43
	v_add_f32_e32 v45, 1.0, v45
	v_rcp_f32_e32 v45, v45
	v_mul_f32_e32 v38, v43, v38
	v_mul_f32_e32 v43, v38, v46
	v_and_b32_e32 v38, 0xffff0000, v41
	v_mul_f32_e32 v41, v45, v44
	v_mul_f32_e32 v41, v41, v38
	v_cvt_pk_bf16_f32 v38, v34, v35
	v_cvt_pk_bf16_f32 v39, v37, v39
	s_waitcnt vmcnt(6)
	v_lshlrev_b32_e32 v37, 16, v16
	v_and_b32_e32 v16, 0xffff0000, v16
	v_cvt_pk_bf16_f32 v40, v42, v40
	v_cvt_pk_bf16_f32 v41, v43, v41
	global_store_dwordx4 v[32:33], v[38:41], off
	v_add_u32_e32 v32, v36, v197
	ds_read_b128 v[32:35], v32
	v_mul_f32_e32 v39, 0xbfb8aa3b, v16
	v_exp_f32_e32 v39, v39
	v_mul_f32_e32 v38, 0xbfb8aa3b, v37
	v_exp_f32_e32 v38, v38
	s_waitcnt lgkmcnt(0)
	v_lshlrev_b32_e32 v40, 16, v32
	v_add_f32_e32 v39, 1.0, v39
	v_rcp_f32_e32 v39, v39
	v_and_b32_e32 v32, 0xffff0000, v32
	v_add_f32_e32 v38, 1.0, v38
	v_rcp_f32_e32 v38, v38
	v_mul_f32_e32 v16, v39, v16
	v_mul_f32_e32 v16, v16, v32
	v_lshlrev_b32_e32 v32, 16, v17
	v_and_b32_e32 v17, 0xffff0000, v17
	v_mul_f32_e32 v39, 0xbfb8aa3b, v17
	v_exp_f32_e32 v39, v39
	v_mul_f32_e32 v37, v38, v37
	v_mul_f32_e32 v38, 0xbfb8aa3b, v32
	v_exp_f32_e32 v38, v38
	v_add_f32_e32 v39, 1.0, v39
	v_rcp_f32_e32 v39, v39
	v_mul_f32_e32 v37, v37, v40
	v_add_f32_e32 v38, 1.0, v38
	v_lshlrev_b32_e32 v40, 16, v33
	v_and_b32_e32 v33, 0xffff0000, v33
	v_mul_f32_e32 v17, v39, v17
	v_rcp_f32_e32 v38, v38
	v_mul_f32_e32 v17, v17, v33
	v_lshlrev_b32_e32 v33, 16, v18
	v_and_b32_e32 v18, 0xffff0000, v18
	v_mul_f32_e32 v39, 0xbfb8aa3b, v18
	v_exp_f32_e32 v39, v39
	v_mul_f32_e32 v32, v38, v32
	v_mul_f32_e32 v38, 0xbfb8aa3b, v33
	v_exp_f32_e32 v38, v38
	v_add_f32_e32 v39, 1.0, v39
	v_rcp_f32_e32 v39, v39
	v_mul_f32_e32 v32, v32, v40
	v_add_f32_e32 v38, 1.0, v38
	v_rcp_f32_e32 v38, v38
	v_lshlrev_b32_e32 v40, 16, v34
	v_and_b32_e32 v34, 0xffff0000, v34
	v_mul_f32_e32 v18, v39, v18
	v_mul_f32_e32 v18, v18, v34
	v_lshlrev_b32_e32 v34, 16, v19
	v_and_b32_e32 v19, 0xffff0000, v19
	v_mul_f32_e32 v39, 0xbfb8aa3b, v19
	v_mul_f32_e32 v33, v38, v33
	v_mul_f32_e32 v38, 0xbfb8aa3b, v34
	v_exp_f32_e32 v39, v39
	v_exp_f32_e32 v38, v38
	v_mul_f32_e32 v33, v33, v40
	v_lshlrev_b32_e32 v40, 16, v35
	v_add_f32_e32 v39, 1.0, v39
	v_add_f32_e32 v38, 1.0, v38
	v_rcp_f32_e32 v39, v39
	v_rcp_f32_e32 v38, v38
	v_and_b32_e32 v35, 0xffff0000, v35
	v_cvt_pk_bf16_f32 v16, v37, v16
	v_mul_f32_e32 v19, v39, v19
	v_mul_f32_e32 v34, v38, v34
	v_mul_f32_e32 v19, v19, v35
	v_mul_f32_e32 v34, v34, v40
	v_cvt_pk_bf16_f32 v17, v32, v17
	v_cvt_pk_bf16_f32 v18, v33, v18
	v_cvt_pk_bf16_f32 v19, v34, v19
	global_store_dwordx4 v[30:31], v[16:19], off
	s_waitcnt vmcnt(7)
; __device__ __forceinline__ float bf2f(short s) { return __uint_as_float(((unsigned)(unsigned short)s) << 16); }
; __device__ __forceinline__ float silu_fast(float g) { return g * __builtin_amdgcn_rcpf(1.f + __builtin_amdgcn_exp2f(-g * LOG2E)); }
; __device__ __forceinline__ bf16x8 tobf8(f32x8 x) { u32x4 w = {cvtpk(x[0], x[1]), cvtpk(x[2], x[3]), cvtpk(x[4], x[5]), cvtpk(x[6], x[7])}; return *reinterpret_cast<bf16x8*>(&w); }
; template <int MODE, bool SAMPLE>
; __device__ __forceinline__ void attn_unit(const Params& p, char* lds, int b, int h, int qb) {
;     ...
;         for (int it = 0; it < NIT; ++it) { const int row = it * 4 + er; const bf16x8 mx = *(const bf16x8*)(Qs + row * 256 + ec * 2); f32x8 y;
; #pragma unroll
;             for (int i = 0; i < 8; ++i) y[i] = bf2f(mx[i]) * silu_fast(bf2f(gt[it][i]));
;             *(bf16x8*)(MIX + (rbase + row) * DM + MODE * 1024 + h * HD + ec) = tobf8(y); }
;     }
;     __syncthreads();
	v_lshlrev_b32_e32 v30, 16, v12
	v_and_b32_e32 v12, 0xffff0000, v12
	v_mul_f32_e32 v32, 0xbfb8aa3b, v12
	v_exp_f32_e32 v32, v32
	v_add_u32_e32 v16, v36, v171
	ds_read_b128 v[16:19], v16
	v_mul_f32_e32 v31, 0xbfb8aa3b, v30
	v_add_f32_e32 v32, 1.0, v32
	v_rcp_f32_e32 v32, v32
	v_exp_f32_e32 v31, v31
	s_waitcnt lgkmcnt(0)
	v_lshlrev_b32_e32 v33, 16, v16
	v_and_b32_e32 v16, 0xffff0000, v16
	v_mul_f32_e32 v12, v32, v12
	v_mul_f32_e32 v12, v12, v16
	v_lshlrev_b32_e32 v16, 16, v13
	v_and_b32_e32 v13, 0xffff0000, v13
	v_add_f32_e32 v31, 1.0, v31
	v_mul_f32_e32 v32, 0xbfb8aa3b, v13
	v_rcp_f32_e32 v31, v31
	v_exp_f32_e32 v32, v32
	v_mul_f32_e32 v30, v31, v30
	v_mul_f32_e32 v31, 0xbfb8aa3b, v16
	v_add_f32_e32 v32, 1.0, v32
	v_exp_f32_e32 v31, v31
	v_rcp_f32_e32 v32, v32
	v_mul_f32_e32 v30, v30, v33
	v_lshlrev_b32_e32 v33, 16, v17
	v_add_f32_e32 v31, 1.0, v31
	v_and_b32_e32 v17, 0xffff0000, v17
	v_mul_f32_e32 v13, v32, v13
	v_rcp_f32_e32 v31, v31
	v_mul_f32_e32 v13, v13, v17
	v_lshlrev_b32_e32 v17, 16, v14
	v_and_b32_e32 v14, 0xffff0000, v14
	v_mul_f32_e32 v32, 0xbfb8aa3b, v14
	v_exp_f32_e32 v32, v32
	v_mul_f32_e32 v16, v31, v16
	v_mul_f32_e32 v31, 0xbfb8aa3b, v17
	v_exp_f32_e32 v31, v31
	v_add_f32_e32 v32, 1.0, v32
	v_rcp_f32_e32 v32, v32
	v_mul_f32_e32 v16, v16, v33
	v_add_f32_e32 v31, 1.0, v31
	v_rcp_f32_e32 v31, v31
	v_lshlrev_b32_e32 v33, 16, v18
	v_and_b32_e32 v18, 0xffff0000, v18
	v_mul_f32_e32 v14, v32, v14
	v_mul_f32_e32 v14, v14, v18
	v_lshlrev_b32_e32 v18, 16, v15
	v_and_b32_e32 v15, 0xffff0000, v15
	v_mul_f32_e32 v32, 0xbfb8aa3b, v15
	v_mul_f32_e32 v17, v31, v17
	v_mul_f32_e32 v31, 0xbfb8aa3b, v18
	v_exp_f32_e32 v32, v32
	v_exp_f32_e32 v31, v31
	v_mul_f32_e32 v17, v17, v33
	v_lshlrev_b32_e32 v33, 16, v19
	v_add_f32_e32 v32, 1.0, v32
	v_add_f32_e32 v31, 1.0, v31
	v_rcp_f32_e32 v32, v32
	v_rcp_f32_e32 v31, v31
	v_and_b32_e32 v19, 0xffff0000, v19
	v_cvt_pk_bf16_f32 v12, v30, v12
	v_mul_f32_e32 v15, v32, v15
	v_cvt_pk_bf16_f32 v13, v16, v13
	v_cvt_pk_bf16_f32 v14, v17, v14
	v_lshlrev_b64 v[16:17], 12, v[28:29]
	v_mul_f32_e32 v18, v31, v18
	v_mul_f32_e32 v15, v15, v19
	v_lshl_add_u64 v[16:17], v[22:23], 0, v[16:17]
	v_mul_f32_e32 v18, v18, v33
	v_cvt_pk_bf16_f32 v15, v18, v15
	global_store_dwordx4 v[16:17], v[12:15], off
	s_waitcnt vmcnt(7)
	v_lshlrev_b32_e32 v16, 16, v8
	v_and_b32_e32 v8, 0xffff0000, v8
	v_mul_f32_e32 v18, 0xbfb8aa3b, v8
	v_exp_f32_e32 v18, v18
	v_add_u32_e32 v12, v36, v210
	ds_read_b128 v[12:15], v12
	v_mul_f32_e32 v17, 0xbfb8aa3b, v16
	v_add_f32_e32 v18, 1.0, v18
	v_rcp_f32_e32 v18, v18
	v_exp_f32_e32 v17, v17
	s_waitcnt lgkmcnt(0)
	v_lshlrev_b32_e32 v19, 16, v12
	v_and_b32_e32 v12, 0xffff0000, v12
	v_mul_f32_e32 v8, v18, v8
	v_mul_f32_e32 v8, v8, v12
	v_lshlrev_b32_e32 v12, 16, v9
	v_and_b32_e32 v9, 0xffff0000, v9
	v_add_f32_e32 v17, 1.0, v17
	v_mul_f32_e32 v18, 0xbfb8aa3b, v9
	v_rcp_f32_e32 v17, v17
	v_exp_f32_e32 v18, v18
	v_mul_f32_e32 v16, v17, v16
	v_mul_f32_e32 v17, 0xbfb8aa3b, v12
	v_add_f32_e32 v18, 1.0, v18
	v_exp_f32_e32 v17, v17
	v_rcp_f32_e32 v18, v18
	v_mul_f32_e32 v16, v16, v19
	v_lshlrev_b32_e32 v19, 16, v13
	v_add_f32_e32 v17, 1.0, v17
	v_and_b32_e32 v13, 0xffff0000, v13
	v_mul_f32_e32 v9, v18, v9
	v_rcp_f32_e32 v17, v17
	v_mul_f32_e32 v9, v9, v13
	v_lshlrev_b32_e32 v13, 16, v10
	v_and_b32_e32 v10, 0xffff0000, v10
	v_mul_f32_e32 v18, 0xbfb8aa3b, v10
	v_exp_f32_e32 v18, v18
	v_mul_f32_e32 v12, v17, v12
	v_mul_f32_e32 v17, 0xbfb8aa3b, v13
	v_exp_f32_e32 v17, v17
	v_add_f32_e32 v18, 1.0, v18
	v_rcp_f32_e32 v18, v18
	v_mul_f32_e32 v12, v12, v19
	v_add_f32_e32 v17, 1.0, v17
	v_rcp_f32_e32 v17, v17
	v_lshlrev_b32_e32 v19, 16, v14
	v_and_b32_e32 v14, 0xffff0000, v14
	v_mul_f32_e32 v10, v18, v10
	v_mul_f32_e32 v10, v10, v14
	v_lshlrev_b32_e32 v14, 16, v11
	v_and_b32_e32 v11, 0xffff0000, v11
	v_mul_f32_e32 v18, 0xbfb8aa3b, v11
	v_mul_f32_e32 v13, v17, v13
	v_mul_f32_e32 v17, 0xbfb8aa3b, v14
	v_exp_f32_e32 v18, v18
	v_exp_f32_e32 v17, v17
	v_mul_f32_e32 v13, v13, v19
	v_lshlrev_b32_e32 v19, 16, v15
	v_add_f32_e32 v18, 1.0, v18
	v_add_f32_e32 v17, 1.0, v17
	v_rcp_f32_e32 v18, v18
	v_rcp_f32_e32 v17, v17
	v_and_b32_e32 v15, 0xffff0000, v15
	v_cvt_pk_bf16_f32 v8, v16, v8
	v_mul_f32_e32 v11, v18, v11
	v_cvt_pk_bf16_f32 v9, v12, v9
	v_cvt_pk_bf16_f32 v10, v13, v10
	v_lshlrev_b64 v[12:13], 12, v[26:27]
	v_mul_f32_e32 v14, v17, v14
	v_mul_f32_e32 v11, v11, v15
	v_lshl_add_u64 v[12:13], v[22:23], 0, v[12:13]
	v_mul_f32_e32 v14, v14, v19
	v_cvt_pk_bf16_f32 v11, v14, v11
	global_store_dwordx4 v[12:13], v[8:11], off
	s_waitcnt vmcnt(7)
	v_lshlrev_b32_e32 v12, 16, v4
	v_and_b32_e32 v4, 0xffff0000, v4
	v_mul_f32_e32 v14, 0xbfb8aa3b, v4
	v_exp_f32_e32 v14, v14
	v_add_u32_e32 v8, v36, v211
	ds_read_b128 v[8:11], v8
	v_mul_f32_e32 v13, 0xbfb8aa3b, v12
	v_add_f32_e32 v14, 1.0, v14
	v_rcp_f32_e32 v14, v14
	v_exp_f32_e32 v13, v13
	s_waitcnt lgkmcnt(0)
; __device__ __forceinline__ float bf2f(short s) { return __uint_as_float(((unsigned)(unsigned short)s) << 16); }
; __device__ __forceinline__ float silu_fast(float g) { return g * __builtin_amdgcn_rcpf(1.f + __builtin_amdgcn_exp2f(-g * LOG2E)); }
; __device__ __forceinline__ bf16x8 tobf8(f32x8 x) { u32x4 w = {cvtpk(x[0], x[1]), cvtpk(x[2], x[3]), cvtpk(x[4], x[5]), cvtpk(x[6], x[7])}; return *reinterpret_cast<bf16x8*>(&w); }
; template <int MODE, bool SAMPLE>
; __device__ __forceinline__ void attn_unit(const Params& p, char* lds, int b, int h, int qb) {
;     ...
;         for (int it = 0; it < NIT; ++it) { const int row = it * 4 + er; const bf16x8 mx = *(const bf16x8*)(Qs + row * 256 + ec * 2); f32x8 y;
; #pragma unroll
;             for (int i = 0; i < 8; ++i) y[i] = bf2f(mx[i]) * silu_fast(bf2f(gt[it][i]));
;             *(bf16x8*)(MIX + (rbase + row) * DM + MODE * 1024 + h * HD + ec) = tobf8(y); }
;     }
;     __syncthreads();
	v_lshlrev_b32_e32 v15, 16, v8
	v_and_b32_e32 v8, 0xffff0000, v8
	v_mul_f32_e32 v4, v14, v4
	v_mul_f32_e32 v4, v4, v8
	v_lshlrev_b32_e32 v8, 16, v5
	v_and_b32_e32 v5, 0xffff0000, v5
	v_add_f32_e32 v13, 1.0, v13
	v_mul_f32_e32 v14, 0xbfb8aa3b, v5
	v_rcp_f32_e32 v13, v13
	v_exp_f32_e32 v14, v14
	v_mul_f32_e32 v12, v13, v12
	v_mul_f32_e32 v13, 0xbfb8aa3b, v8
	v_add_f32_e32 v14, 1.0, v14
	v_exp_f32_e32 v13, v13
	v_rcp_f32_e32 v14, v14
	v_mul_f32_e32 v12, v12, v15
	v_lshlrev_b32_e32 v15, 16, v9
	v_add_f32_e32 v13, 1.0, v13
	v_and_b32_e32 v9, 0xffff0000, v9
	v_mul_f32_e32 v5, v14, v5
	v_rcp_f32_e32 v13, v13
	v_mul_f32_e32 v5, v5, v9
	v_lshlrev_b32_e32 v9, 16, v6
	v_and_b32_e32 v6, 0xffff0000, v6
	v_mul_f32_e32 v14, 0xbfb8aa3b, v6
	v_exp_f32_e32 v14, v14
	v_mul_f32_e32 v8, v13, v8
	v_mul_f32_e32 v13, 0xbfb8aa3b, v9
	v_exp_f32_e32 v13, v13
	v_add_f32_e32 v14, 1.0, v14
	v_rcp_f32_e32 v14, v14
	v_mul_f32_e32 v8, v8, v15
	v_add_f32_e32 v13, 1.0, v13
	v_rcp_f32_e32 v13, v13
	v_lshlrev_b32_e32 v15, 16, v10
	v_and_b32_e32 v10, 0xffff0000, v10
	v_mul_f32_e32 v6, v14, v6
	v_mul_f32_e32 v6, v6, v10
	v_lshlrev_b32_e32 v10, 16, v7
	v_and_b32_e32 v7, 0xffff0000, v7
	v_mul_f32_e32 v14, 0xbfb8aa3b, v7
	v_mul_f32_e32 v9, v13, v9
	v_mul_f32_e32 v13, 0xbfb8aa3b, v10
	v_exp_f32_e32 v14, v14
	v_exp_f32_e32 v13, v13
	v_mul_f32_e32 v9, v9, v15
	v_lshlrev_b32_e32 v15, 16, v11
	v_add_f32_e32 v14, 1.0, v14
	v_add_f32_e32 v13, 1.0, v13
	v_rcp_f32_e32 v14, v14
	v_rcp_f32_e32 v13, v13
	v_and_b32_e32 v11, 0xffff0000, v11
	v_cvt_pk_bf16_f32 v4, v12, v4
	v_mul_f32_e32 v7, v14, v7
	v_cvt_pk_bf16_f32 v5, v8, v5
	v_cvt_pk_bf16_f32 v6, v9, v6
	v_lshlrev_b64 v[8:9], 12, v[24:25]
	v_mul_f32_e32 v10, v13, v10
	v_mul_f32_e32 v7, v7, v11
	v_lshl_add_u64 v[8:9], v[22:23], 0, v[8:9]
	v_mul_f32_e32 v10, v10, v15
	v_cvt_pk_bf16_f32 v7, v10, v7
	global_store_dwordx4 v[8:9], v[4:7], off
	s_waitcnt vmcnt(7)
	v_lshlrev_b32_e32 v8, 16, v0
	v_and_b32_e32 v0, 0xffff0000, v0
	v_mul_f32_e32 v10, 0xbfb8aa3b, v0
	v_exp_f32_e32 v10, v10
	v_add_u32_e32 v4, v36, v212
	ds_read_b128 v[4:7], v4
	v_mul_f32_e32 v9, 0xbfb8aa3b, v8
	v_add_f32_e32 v10, 1.0, v10
	v_rcp_f32_e32 v10, v10
	v_exp_f32_e32 v9, v9
	s_waitcnt lgkmcnt(0)
	v_lshlrev_b32_e32 v11, 16, v4
	v_and_b32_e32 v4, 0xffff0000, v4
	v_mul_f32_e32 v0, v10, v0
	v_mul_f32_e32 v0, v0, v4
	v_lshlrev_b32_e32 v4, 16, v1
	v_and_b32_e32 v1, 0xffff0000, v1
	v_add_f32_e32 v9, 1.0, v9
	v_mul_f32_e32 v10, 0xbfb8aa3b, v1
	v_rcp_f32_e32 v9, v9
	v_exp_f32_e32 v10, v10
	v_mul_f32_e32 v8, v9, v8
	v_mul_f32_e32 v9, 0xbfb8aa3b, v4
	v_add_f32_e32 v10, 1.0, v10
	v_exp_f32_e32 v9, v9
	v_rcp_f32_e32 v10, v10
	v_mul_f32_e32 v8, v8, v11
	v_lshlrev_b32_e32 v11, 16, v5
	v_add_f32_e32 v9, 1.0, v9
	v_and_b32_e32 v5, 0xffff0000, v5
	v_mul_f32_e32 v1, v10, v1
	v_rcp_f32_e32 v9, v9
	v_mul_f32_e32 v1, v1, v5
	v_lshlrev_b32_e32 v5, 16, v2
	v_and_b32_e32 v2, 0xffff0000, v2
	v_mul_f32_e32 v10, 0xbfb8aa3b, v2
	v_exp_f32_e32 v10, v10
	v_mul_f32_e32 v4, v9, v4
	v_mul_f32_e32 v9, 0xbfb8aa3b, v5
	v_exp_f32_e32 v9, v9
	v_add_f32_e32 v10, 1.0, v10
	v_rcp_f32_e32 v10, v10
	v_mul_f32_e32 v4, v4, v11
	v_add_f32_e32 v9, 1.0, v9
	v_rcp_f32_e32 v9, v9
	v_lshlrev_b32_e32 v11, 16, v6
	v_and_b32_e32 v6, 0xffff0000, v6
	v_mul_f32_e32 v2, v10, v2
	v_mul_f32_e32 v2, v2, v6
	v_lshlrev_b32_e32 v6, 16, v3
	v_and_b32_e32 v3, 0xffff0000, v3
	v_mul_f32_e32 v10, 0xbfb8aa3b, v3
	v_mul_f32_e32 v5, v9, v5
	v_mul_f32_e32 v9, 0xbfb8aa3b, v6
	v_exp_f32_e32 v10, v10
	v_exp_f32_e32 v9, v9
	v_mul_f32_e32 v5, v5, v11
	v_lshlrev_b32_e32 v11, 16, v7
	v_add_f32_e32 v10, 1.0, v10
	v_add_f32_e32 v9, 1.0, v9
	v_rcp_f32_e32 v10, v10
	v_rcp_f32_e32 v9, v9
	v_and_b32_e32 v7, 0xffff0000, v7
	v_cvt_pk_bf16_f32 v0, v8, v0
	v_mul_f32_e32 v3, v10, v3
	v_cvt_pk_bf16_f32 v1, v4, v1
	v_cvt_pk_bf16_f32 v2, v5, v2
	v_lshlrev_b64 v[4:5], 12, v[20:21]
	v_mul_f32_e32 v6, v9, v6
	v_mul_f32_e32 v3, v3, v7
	v_lshl_add_u64 v[4:5], v[22:23], 0, v[4:5]
	v_mul_f32_e32 v6, v6, v11
	v_cvt_pk_bf16_f32 v3, v6, v3
	global_store_dwordx4 v[4:5], v[0:3], off
	s_barrier
; __device__ __forceinline__ int crow(int r, int hi) { return (r & 3) + 8 * (r >> 2) + 4 * hi; }
; __device__ __forceinline__ int v_st(int k, int c) { const int kk = (k & ~0xC) | ((k & 4) << 1) | ((k & 8) >> 1); return ((kk >> 3) * 4 + (c >> 5)) * 512 + ((kk & 7) * 32 + (c & 31)) * 2; }
; __device__ __forceinline__ int v_rd_base(int lane) { return ((lane & 3) << 3) | (((lane >> 2) & 3) << 6) | (((lane >> 4) & 1) << 5) | (((lane >> 5) & 1) << 8); }
; template <int MODE, bool SAMPLE>
; __device__ __forceinline__ void attn_unit(const Params& p, char* lds, int b, int h, int qb) {
;     ...
;     const size_t qrow = SAMPLE ? (size_t)(MP + b * TS + (r32 & 15)) : (size_t)(b * SEQ + qb * 256 + wid * 32 + r32);
;     const bf16_t* Qw = P1q + qrow * 128 + hi * 8;
;     char* Qs = lds + AL_Q + wid * 8192;
; #pragma unroll
;     for (int d0 = 0; d0 < 8; ++d0) *reinterpret_cast<bf16x8*>(Qs + KSWZ(r32, (d0 * 16 + hi * 8) * 2)) = *reinterpret_cast<const bf16x8*>(Qw + d0 * 16);
;     const int qw0 = SAMPLE ? PAST : qb * 256 + wid * 32;
;     const int qpos = SAMPLE ? PAST + (r32 & 15) : qw0 + r32;
;     const int jd = SAMPLE ? 16 : (qw0 >> 6);
;     const int jfirst = SAMPLE ? 16 : qb * 4 + 3;
;     const bool wact = SAMPLE ? (wid == 0) : true;
;     const int sr = tid >> 4, sc = (tid & 15) * 8;
;     const int vst0 = v_st(sr, sc), vst1 = v_st(32 + sr, sc), kst0 = KSWZ(sr, sc * 2), kst1 = KSWZ(32 + sr, sc * 2);
;     const int vb0 = (int)(uintptr_t)V_lds + v_rd_base(lane);
;     struct StgT { bf16x8 k0, k1, v0, v1; f32x8 fk0, fk1, fv0, fv1; } stg2[SAMPLE ? 1 : NSP];
;     ...
;     f32x16 o[4] = {};
;     float m_reg = -1e30f, l_reg = 0.f, carry = 1.f;
;     constexpr int NS = SAMPLE ? 1 : NSP;
;     constexpr int PAR0 = SAMPLE ? 0 : 1;
;     LOADT(jfirst, stg2[NS == 2 ? PAR0 : 0]); if (NS == 2) LOADT(jfirst - 1, stg2[NS == 2 ? (PAR0 ^ 1) : 0]);
;     ...
;                 if (j == jd) {
; #pragma unroll
;                     for (int r = 0; r < 16; ++r) { const int kp = j * 64 + crow(r, hi); if (kp >= qpos) p0[r] = -1e30f; if (kp + 32 >= qpos) p1[r] = -1e30f; } }
	s_nop 0
	v_or_b32_e32 v0, s11, v131
	v_mov_b32_e32 v1, v129
	v_lshlrev_b64 v[0:1], 8, v[0:1]
	v_lshl_add_u64 v[0:1], s[82:83], 0, v[0:1]
	v_lshl_add_u64 v[4:5], v[0:1], 0, v[146:147]
	v_add_co_u32_e32 v0, vcc, s0, v4
	s_nop 1
	v_addc_co_u32_e32 v1, vcc, 0, v5, vcc
	global_load_dwordx4 v[0:3], v[0:1], off
	s_mov_b64 s[0:1], 0xcf00000
	v_lshl_add_u64 v[28:29], v[4:5], 0, s[0:1]
	global_load_dwordx4 v[4:7], v[28:29], off offset:32
	global_load_dwordx4 v[8:11], v[28:29], off offset:64
	global_load_dwordx4 v[12:15], v[28:29], off offset:96
	global_load_dwordx4 v[16:19], v[28:29], off offset:128
	global_load_dwordx4 v[20:23], v[28:29], off offset:160
	global_load_dwordx4 v[24:27], v[28:29], off offset:192
	s_nop 0
	global_load_dwordx4 v[28:31], v[28:29], off offset:224
	s_lshl_b32 s0, s6, 13
	s_add_i32 s12, s0, 0
	s_add_i32 s12, s12, 0x13000
	v_add_u32_e32 v32, s12, v135
	v_add_u32_e32 v33, v32, v139
	s_lshl_b32 s0, s4, 2
	s_or_b32 s16, s0, 3
	s_add_u32 s0, s82, 0xe000000
	s_addc_u32 s1, s83, 0
	s_lshl_b32 s4, s16, 6
	s_add_i32 s4, s4, s22
	s_lshl_b64 s[18:19], s[4:5], 8
	s_add_u32 s18, s0, s18
	s_addc_u32 s19, s1, s19
	s_add_i32 s4, s25, s17
	v_lshl_add_u64 v[164:165], s[0:1], 0, v[144:145]
	s_waitcnt vmcnt(7)
	ds_write_b128 v33, v[0:3]
	v_add_u32_e32 v0, v32, v141
	s_waitcnt vmcnt(6)
	ds_write_b128 v0, v[4:7]
	v_add_u32_e32 v0, v32, v149
	s_waitcnt vmcnt(5)
	ds_write_b128 v0, v[8:11]
	v_add_u32_e32 v0, v32, v151
	s_waitcnt vmcnt(4)
	ds_write_b128 v0, v[12:15]
	v_add_u32_e32 v0, v32, v153
	s_waitcnt vmcnt(3)
	ds_write_b128 v0, v[16:19]
	v_add_u32_e32 v0, v32, v155
	s_waitcnt vmcnt(2)
	ds_write_b128 v0, v[20:23]
	v_add_u32_e32 v0, v32, v172
	s_waitcnt vmcnt(1)
	ds_write_b128 v0, v[24:27]
	v_add_u32_e32 v0, v32, v173
	s_waitcnt vmcnt(0)
	ds_write_b128 v0, v[28:31]
	v_lshl_add_u64 v[0:1], s[18:19], 0, v[144:145]
	s_lshl_b64 s[18:19], s[4:5], 8
	v_lshl_add_u64 v[2:3], v[0:1], 0, v[128:129]
	v_lshl_add_u64 v[4:5], v[0:1], 0, v[160:161]
	v_lshl_add_u64 v[0:1], v[0:1], 0, s[96:97]
	s_add_u32 s18, s0, s18
	global_load_dwordx4 v[96:99], v[2:3], off
	global_load_dwordx4 v[100:103], v[4:5], off
	v_lshl_add_u64 v[2:3], v[0:1], 0, v[128:129]
	v_lshl_add_u64 v[0:1], v[0:1], 0, v[160:161]
	s_addc_u32 s19, s1, s19
	global_load_dwordx4 v[104:107], v[2:3], off
	global_load_dwordx4 v[108:111], v[0:1], off
	v_lshl_add_u64 v[0:1], s[18:19], 0, v[144:145]
	v_lshl_add_u64 v[2:3], v[0:1], 0, v[128:129]
	v_lshl_add_u64 v[4:5], v[0:1], 0, v[160:161]
	v_lshl_add_u64 v[0:1], v[0:1], 0, s[96:97]
	global_load_dwordx4 v[112:115], v[2:3], off
	global_load_dwordx4 v[116:119], v[4:5], off
	v_lshl_add_u64 v[2:3], v[0:1], 0, v[128:129]
	v_lshl_add_u64 v[0:1], v[0:1], 0, v[160:161]
	global_load_dwordx4 v[120:123], v[2:3], off
	global_load_dwordx4 v[124:127], v[0:1], off
	v_or_b32_e32 v6, s20, v131
	s_andn2_b32 s20, s20, 63
	v_or_b32_e32 v0, s20, v181
	v_or_b32_e32 v1, 32, v0
	v_cmp_lt_i32_e64 s[0:1], v1, v6
	v_or_b32_e32 v1, 1, v0
	v_cmp_lt_i32_e64 s[18:19], v1, v6
	v_or_b32_e32 v1, 33, v0
	v_cmp_lt_i32_e64 s[20:21], v1, v6
	v_or_b32_e32 v1, 2, v0
	v_cmp_lt_i32_e64 s[22:23], v1, v6
	v_or_b32_e32 v1, 34, v0
	v_cmp_lt_i32_e64 s[24:25], v1, v6
	v_or_b32_e32 v1, 3, v0
	v_cmp_lt_i32_e64 s[26:27], v1, v6
	v_or_b32_e32 v1, 35, v0
	v_cmp_lt_i32_e64 s[28:29], v1, v6
	v_or_b32_e32 v1, 8, v0
	v_cmp_lt_i32_e64 s[30:31], v1, v6
	v_or_b32_e32 v1, 40, v0
	v_cmp_lt_i32_e64 s[34:35], v1, v6
	v_or_b32_e32 v1, 9, v0
	v_cmp_lt_i32_e64 s[36:37], v1, v6
	v_or_b32_e32 v1, 41, v0
	v_cmp_lt_i32_e64 s[38:39], v1, v6
	v_or_b32_e32 v1, 10, v0
	v_cmp_lt_i32_e64 s[40:41], v1, v6
	v_or_b32_e32 v1, 42, v0
	v_cmp_lt_i32_e64 s[42:43], v1, v6
	v_or_b32_e32 v1, 11, v0
	v_cmp_lt_i32_e64 s[44:45], v1, v6
	v_or_b32_e32 v1, 43, v0
	v_cmp_lt_i32_e64 s[46:47], v1, v6
	v_or_b32_e32 v1, 16, v0
	v_cmp_lt_i32_e64 s[48:49], v1, v6
	v_or_b32_e32 v1, 48, v0
	v_cmp_lt_i32_e64 s[50:51], v1, v6
	v_or_b32_e32 v1, 17, v0
	v_cmp_lt_i32_e64 s[52:53], v1, v6
	v_or_b32_e32 v1, 49, v0
	v_cmp_lt_i32_e64 s[54:55], v1, v6
	v_or_b32_e32 v1, 18, v0
	v_cmp_lt_i32_e64 s[56:57], v1, v6
	v_or_b32_e32 v1, 50, v0
	v_cmp_lt_i32_e64 s[58:59], v1, v6
	v_or_b32_e32 v1, 19, v0
	v_cmp_lt_i32_e64 s[60:61], v1, v6
	v_or_b32_e32 v1, 51, v0
	v_cmp_lt_i32_e64 s[62:63], v1, v6
	v_or_b32_e32 v1, 24, v0
	v_cmp_lt_i32_e64 s[64:65], v1, v6
	v_or_b32_e32 v1, 56, v0
	v_cmp_lt_i32_e64 s[66:67], v1, v6
	v_or_b32_e32 v1, 25, v0
	v_cmp_lt_i32_e64 s[68:69], v1, v6
	v_or_b32_e32 v1, 57, v0
	v_cmp_lt_i32_e64 s[70:71], v1, v6
	v_or_b32_e32 v1, 26, v0
	s_lshr_b32 s4, s16, 1
	v_cmp_lt_i32_e64 s[72:73], v1, v6
	v_or_b32_e32 v1, 58, v0
	v_cmp_lt_i32_e32 vcc, v0, v6
	v_cmp_lt_i32_e64 s[74:75], v1, v6
	v_or_b32_e32 v1, 27, v0
	v_or_b32_e32 v0, 59, v0
	s_lshl_b32 s6, s4, 7
	v_mov_b32_e32 v14, v129
	v_mov_b32_e32 v15, v129
	v_cmp_lt_i32_e64 s[76:77], v1, v6
	v_cmp_lt_i32_e64 s[78:79], v0, v6
	s_add_i32 s6, s33, s6
	v_mov_b32_e32 v0, v129
	v_mov_b32_e32 v1, v129
	v_mov_b32_e32 v2, v129
	v_mov_b32_e32 v3, v129
	v_mov_b32_e32 v4, v129
	v_mov_b32_e32 v5, v129
	v_mov_b32_e32 v6, v129
	v_mov_b32_e32 v7, v129
	v_mov_b32_e32 v8, v129
	v_mov_b32_e32 v9, v129
	v_mov_b32_e32 v10, v129
	v_mov_b32_e32 v11, v129
	v_mov_b32_e32 v12, v129
	v_mov_b32_e32 v13, v129
	v_mov_b64_e32 v[30:31], v[14:15]
	v_mov_b64_e32 v[46:47], v[14:15]
	v_mov_b64_e32 v[62:63], v[14:15]
	s_add_i32 s86, s6, 0xffffff80
	s_sub_i32 s17, 0, s4
	s_and_b32 s33, s16, 0x7ffffffe
	s_add_i32 s6, s13, -1
	v_mov_b32_e32 v145, 1.0
	v_mov_b64_e32 v[28:29], v[12:13]
	v_mov_b64_e32 v[26:27], v[10:11]
	v_mov_b64_e32 v[24:25], v[8:9]
	v_mov_b64_e32 v[22:23], v[6:7]
	v_mov_b64_e32 v[20:21], v[4:5]
	v_mov_b64_e32 v[18:19], v[2:3]
	v_mov_b64_e32 v[16:17], v[0:1]
	v_mov_b64_e32 v[44:45], v[12:13]
	v_mov_b64_e32 v[42:43], v[10:11]
	v_mov_b64_e32 v[40:41], v[8:9]
	v_mov_b64_e32 v[38:39], v[6:7]
	v_mov_b64_e32 v[36:37], v[4:5]
	v_mov_b64_e32 v[34:35], v[2:3]
	v_mov_b64_e32 v[32:33], v[0:1]
	v_mov_b64_e32 v[60:61], v[12:13]
	v_mov_b64_e32 v[58:59], v[10:11]
	v_mov_b64_e32 v[56:57], v[8:9]
	v_mov_b64_e32 v[54:55], v[6:7]
	v_mov_b64_e32 v[52:53], v[4:5]
	v_mov_b64_e32 v[50:51], v[2:3]
	v_mov_b64_e32 v[48:49], v[0:1]
	s_branch .LBB0_708

; template <int MODE, bool SAMPLE>
; __device__ __forceinline__ void attn_unit(const Params& p, char* lds, int b, int h, int qb) {
;     ...
; #pragma unroll
;     ...
;         const int j = 2 * jj + par;
;         if (j > jfirst) continue;
;         const int buf = par;
;         WRITET(buf, stg2[NS == 2 ? par : 0]);
;         if (j >= NS) LOADT(j - NS, stg2[NS == 2 ? par : 0]);
.LBB0_708:
	s_cmp_ge_u32 s33, s16
	s_cbranch_scc1 .Lph_1
	s_cmp_eq_u32 s17, 0
	s_waitcnt vmcnt(7)
	ds_write_b128 v133, v[96:99] offset:16384
	s_waitcnt vmcnt(6)
	ds_write_b128 v198, v[100:103] offset:16384
	s_waitcnt vmcnt(5)
	ds_write_b128 v199, v[104:107] offset:49152
	s_waitcnt vmcnt(4)
	ds_write_b128 v200, v[108:111] offset:49152
	s_cbranch_scc1 .Lpd_1
	s_add_i32 s4, s86, 64
	s_lshl_b64 s[80:81], s[4:5], 8
	v_lshl_add_u64 v[64:65], v[164:165], 0, s[80:81]
	v_mov_b32_e32 v161, v129
	v_lshl_add_u64 v[66:67], v[64:65], 0, v[128:129]
	v_lshl_add_u64 v[68:69], v[64:65], 0, v[160:161]
	v_lshl_add_u64 v[64:65], v[64:65], 0, s[96:97]
	global_load_dwordx4 v[96:99], v[66:67], off
	global_load_dwordx4 v[100:103], v[68:69], off
	v_lshl_add_u64 v[66:67], v[64:65], 0, v[128:129]
	v_lshl_add_u64 v[64:65], v[64:65], 0, v[160:161]
	global_load_dwordx4 v[104:107], v[66:67], off
	global_load_dwordx4 v[108:111], v[64:65], off
	s_branch .LBB0_711

; template <int MODE, bool SAMPLE>
; __device__ __forceinline__ void attn_unit(const Params& p, char* lds, int b, int h, int qb) {
;     ...
; #pragma unroll
;     ...
;         const int j = 2 * jj + par;
;         if (j > jfirst) continue;
;         const int buf = par;
;         WRITET(buf, stg2[NS == 2 ? par : 0]);
;         if (j >= NS) LOADT(j - NS, stg2[NS == 2 ? par : 0]);
.LBB0_715:
	s_cmp_gt_u32 s33, s16
	s_cbranch_scc1 .LBB0_707
	s_cmp_eq_u32 s17, 0
	s_waitcnt vmcnt(7)
	ds_write_b128 v133, v[112:115]
	s_waitcnt vmcnt(6)
	ds_write_b128 v198, v[116:119]
	s_waitcnt vmcnt(5)
	ds_write_b128 v199, v[120:123] offset:32768
	s_waitcnt vmcnt(4)
	ds_write_b128 v200, v[124:127] offset:32768
	s_cbranch_scc1 .LBB0_718
	s_mov_b32 s87, s5
	s_lshl_b64 s[80:81], s[86:87], 8
	v_lshl_add_u64 v[64:65], v[164:165], 0, s[80:81]
	v_mov_b32_e32 v161, v129
	v_lshl_add_u64 v[66:67], v[64:65], 0, v[128:129]
	v_lshl_add_u64 v[68:69], v[64:65], 0, v[160:161]
	v_lshl_add_u64 v[64:65], v[64:65], 0, s[96:97]
	global_load_dwordx4 v[112:115], v[66:67], off
	global_load_dwordx4 v[116:119], v[68:69], off
	v_lshl_add_u64 v[66:67], v[64:65], 0, v[128:129]
	v_lshl_add_u64 v[64:65], v[64:65], 0, v[160:161]
	global_load_dwordx4 v[120:123], v[66:67], off
	global_load_dwordx4 v[124:127], v[64:65], off

; __device__ __forceinline__ unsigned cvtpk(float lo, float hi) { unsigned r; asm volatile("v_cvt_pk_bf16_f32 %0, %1, %2" : "=v"(r) : "v"(lo), "v"(hi)); return r; }
; __device__ __forceinline__ int crow(int r, int hi) { return (r & 3) + 8 * (r >> 2) + 4 * hi; }
; template <int MODE, bool SAMPLE>
; __device__ __forceinline__ void attn_unit(const Params& p, char* lds, int b, int h, int qb) {
;     ...
;     if (wact && var < 1) {
;         bf16_t* MIX = (bf16_t*)(p.ws + (var == 0 ? WS_MIX : WS_ACT));
;         const size_t rbase = SAMPLE ? (size_t)(MP + b * TS) : (size_t)(b * SEQ + qb * 256 + wid * 32);
;         constexpr int NIT = SAMPLE ? 4 : 8; const int er = lane >> 4, ec = (lane & 15) * 8;
;         float rli[16];
;         if (MODE == 0) { if (hi == 0) wsc[32 + r32] = l_reg; asm volatile("s_waitcnt lgkmcnt(0)" ::: "memory");
; #pragma unroll
;             for (int r = 0; r < 16; ++r) rli[r] = __builtin_amdgcn_rcpf(wsc[32 + crow(r, hi)]); }
; #pragma unroll
;         for (int r = 0; r < 16; ++r) { const int orow = crow(r, hi);
;             if (!SAMPLE || orow < TS) {
; #pragma unroll
;                 for (int d0 = 0; d0 < 4; ++d0) { float ov = o[d0][r]; if (MODE == 0) ov *= rli[r];
;                     const unsigned pk = cvtpk(ov, 0.f); *(bf16_t*)(Qs + orow * 256 + (d0 * 32 + r32) * 2) = (bf16_t)(pk & 0xffffu); } } }
;         asm volatile("s_waitcnt lgkmcnt(0)" ::: "memory");
;         bf16x8 gt[NIT];
; #pragma unroll
;         for (int it = 0; it < NIT; ++it) gt[it] = __builtin_nontemporal_load((const bf16x8*)(P1q + 24 * HB + (rbase + it * 4 + er) * 128 + ec));
; #pragma unroll
.LBB0_725:
	s_waitcnt vmcnt(0)
	v_add3_u32 v64, s10, v191, v192
	v_cvt_pk_bf16_f32 v48, v48, v129
	ds_write_b16 v64, v48
	v_cvt_pk_bf16_f32 v32, v32, v129
	ds_write_b16 v64, v32 offset:64
	v_cvt_pk_bf16_f32 v16, v16, v129
	ds_write_b16 v64, v16 offset:128
	v_cvt_pk_bf16_f32 v0, v0, v129
	s_nop 2
	ds_write_b16 v64, v0 offset:192
	v_cvt_pk_bf16_f32 v0, v49, v129
	ds_write_b16 v64, v0 offset:256
	v_cvt_pk_bf16_f32 v0, v33, v129
	ds_write_b16 v64, v0 offset:320
	v_cvt_pk_bf16_f32 v0, v17, v129
	ds_write_b16 v64, v0 offset:384
	v_cvt_pk_bf16_f32 v0, v1, v129
	ds_write_b16 v64, v0 offset:448
	v_cvt_pk_bf16_f32 v0, v50, v129
	ds_write_b16 v64, v0 offset:512
	v_cvt_pk_bf16_f32 v0, v34, v129
	ds_write_b16 v64, v0 offset:576
	v_cvt_pk_bf16_f32 v0, v18, v129
	ds_write_b16 v64, v0 offset:640
	v_cvt_pk_bf16_f32 v0, v2, v129
	ds_write_b16 v64, v0 offset:704
	v_cvt_pk_bf16_f32 v0, v51, v129
	ds_write_b16 v64, v0 offset:768
	v_cvt_pk_bf16_f32 v0, v35, v129
	ds_write_b16 v64, v0 offset:832
	v_cvt_pk_bf16_f32 v0, v19, v129
	ds_write_b16 v64, v0 offset:896
	v_cvt_pk_bf16_f32 v0, v3, v129
	ds_write_b16 v64, v0 offset:960
	v_cvt_pk_bf16_f32 v0, v52, v129
	ds_write_b16 v64, v0 offset:2048
	v_cvt_pk_bf16_f32 v0, v36, v129
	ds_write_b16 v64, v0 offset:2112
	v_cvt_pk_bf16_f32 v0, v20, v129
	ds_write_b16 v64, v0 offset:2176
	v_cvt_pk_bf16_f32 v0, v4, v129
	ds_write_b16 v64, v0 offset:2240
	v_cvt_pk_bf16_f32 v0, v53, v129
	ds_write_b16 v64, v0 offset:2304
	v_cvt_pk_bf16_f32 v0, v37, v129
	ds_write_b16 v64, v0 offset:2368
	v_cvt_pk_bf16_f32 v0, v21, v129
	ds_write_b16 v64, v0 offset:2432
	v_cvt_pk_bf16_f32 v0, v5, v129
	ds_write_b16 v64, v0 offset:2496
	v_cvt_pk_bf16_f32 v0, v54, v129
	ds_write_b16 v64, v0 offset:2560
	v_cvt_pk_bf16_f32 v0, v38, v129
	ds_write_b16 v64, v0 offset:2624
	v_cvt_pk_bf16_f32 v0, v22, v129
	ds_write_b16 v64, v0 offset:2688
	v_cvt_pk_bf16_f32 v0, v6, v129
	ds_write_b16 v64, v0 offset:2752
	v_cvt_pk_bf16_f32 v0, v55, v129
	ds_write_b16 v64, v0 offset:2816
	v_cvt_pk_bf16_f32 v0, v39, v129
	ds_write_b16 v64, v0 offset:2880
	v_cvt_pk_bf16_f32 v0, v23, v129
	ds_write_b16 v64, v0 offset:2944
	v_cvt_pk_bf16_f32 v0, v7, v129
	ds_write_b16 v64, v0 offset:3008
	v_cvt_pk_bf16_f32 v0, v56, v129
	ds_write_b16 v64, v0 offset:4096
	v_cvt_pk_bf16_f32 v0, v40, v129
	ds_write_b16 v64, v0 offset:4160
	v_cvt_pk_bf16_f32 v0, v24, v129
	ds_write_b16 v64, v0 offset:4224
	v_cvt_pk_bf16_f32 v0, v8, v129
	ds_write_b16 v64, v0 offset:4288
	v_cvt_pk_bf16_f32 v0, v57, v129
	ds_write_b16 v64, v0 offset:4352
	v_cvt_pk_bf16_f32 v0, v41, v129
	ds_write_b16 v64, v0 offset:4416
	v_cvt_pk_bf16_f32 v0, v25, v129
	ds_write_b16 v64, v0 offset:4480
	v_cvt_pk_bf16_f32 v0, v9, v129
	ds_write_b16 v64, v0 offset:4544
	v_cvt_pk_bf16_f32 v0, v58, v129
	ds_write_b16 v64, v0 offset:4608
	v_cvt_pk_bf16_f32 v0, v42, v129
	ds_write_b16 v64, v0 offset:4672
	v_cvt_pk_bf16_f32 v0, v26, v129
	ds_write_b16 v64, v0 offset:4736
	v_cvt_pk_bf16_f32 v0, v10, v129
	ds_write_b16 v64, v0 offset:4800
	v_cvt_pk_bf16_f32 v0, v59, v129
	ds_write_b16 v64, v0 offset:4864
	v_cvt_pk_bf16_f32 v0, v43, v129
	ds_write_b16 v64, v0 offset:4928
	v_cvt_pk_bf16_f32 v0, v27, v129
	ds_write_b16 v64, v0 offset:4992
	v_cvt_pk_bf16_f32 v0, v11, v129
	ds_write_b16 v64, v0 offset:5056
	v_cvt_pk_bf16_f32 v0, v60, v129
	ds_write_b16 v64, v0 offset:6144
	v_cvt_pk_bf16_f32 v0, v44, v129
	ds_write_b16 v64, v0 offset:6208
	v_cvt_pk_bf16_f32 v0, v28, v129
	ds_write_b16 v64, v0 offset:6272
	v_cvt_pk_bf16_f32 v0, v12, v129
	ds_write_b16 v64, v0 offset:6336
	v_cvt_pk_bf16_f32 v0, v61, v129
	ds_write_b16 v64, v0 offset:6400
	v_cvt_pk_bf16_f32 v0, v45, v129
	ds_write_b16 v64, v0 offset:6464
	v_cvt_pk_bf16_f32 v0, v29, v129
	ds_write_b16 v64, v0 offset:6528
	v_cvt_pk_bf16_f32 v0, v13, v129
	ds_write_b16 v64, v0 offset:6592
	v_cvt_pk_bf16_f32 v0, v62, v129
	ds_write_b16 v64, v0 offset:6656
	v_cvt_pk_bf16_f32 v0, v46, v129
	ds_write_b16 v64, v0 offset:6720
	v_cvt_pk_bf16_f32 v0, v30, v129
	ds_write_b16 v64, v0 offset:6784
	v_cvt_pk_bf16_f32 v0, v14, v129
	ds_write_b16 v64, v0 offset:6848
	v_cvt_pk_bf16_f32 v0, v63, v129
	ds_write_b16 v64, v0 offset:6912
	v_cvt_pk_bf16_f32 v0, v47, v129
	ds_write_b16 v64, v0 offset:6976
	v_cvt_pk_bf16_f32 v0, v31, v129
	ds_write_b16 v64, v0 offset:7040
	v_cvt_pk_bf16_f32 v0, v15, v129
	v_mov_b32_e32 v147, v129
	ds_write_b16 v64, v0 offset:7104
	v_or_b32_e32 v34, s9, v132
	v_lshl_add_u64 v[0:1], s[82:83], 0, v[146:147]
	s_mov_b64 s[0:1], 0x10200000
	v_mov_b32_e32 v35, v129
	v_lshl_add_u64 v[4:5], v[0:1], 0, s[0:1]
	v_lshlrev_b64 v[0:1], 8, v[34:35]
	s_waitcnt lgkmcnt(0)
	v_lshl_add_u64 v[0:1], v[4:5], 0, v[0:1]
	global_load_dwordx4 v[0:3], v[0:1], off nt
	v_or_b32_e32 v6, 4, v34
	v_mov_b32_e32 v7, v129
	v_lshlrev_b64 v[6:7], 8, v[6:7]
	v_lshl_add_u64 v[8:9], v[4:5], 0, v[6:7]
	v_or_b32_e32 v6, 8, v34
	v_mov_b32_e32 v7, v129
	v_lshlrev_b64 v[6:7], 8, v[6:7]
	v_lshl_add_u64 v[10:11], v[4:5], 0, v[6:7]
	v_or_b32_e32 v6, 12, v34
	v_mov_b32_e32 v7, v129
	v_lshlrev_b64 v[6:7], 8, v[6:7]
	global_load_dwordx4 v[22:25], v[8:9], off nt
	v_lshl_add_u64 v[12:13], v[4:5], 0, v[6:7]
	v_or_b32_e32 v6, 16, v34
	v_mov_b32_e32 v7, v129
	v_lshlrev_b64 v[6:7], 8, v[6:7]
	v_lshl_add_u64 v[14:15], v[4:5], 0, v[6:7]
	v_or_b32_e32 v6, 20, v34
	v_mov_b32_e32 v7, v129
	v_lshlrev_b64 v[6:7], 8, v[6:7]
	v_lshl_add_u64 v[30:31], v[4:5], 0, v[6:7]
	v_or_b32_e32 v6, 24, v34
	v_mov_b32_e32 v7, v129
	v_lshlrev_b64 v[6:7], 8, v[6:7]
	v_lshl_add_u64 v[32:33], v[4:5], 0, v[6:7]
	v_or_b32_e32 v6, 28, v34
	v_mov_b32_e32 v7, v129
	v_lshlrev_b64 v[6:7], 8, v[6:7]
	v_add_u32_e32 v20, s10, v134
	v_lshl_add_u64 v[36:37], v[4:5], 0, v[6:7]
	v_add_u32_e32 v4, v20, v193
	ds_read_b128 v[4:7], v4
	v_lshlrev_b64 v[34:35], 12, v[34:35]
	v_lshl_add_u64 v[34:35], s[92:93], 0, v[34:35]
	s_lshl_b32 s2, s8, 1
	v_lshl_add_u64 v[34:35], v[34:35], 0, s[2:3]
	s_waitcnt lgkmcnt(0)
; __device__ __forceinline__ float bf2f(short s) { return __uint_as_float(((unsigned)(unsigned short)s) << 16); }
; __device__ __forceinline__ float silu_fast(float g) { return g * __builtin_amdgcn_rcpf(1.f + __builtin_amdgcn_exp2f(-g * LOG2E)); }
; __device__ __forceinline__ bf16x8 tobf8(f32x8 x) { u32x4 w = {cvtpk(x[0], x[1]), cvtpk(x[2], x[3]), cvtpk(x[4], x[5]), cvtpk(x[6], x[7])}; return *reinterpret_cast<bf16x8*>(&w); }
; template <int MODE, bool SAMPLE>
; __device__ __forceinline__ void attn_unit(const Params& p, char* lds, int b, int h, int qb) {
;     ...
;         bf16x8 gt[NIT];
; #pragma unroll
;         for (int it = 0; it < NIT; ++it) gt[it] = __builtin_nontemporal_load((const bf16x8*)(P1q + 24 * HB + (rbase + it * 4 + er) * 128 + ec));
; #pragma unroll
;         for (int it = 0; it < NIT; ++it) { const int row = it * 4 + er; const bf16x8 mx = *(const bf16x8*)(Qs + row * 256 + ec * 2); f32x8 y;
; #pragma unroll
;             for (int i = 0; i < 8; ++i) y[i] = bf2f(mx[i]) * silu_fast(bf2f(gt[it][i]));
;             *(bf16x8*)(MIX + (rbase + row) * DM + MODE * 1024 + h * HD + ec) = tobf8(y); }
	v_lshlrev_b32_e32 v17, 16, v4
	v_and_b32_e32 v4, 0xffff0000, v4
	v_lshl_add_u64 v[34:35], v[34:35], 0, v[146:147]
	v_add_co_u32_e32 v34, vcc, s6, v34
	v_readlane_b32 s0, v253, 9
	s_nop 0
	v_addc_co_u32_e32 v35, vcc, 0, v35, vcc
	s_add_i32 s7, s7, s0
	s_cmpk_gt_i32 s7, 0xff
	v_readlane_b32 s1, v253, 10
	s_waitcnt vmcnt(1)
	v_lshlrev_b32_e32 v8, 16, v0
	v_and_b32_e32 v0, 0xffff0000, v0
	v_mul_f32_e32 v16, 0xbfb8aa3b, v0
	v_exp_f32_e32 v16, v16
	v_mul_f32_e32 v9, 0xbfb8aa3b, v8
	v_exp_f32_e32 v9, v9
	v_add_f32_e32 v16, 1.0, v16
	v_rcp_f32_e32 v16, v16
	v_add_f32_e32 v9, 1.0, v9
	v_rcp_f32_e32 v9, v9
	v_mul_f32_e32 v0, v16, v0
	v_mul_f32_e32 v38, v0, v4
	v_lshlrev_b32_e32 v0, 16, v1
	v_mul_f32_e32 v8, v9, v8
	v_mul_f32_e32 v4, 0xbfb8aa3b, v0
	v_and_b32_e32 v1, 0xffff0000, v1
	v_mul_f32_e32 v21, v8, v17
	v_exp_f32_e32 v4, v4
	v_mul_f32_e32 v8, 0xbfb8aa3b, v1
	v_exp_f32_e32 v8, v8
	v_lshlrev_b32_e32 v9, 16, v5
	v_add_f32_e32 v4, 1.0, v4
	v_rcp_f32_e32 v4, v4
	v_add_f32_e32 v8, 1.0, v8
	v_rcp_f32_e32 v8, v8
	v_mul_f32_e32 v0, v4, v0
	v_mul_f32_e32 v39, v0, v9
	v_and_b32_e32 v0, 0xffff0000, v5
	v_mul_f32_e32 v1, v8, v1
	v_mul_f32_e32 v40, v1, v0
	v_lshlrev_b32_e32 v0, 16, v2
	v_mul_f32_e32 v1, 0xbfb8aa3b, v0
	v_and_b32_e32 v2, 0xffff0000, v2
	v_exp_f32_e32 v1, v1
	v_mul_f32_e32 v4, 0xbfb8aa3b, v2
	v_exp_f32_e32 v4, v4
	v_lshlrev_b32_e32 v5, 16, v6
	v_add_f32_e32 v1, 1.0, v1
	v_rcp_f32_e32 v1, v1
	v_add_f32_e32 v4, 1.0, v4
	v_rcp_f32_e32 v4, v4
	v_mul_f32_e32 v0, v1, v0
	v_mul_f32_e32 v41, v0, v5
	v_and_b32_e32 v0, 0xffff0000, v6
	v_mul_f32_e32 v1, v4, v2
	v_mul_f32_e32 v42, v1, v0
	v_lshlrev_b32_e32 v0, 16, v3
	v_mul_f32_e32 v1, 0xbfb8aa3b, v0
	v_and_b32_e32 v2, 0xffff0000, v3
	v_exp_f32_e32 v1, v1
	v_mul_f32_e32 v3, 0xbfb8aa3b, v2
	v_exp_f32_e32 v3, v3
	v_lshlrev_b32_e32 v4, 16, v7
	v_add_f32_e32 v1, 1.0, v1
	v_rcp_f32_e32 v1, v1
	v_add_f32_e32 v3, 1.0, v3
	v_rcp_f32_e32 v3, v3
	v_mul_f32_e32 v0, v1, v0
	v_mul_f32_e32 v43, v0, v4
	v_and_b32_e32 v0, 0xffff0000, v7
	v_mul_f32_e32 v1, v3, v2
	v_mul_f32_e32 v44, v1, v0
	global_load_dwordx4 v[26:29], v[10:11], off nt
	global_load_dwordx4 v[16:19], v[12:13], off nt
	s_nop 0
	global_load_dwordx4 v[12:15], v[14:15], off nt
	s_nop 0
	global_load_dwordx4 v[8:11], v[30:31], off nt
	global_load_dwordx4 v[4:7], v[32:33], off nt
	global_load_dwordx4 v[0:3], v[36:37], off nt
	v_cvt_pk_bf16_f32 v30, v21, v38
	v_cvt_pk_bf16_f32 v31, v39, v40
	v_cvt_pk_bf16_f32 v32, v41, v42
	v_cvt_pk_bf16_f32 v33, v43, v44
	v_add_u32_e32 v21, v20, v194
	global_store_dwordx4 v[34:35], v[30:33], off offset:2048
	ds_read_b128 v[30:33], v21
	s_waitcnt vmcnt(7)
	v_lshlrev_b32_e32 v21, 16, v22
	v_and_b32_e32 v22, 0xffff0000, v22
	v_mul_f32_e32 v35, 0xbfb8aa3b, v22
	v_exp_f32_e32 v35, v35
	v_mul_f32_e32 v34, 0xbfb8aa3b, v21
	v_exp_f32_e32 v34, v34
	s_waitcnt lgkmcnt(0)
	v_lshlrev_b32_e32 v36, 16, v30
	v_add_f32_e32 v35, 1.0, v35
	v_rcp_f32_e32 v35, v35
	v_and_b32_e32 v30, 0xffff0000, v30
	v_add_f32_e32 v34, 1.0, v34
	v_rcp_f32_e32 v34, v34
	v_mul_f32_e32 v22, v35, v22
	v_mul_f32_e32 v22, v22, v30
	v_lshlrev_b32_e32 v30, 16, v23
	v_and_b32_e32 v23, 0xffff0000, v23
	v_mul_f32_e32 v35, 0xbfb8aa3b, v23
	v_exp_f32_e32 v35, v35
	v_mul_f32_e32 v21, v34, v21
	v_mul_f32_e32 v34, 0xbfb8aa3b, v30
	v_exp_f32_e32 v34, v34
	v_add_f32_e32 v35, 1.0, v35
	v_rcp_f32_e32 v35, v35
	v_mul_f32_e32 v21, v21, v36
	v_add_f32_e32 v34, 1.0, v34
	v_lshlrev_b32_e32 v36, 16, v31
	v_and_b32_e32 v31, 0xffff0000, v31
	v_mul_f32_e32 v23, v35, v23
	v_rcp_f32_e32 v34, v34
	v_mul_f32_e32 v23, v23, v31
	v_lshlrev_b32_e32 v31, 16, v24
	v_and_b32_e32 v24, 0xffff0000, v24
	v_mul_f32_e32 v35, 0xbfb8aa3b, v24
	v_exp_f32_e32 v35, v35
	v_mul_f32_e32 v30, v34, v30
	v_mul_f32_e32 v34, 0xbfb8aa3b, v31
	v_exp_f32_e32 v34, v34
	v_add_f32_e32 v35, 1.0, v35
	v_rcp_f32_e32 v35, v35
	v_mul_f32_e32 v30, v30, v36
	v_add_f32_e32 v34, 1.0, v34
	v_rcp_f32_e32 v34, v34
	v_lshlrev_b32_e32 v36, 16, v32
	v_and_b32_e32 v32, 0xffff0000, v32
	v_mul_f32_e32 v24, v35, v24
	v_mul_f32_e32 v24, v24, v32
	v_lshlrev_b32_e32 v32, 16, v25
	v_and_b32_e32 v25, 0xffff0000, v25
	v_mul_f32_e32 v35, 0xbfb8aa3b, v25
	v_mul_f32_e32 v31, v34, v31
	v_mul_f32_e32 v34, 0xbfb8aa3b, v32
	v_exp_f32_e32 v35, v35
	v_exp_f32_e32 v34, v34
	v_mul_f32_e32 v31, v31, v36
	v_cvt_pk_bf16_f32 v22, v21, v22
	v_add_f32_e32 v35, 1.0, v35
	v_add_f32_e32 v34, 1.0, v34
	v_rcp_f32_e32 v35, v35
	v_cvt_pk_bf16_f32 v23, v30, v23
	v_cvt_pk_bf16_f32 v24, v31, v24
	v_or_b32_e32 v30, s9, v138
	v_mov_b32_e32 v31, v129
	v_rcp_f32_e32 v34, v34
	v_lshlrev_b64 v[30:31], 12, v[30:31]
	v_lshl_add_u64 v[30:31], s[92:93], 0, v[30:31]
	v_lshl_add_u64 v[30:31], v[30:31], 0, s[2:3]
	v_lshlrev_b32_e32 v36, 16, v33
	v_and_b32_e32 v33, 0xffff0000, v33
	v_mul_f32_e32 v25, v35, v25
	v_lshl_add_u64 v[30:31], v[30:31], 0, v[146:147]
	v_mul_f32_e32 v32, v34, v32
	v_mul_f32_e32 v25, v25, v33
	v_add_co_u32_e32 v30, vcc, s6, v30
	v_mul_f32_e32 v32, v32, v36
	v_cvt_pk_bf16_f32 v25, v32, v25
	s_nop 0
	v_addc_co_u32_e32 v31, vcc, 0, v31, vcc
	v_add_u32_e32 v21, v20, v195
	global_store_dwordx4 v[30:31], v[22:25], off offset:2048
	ds_read_b128 v[22:25], v21
	s_waitcnt vmcnt(7)
	v_lshlrev_b32_e32 v21, 16, v26
	v_and_b32_e32 v26, 0xffff0000, v26
	v_mul_f32_e32 v31, 0xbfb8aa3b, v26
	v_exp_f32_e32 v31, v31
	v_mul_f32_e32 v30, 0xbfb8aa3b, v21
	v_exp_f32_e32 v30, v30
	s_waitcnt lgkmcnt(0)
; __device__ __forceinline__ float bf2f(short s) { return __uint_as_float(((unsigned)(unsigned short)s) << 16); }
; __device__ __forceinline__ float silu_fast(float g) { return g * __builtin_amdgcn_rcpf(1.f + __builtin_amdgcn_exp2f(-g * LOG2E)); }
; __device__ __forceinline__ bf16x8 tobf8(f32x8 x) { u32x4 w = {cvtpk(x[0], x[1]), cvtpk(x[2], x[3]), cvtpk(x[4], x[5]), cvtpk(x[6], x[7])}; return *reinterpret_cast<bf16x8*>(&w); }
; template <int MODE, bool SAMPLE>
; __device__ __forceinline__ void attn_unit(const Params& p, char* lds, int b, int h, int qb) {
;     ...
;         for (int it = 0; it < NIT; ++it) gt[it] = __builtin_nontemporal_load((const bf16x8*)(P1q + 24 * HB + (rbase + it * 4 + er) * 128 + ec));
; #pragma unroll
;         for (int it = 0; it < NIT; ++it) { const int row = it * 4 + er; const bf16x8 mx = *(const bf16x8*)(Qs + row * 256 + ec * 2); f32x8 y;
; #pragma unroll
;             for (int i = 0; i < 8; ++i) y[i] = bf2f(mx[i]) * silu_fast(bf2f(gt[it][i]));
;             *(bf16x8*)(MIX + (rbase + row) * DM + MODE * 1024 + h * HD + ec) = tobf8(y); }
	v_lshlrev_b32_e32 v32, 16, v22
	v_add_f32_e32 v31, 1.0, v31
	v_rcp_f32_e32 v31, v31
	v_and_b32_e32 v22, 0xffff0000, v22
	v_add_f32_e32 v30, 1.0, v30
	v_rcp_f32_e32 v30, v30
	v_mul_f32_e32 v26, v31, v26
	v_mul_f32_e32 v22, v26, v22
	v_lshlrev_b32_e32 v26, 16, v27
	v_and_b32_e32 v27, 0xffff0000, v27
	v_mul_f32_e32 v31, 0xbfb8aa3b, v27
	v_exp_f32_e32 v31, v31
	v_mul_f32_e32 v21, v30, v21
	v_mul_f32_e32 v30, 0xbfb8aa3b, v26
	v_exp_f32_e32 v30, v30
	v_add_f32_e32 v31, 1.0, v31
	v_rcp_f32_e32 v31, v31
	v_mul_f32_e32 v21, v21, v32
	v_add_f32_e32 v30, 1.0, v30
	v_lshlrev_b32_e32 v32, 16, v23
	v_and_b32_e32 v23, 0xffff0000, v23
	v_mul_f32_e32 v27, v31, v27
	v_rcp_f32_e32 v30, v30
	v_mul_f32_e32 v23, v27, v23
	v_lshlrev_b32_e32 v27, 16, v28
	v_and_b32_e32 v28, 0xffff0000, v28
	v_mul_f32_e32 v31, 0xbfb8aa3b, v28
	v_exp_f32_e32 v31, v31
	v_mul_f32_e32 v26, v30, v26
	v_mul_f32_e32 v30, 0xbfb8aa3b, v27
	v_exp_f32_e32 v30, v30
	v_add_f32_e32 v31, 1.0, v31
	v_rcp_f32_e32 v31, v31
	v_mul_f32_e32 v26, v26, v32
	v_add_f32_e32 v30, 1.0, v30
	v_rcp_f32_e32 v30, v30
	v_lshlrev_b32_e32 v32, 16, v24
	v_and_b32_e32 v24, 0xffff0000, v24
	v_mul_f32_e32 v28, v31, v28
	v_mul_f32_e32 v24, v28, v24
	v_lshlrev_b32_e32 v28, 16, v29
	v_and_b32_e32 v29, 0xffff0000, v29
	v_mul_f32_e32 v31, 0xbfb8aa3b, v29
	v_mul_f32_e32 v27, v30, v27
	v_mul_f32_e32 v30, 0xbfb8aa3b, v28
	v_exp_f32_e32 v31, v31
	v_exp_f32_e32 v30, v30
	v_mul_f32_e32 v27, v27, v32
	v_cvt_pk_bf16_f32 v22, v21, v22
	v_add_f32_e32 v31, 1.0, v31
	v_add_f32_e32 v30, 1.0, v30
	v_rcp_f32_e32 v31, v31
	v_cvt_pk_bf16_f32 v23, v26, v23
	v_cvt_pk_bf16_f32 v24, v27, v24
	v_or_b32_e32 v26, s9, v140
	v_mov_b32_e32 v27, v129
	v_rcp_f32_e32 v30, v30
	v_lshlrev_b64 v[26:27], 12, v[26:27]
	v_lshl_add_u64 v[26:27], s[92:93], 0, v[26:27]
	v_lshl_add_u64 v[26:27], v[26:27], 0, s[2:3]
	v_lshlrev_b32_e32 v32, 16, v25
	v_and_b32_e32 v25, 0xffff0000, v25
	v_mul_f32_e32 v29, v31, v29
	v_lshl_add_u64 v[26:27], v[26:27], 0, v[146:147]
	v_mul_f32_e32 v28, v30, v28
	v_mul_f32_e32 v25, v29, v25
	v_add_co_u32_e32 v26, vcc, s6, v26
	v_mul_f32_e32 v28, v28, v32
	v_cvt_pk_bf16_f32 v25, v28, v25
	s_nop 0
	v_addc_co_u32_e32 v27, vcc, 0, v27, vcc
	v_add_u32_e32 v21, v20, v196
	global_store_dwordx4 v[26:27], v[22:25], off offset:2048
	ds_read_b128 v[22:25], v21
	s_waitcnt vmcnt(7)
	v_lshlrev_b32_e32 v21, 16, v16
	v_and_b32_e32 v16, 0xffff0000, v16
	v_mul_f32_e32 v27, 0xbfb8aa3b, v16
	v_exp_f32_e32 v27, v27
	v_mul_f32_e32 v26, 0xbfb8aa3b, v21
	v_exp_f32_e32 v26, v26
	s_waitcnt lgkmcnt(0)
	v_lshlrev_b32_e32 v28, 16, v22
	v_add_f32_e32 v27, 1.0, v27
	v_rcp_f32_e32 v27, v27
	v_and_b32_e32 v22, 0xffff0000, v22
	v_add_f32_e32 v26, 1.0, v26
	v_rcp_f32_e32 v26, v26
	v_mul_f32_e32 v16, v27, v16
	v_mul_f32_e32 v16, v16, v22
	v_lshlrev_b32_e32 v22, 16, v17
	v_and_b32_e32 v17, 0xffff0000, v17
	v_mul_f32_e32 v27, 0xbfb8aa3b, v17
	v_exp_f32_e32 v27, v27
	v_mul_f32_e32 v21, v26, v21
	v_mul_f32_e32 v26, 0xbfb8aa3b, v22
	v_exp_f32_e32 v26, v26
	v_add_f32_e32 v27, 1.0, v27
	v_rcp_f32_e32 v27, v27
	v_mul_f32_e32 v21, v21, v28
	v_add_f32_e32 v26, 1.0, v26
	v_lshlrev_b32_e32 v28, 16, v23
	v_and_b32_e32 v23, 0xffff0000, v23
	v_mul_f32_e32 v17, v27, v17
	v_rcp_f32_e32 v26, v26
	v_mul_f32_e32 v17, v17, v23
	v_lshlrev_b32_e32 v23, 16, v18
	v_and_b32_e32 v18, 0xffff0000, v18
	v_mul_f32_e32 v27, 0xbfb8aa3b, v18
	v_exp_f32_e32 v27, v27
	v_mul_f32_e32 v22, v26, v22
	v_mul_f32_e32 v26, 0xbfb8aa3b, v23
	v_exp_f32_e32 v26, v26
	v_add_f32_e32 v27, 1.0, v27
	v_rcp_f32_e32 v27, v27
	v_mul_f32_e32 v22, v22, v28
	v_add_f32_e32 v26, 1.0, v26
	v_rcp_f32_e32 v26, v26
	v_lshlrev_b32_e32 v28, 16, v24
	v_and_b32_e32 v24, 0xffff0000, v24
	v_mul_f32_e32 v18, v27, v18
	v_mul_f32_e32 v18, v18, v24
	v_lshlrev_b32_e32 v24, 16, v19
	v_and_b32_e32 v19, 0xffff0000, v19
	v_mul_f32_e32 v27, 0xbfb8aa3b, v19
	v_mul_f32_e32 v23, v26, v23
	v_mul_f32_e32 v26, 0xbfb8aa3b, v24
	v_exp_f32_e32 v27, v27
	v_exp_f32_e32 v26, v26
	v_mul_f32_e32 v23, v23, v28
	v_cvt_pk_bf16_f32 v16, v21, v16
	v_add_f32_e32 v27, 1.0, v27
	v_cvt_pk_bf16_f32 v17, v22, v17
	v_cvt_pk_bf16_f32 v18, v23, v18
	v_or_b32_e32 v22, s9, v142
	v_mov_b32_e32 v23, v129
	v_add_f32_e32 v26, 1.0, v26
	v_rcp_f32_e32 v27, v27
	v_lshlrev_b64 v[22:23], 12, v[22:23]
	v_rcp_f32_e32 v26, v26
	v_lshl_add_u64 v[22:23], s[92:93], 0, v[22:23]
	v_lshl_add_u64 v[22:23], v[22:23], 0, s[2:3]
	v_lshl_add_u64 v[22:23], v[22:23], 0, v[146:147]
	v_lshlrev_b32_e32 v28, 16, v25
	v_and_b32_e32 v25, 0xffff0000, v25
	v_mul_f32_e32 v19, v27, v19
	v_add_co_u32_e32 v22, vcc, s6, v22
	v_mul_f32_e32 v24, v26, v24
	v_mul_f32_e32 v19, v19, v25
	v_addc_co_u32_e32 v23, vcc, 0, v23, vcc
	s_waitcnt vmcnt(6)
	v_lshlrev_b32_e32 v21, 16, v12
	v_and_b32_e32 v12, 0xffff0000, v12
	v_mul_f32_e32 v24, v24, v28
	v_cvt_pk_bf16_f32 v19, v24, v19
	global_store_dwordx4 v[22:23], v[16:19], off offset:2048
	v_mul_f32_e32 v23, 0xbfb8aa3b, v12
	v_exp_f32_e32 v23, v23
	v_add_u32_e32 v16, v20, v208
	ds_read_b128 v[16:19], v16
	v_mul_f32_e32 v22, 0xbfb8aa3b, v21
	v_add_f32_e32 v23, 1.0, v23
	v_rcp_f32_e32 v23, v23
	v_exp_f32_e32 v22, v22
	s_waitcnt lgkmcnt(0)
; __device__ __forceinline__ float bf2f(short s) { return __uint_as_float(((unsigned)(unsigned short)s) << 16); }
; __device__ __forceinline__ float silu_fast(float g) { return g * __builtin_amdgcn_rcpf(1.f + __builtin_amdgcn_exp2f(-g * LOG2E)); }
; __device__ __forceinline__ bf16x8 tobf8(f32x8 x) { u32x4 w = {cvtpk(x[0], x[1]), cvtpk(x[2], x[3]), cvtpk(x[4], x[5]), cvtpk(x[6], x[7])}; return *reinterpret_cast<bf16x8*>(&w); }
; template <int MODE, bool SAMPLE>
; __device__ __forceinline__ void attn_unit(const Params& p, char* lds, int b, int h, int qb) {
;     ...
;         for (int it = 0; it < NIT; ++it) gt[it] = __builtin_nontemporal_load((const bf16x8*)(P1q + 24 * HB + (rbase + it * 4 + er) * 128 + ec));
; #pragma unroll
;         for (int it = 0; it < NIT; ++it) { const int row = it * 4 + er; const bf16x8 mx = *(const bf16x8*)(Qs + row * 256 + ec * 2); f32x8 y;
; #pragma unroll
;             for (int i = 0; i < 8; ++i) y[i] = bf2f(mx[i]) * silu_fast(bf2f(gt[it][i]));
;             *(bf16x8*)(MIX + (rbase + row) * DM + MODE * 1024 + h * HD + ec) = tobf8(y); }
	v_lshlrev_b32_e32 v24, 16, v16
	v_and_b32_e32 v16, 0xffff0000, v16
	v_mul_f32_e32 v12, v23, v12
	v_mul_f32_e32 v12, v12, v16
	v_lshlrev_b32_e32 v16, 16, v13
	v_and_b32_e32 v13, 0xffff0000, v13
	v_add_f32_e32 v22, 1.0, v22
	v_mul_f32_e32 v23, 0xbfb8aa3b, v13
	v_rcp_f32_e32 v22, v22
	v_exp_f32_e32 v23, v23
	v_mul_f32_e32 v21, v22, v21
	v_mul_f32_e32 v22, 0xbfb8aa3b, v16
	v_add_f32_e32 v23, 1.0, v23
	v_exp_f32_e32 v22, v22
	v_rcp_f32_e32 v23, v23
	v_mul_f32_e32 v21, v21, v24
	v_lshlrev_b32_e32 v24, 16, v17
	v_add_f32_e32 v22, 1.0, v22
	v_and_b32_e32 v17, 0xffff0000, v17
	v_mul_f32_e32 v13, v23, v13
	v_rcp_f32_e32 v22, v22
	v_mul_f32_e32 v13, v13, v17
	v_lshlrev_b32_e32 v17, 16, v14
	v_and_b32_e32 v14, 0xffff0000, v14
	v_mul_f32_e32 v23, 0xbfb8aa3b, v14
	v_exp_f32_e32 v23, v23
	v_mul_f32_e32 v16, v22, v16
	v_mul_f32_e32 v22, 0xbfb8aa3b, v17
	v_exp_f32_e32 v22, v22
	v_add_f32_e32 v23, 1.0, v23
	v_rcp_f32_e32 v23, v23
	v_mul_f32_e32 v16, v16, v24
	v_add_f32_e32 v22, 1.0, v22
	v_rcp_f32_e32 v22, v22
	v_lshlrev_b32_e32 v24, 16, v18
	v_and_b32_e32 v18, 0xffff0000, v18
	v_mul_f32_e32 v14, v23, v14
	v_mul_f32_e32 v14, v14, v18
	v_lshlrev_b32_e32 v18, 16, v15
	v_and_b32_e32 v15, 0xffff0000, v15
	v_mul_f32_e32 v23, 0xbfb8aa3b, v15
	v_mul_f32_e32 v17, v22, v17
	v_mul_f32_e32 v22, 0xbfb8aa3b, v18
	v_exp_f32_e32 v23, v23
	v_exp_f32_e32 v22, v22
	v_mul_f32_e32 v17, v17, v24
	v_cvt_pk_bf16_f32 v12, v21, v12
	v_add_f32_e32 v23, 1.0, v23
	v_cvt_pk_bf16_f32 v13, v16, v13
	v_cvt_pk_bf16_f32 v14, v17, v14
	v_or_b32_e32 v16, s9, v150
	v_mov_b32_e32 v17, v129
	v_add_f32_e32 v22, 1.0, v22
	v_rcp_f32_e32 v23, v23
	v_lshlrev_b64 v[16:17], 12, v[16:17]
	v_rcp_f32_e32 v22, v22
	v_lshl_add_u64 v[16:17], s[92:93], 0, v[16:17]
	v_lshl_add_u64 v[16:17], v[16:17], 0, s[2:3]
	v_lshl_add_u64 v[16:17], v[16:17], 0, v[146:147]
	v_lshlrev_b32_e32 v24, 16, v19
	v_and_b32_e32 v19, 0xffff0000, v19
	v_mul_f32_e32 v15, v23, v15
	v_add_co_u32_e32 v16, vcc, s6, v16
	v_mul_f32_e32 v18, v22, v18
	v_mul_f32_e32 v15, v15, v19
	v_addc_co_u32_e32 v17, vcc, 0, v17, vcc
	v_mul_f32_e32 v18, v18, v24
	v_cvt_pk_bf16_f32 v15, v18, v15
	global_store_dwordx4 v[16:17], v[12:15], off offset:2048
	s_waitcnt vmcnt(7)
	v_lshlrev_b32_e32 v16, 16, v8
	v_and_b32_e32 v8, 0xffff0000, v8
	v_mul_f32_e32 v18, 0xbfb8aa3b, v8
	v_exp_f32_e32 v18, v18
	v_add_u32_e32 v12, v20, v209
	ds_read_b128 v[12:15], v12
	v_mul_f32_e32 v17, 0xbfb8aa3b, v16
	v_add_f32_e32 v18, 1.0, v18
	v_rcp_f32_e32 v18, v18
	v_exp_f32_e32 v17, v17
	s_waitcnt lgkmcnt(0)
	v_lshlrev_b32_e32 v19, 16, v12
	v_and_b32_e32 v12, 0xffff0000, v12
	v_mul_f32_e32 v8, v18, v8
	v_mul_f32_e32 v8, v8, v12
	v_lshlrev_b32_e32 v12, 16, v9
	v_and_b32_e32 v9, 0xffff0000, v9
	v_add_f32_e32 v17, 1.0, v17
	v_mul_f32_e32 v18, 0xbfb8aa3b, v9
	v_rcp_f32_e32 v17, v17
	v_exp_f32_e32 v18, v18
	v_mul_f32_e32 v16, v17, v16
	v_mul_f32_e32 v17, 0xbfb8aa3b, v12
	v_add_f32_e32 v18, 1.0, v18
	v_exp_f32_e32 v17, v17
	v_rcp_f32_e32 v18, v18
	v_mul_f32_e32 v16, v16, v19
	v_lshlrev_b32_e32 v19, 16, v13
	v_add_f32_e32 v17, 1.0, v17
	v_and_b32_e32 v13, 0xffff0000, v13
	v_mul_f32_e32 v9, v18, v9
	v_rcp_f32_e32 v17, v17
	v_mul_f32_e32 v9, v9, v13
	v_lshlrev_b32_e32 v13, 16, v10
	v_and_b32_e32 v10, 0xffff0000, v10
	v_mul_f32_e32 v18, 0xbfb8aa3b, v10
	v_exp_f32_e32 v18, v18
	v_mul_f32_e32 v12, v17, v12
	v_mul_f32_e32 v17, 0xbfb8aa3b, v13
	v_exp_f32_e32 v17, v17
	v_add_f32_e32 v18, 1.0, v18
	v_rcp_f32_e32 v18, v18
	v_mul_f32_e32 v12, v12, v19
	v_add_f32_e32 v17, 1.0, v17
	v_rcp_f32_e32 v17, v17
	v_lshlrev_b32_e32 v19, 16, v14
	v_and_b32_e32 v14, 0xffff0000, v14
	v_mul_f32_e32 v10, v18, v10
	v_mul_f32_e32 v10, v10, v14
	v_lshlrev_b32_e32 v14, 16, v11
	v_and_b32_e32 v11, 0xffff0000, v11
	v_mul_f32_e32 v18, 0xbfb8aa3b, v11
	v_mul_f32_e32 v13, v17, v13
	v_mul_f32_e32 v17, 0xbfb8aa3b, v14
	v_exp_f32_e32 v18, v18
	v_exp_f32_e32 v17, v17
	v_mul_f32_e32 v13, v13, v19
	v_cvt_pk_bf16_f32 v8, v16, v8
	v_add_f32_e32 v18, 1.0, v18
	v_cvt_pk_bf16_f32 v9, v12, v9
	v_cvt_pk_bf16_f32 v10, v13, v10
	v_or_b32_e32 v12, s9, v152
	v_mov_b32_e32 v13, v129
	v_add_f32_e32 v17, 1.0, v17
	v_rcp_f32_e32 v18, v18
	v_lshlrev_b64 v[12:13], 12, v[12:13]
	v_rcp_f32_e32 v17, v17
	v_lshl_add_u64 v[12:13], s[92:93], 0, v[12:13]
	v_lshl_add_u64 v[12:13], v[12:13], 0, s[2:3]
	v_lshl_add_u64 v[12:13], v[12:13], 0, v[146:147]
	v_lshlrev_b32_e32 v19, 16, v15
	v_and_b32_e32 v15, 0xffff0000, v15
	v_mul_f32_e32 v11, v18, v11
	v_add_co_u32_e32 v12, vcc, s6, v12
	v_mul_f32_e32 v14, v17, v14
	v_mul_f32_e32 v11, v11, v15
	v_addc_co_u32_e32 v13, vcc, 0, v13, vcc
	v_mul_f32_e32 v14, v14, v19
	v_cvt_pk_bf16_f32 v11, v14, v11
	global_store_dwordx4 v[12:13], v[8:11], off offset:2048
	s_waitcnt vmcnt(7)
; __device__ __forceinline__ float bf2f(short s) { return __uint_as_float(((unsigned)(unsigned short)s) << 16); }
; __device__ __forceinline__ float silu_fast(float g) { return g * __builtin_amdgcn_rcpf(1.f + __builtin_amdgcn_exp2f(-g * LOG2E)); }
; __device__ __forceinline__ bf16x8 tobf8(f32x8 x) { u32x4 w = {cvtpk(x[0], x[1]), cvtpk(x[2], x[3]), cvtpk(x[4], x[5]), cvtpk(x[6], x[7])}; return *reinterpret_cast<bf16x8*>(&w); }
; template <int MODE, bool SAMPLE>
; __device__ __forceinline__ void attn_unit(const Params& p, char* lds, int b, int h, int qb) {
;     ...
;         for (int it = 0; it < NIT; ++it) gt[it] = __builtin_nontemporal_load((const bf16x8*)(P1q + 24 * HB + (rbase + it * 4 + er) * 128 + ec));
; #pragma unroll
;         for (int it = 0; it < NIT; ++it) { const int row = it * 4 + er; const bf16x8 mx = *(const bf16x8*)(Qs + row * 256 + ec * 2); f32x8 y;
; #pragma unroll
;             for (int i = 0; i < 8; ++i) y[i] = bf2f(mx[i]) * silu_fast(bf2f(gt[it][i]));
;             *(bf16x8*)(MIX + (rbase + row) * DM + MODE * 1024 + h * HD + ec) = tobf8(y); }
;     }
;     __syncthreads();
	v_lshlrev_b32_e32 v12, 16, v4
	v_and_b32_e32 v4, 0xffff0000, v4
	v_mul_f32_e32 v14, 0xbfb8aa3b, v4
	v_exp_f32_e32 v14, v14
	v_add_u32_e32 v8, v20, v210
	ds_read_b128 v[8:11], v8
	v_mul_f32_e32 v13, 0xbfb8aa3b, v12
	v_add_f32_e32 v14, 1.0, v14
	v_rcp_f32_e32 v14, v14
	v_exp_f32_e32 v13, v13
	s_waitcnt lgkmcnt(0)
	v_lshlrev_b32_e32 v15, 16, v8
	v_and_b32_e32 v8, 0xffff0000, v8
	v_mul_f32_e32 v4, v14, v4
	v_mul_f32_e32 v4, v4, v8
	v_lshlrev_b32_e32 v8, 16, v5
	v_and_b32_e32 v5, 0xffff0000, v5
	v_add_f32_e32 v13, 1.0, v13
	v_mul_f32_e32 v14, 0xbfb8aa3b, v5
	v_rcp_f32_e32 v13, v13
	v_exp_f32_e32 v14, v14
	v_mul_f32_e32 v12, v13, v12
	v_mul_f32_e32 v13, 0xbfb8aa3b, v8
	v_add_f32_e32 v14, 1.0, v14
	v_exp_f32_e32 v13, v13
	v_rcp_f32_e32 v14, v14
	v_mul_f32_e32 v12, v12, v15
	v_lshlrev_b32_e32 v15, 16, v9
	v_add_f32_e32 v13, 1.0, v13
	v_and_b32_e32 v9, 0xffff0000, v9
	v_mul_f32_e32 v5, v14, v5
	v_rcp_f32_e32 v13, v13
	v_mul_f32_e32 v5, v5, v9
	v_lshlrev_b32_e32 v9, 16, v6
	v_and_b32_e32 v6, 0xffff0000, v6
	v_mul_f32_e32 v14, 0xbfb8aa3b, v6
	v_exp_f32_e32 v14, v14
	v_mul_f32_e32 v8, v13, v8
	v_mul_f32_e32 v13, 0xbfb8aa3b, v9
	v_exp_f32_e32 v13, v13
	v_add_f32_e32 v14, 1.0, v14
	v_rcp_f32_e32 v14, v14
	v_mul_f32_e32 v8, v8, v15
	v_add_f32_e32 v13, 1.0, v13
	v_rcp_f32_e32 v13, v13
	v_lshlrev_b32_e32 v15, 16, v10
	v_and_b32_e32 v10, 0xffff0000, v10
	v_mul_f32_e32 v6, v14, v6
	v_mul_f32_e32 v6, v6, v10
	v_lshlrev_b32_e32 v10, 16, v7
	v_and_b32_e32 v7, 0xffff0000, v7
	v_mul_f32_e32 v14, 0xbfb8aa3b, v7
	v_mul_f32_e32 v9, v13, v9
	v_mul_f32_e32 v13, 0xbfb8aa3b, v10
	v_exp_f32_e32 v14, v14
	v_exp_f32_e32 v13, v13
	v_mul_f32_e32 v9, v9, v15
	v_cvt_pk_bf16_f32 v4, v12, v4
	v_add_f32_e32 v14, 1.0, v14
	v_cvt_pk_bf16_f32 v5, v8, v5
	v_cvt_pk_bf16_f32 v6, v9, v6
	v_or_b32_e32 v8, s9, v154
	v_mov_b32_e32 v9, v129
	v_add_f32_e32 v13, 1.0, v13
	v_rcp_f32_e32 v14, v14
	v_lshlrev_b64 v[8:9], 12, v[8:9]
	v_rcp_f32_e32 v13, v13
	v_lshl_add_u64 v[8:9], s[92:93], 0, v[8:9]
	v_lshl_add_u64 v[8:9], v[8:9], 0, s[2:3]
	v_lshl_add_u64 v[8:9], v[8:9], 0, v[146:147]
	v_lshlrev_b32_e32 v15, 16, v11
	v_and_b32_e32 v11, 0xffff0000, v11
	v_mul_f32_e32 v7, v14, v7
	v_add_co_u32_e32 v8, vcc, s6, v8
	v_mul_f32_e32 v10, v13, v10
	v_mul_f32_e32 v7, v7, v11
	v_addc_co_u32_e32 v9, vcc, 0, v9, vcc
	v_mul_f32_e32 v10, v10, v15
	v_cvt_pk_bf16_f32 v7, v10, v7
	global_store_dwordx4 v[8:9], v[4:7], off offset:2048
	s_waitcnt vmcnt(7)
	v_lshlrev_b32_e32 v8, 16, v0
	v_and_b32_e32 v0, 0xffff0000, v0
	v_mul_f32_e32 v10, 0xbfb8aa3b, v0
	v_exp_f32_e32 v10, v10
	v_add_u32_e32 v4, v20, v211
	ds_read_b128 v[4:7], v4
	v_mul_f32_e32 v9, 0xbfb8aa3b, v8
	v_add_f32_e32 v10, 1.0, v10
	v_rcp_f32_e32 v10, v10
	v_exp_f32_e32 v9, v9
	s_waitcnt lgkmcnt(0)
	v_lshlrev_b32_e32 v11, 16, v4
	v_and_b32_e32 v4, 0xffff0000, v4
	v_mul_f32_e32 v0, v10, v0
	v_mul_f32_e32 v0, v0, v4
	v_lshlrev_b32_e32 v4, 16, v1
	v_and_b32_e32 v1, 0xffff0000, v1
	v_add_f32_e32 v9, 1.0, v9
	v_mul_f32_e32 v10, 0xbfb8aa3b, v1
	v_rcp_f32_e32 v9, v9
	v_exp_f32_e32 v10, v10
	v_mul_f32_e32 v8, v9, v8
	v_mul_f32_e32 v9, 0xbfb8aa3b, v4
	v_add_f32_e32 v10, 1.0, v10
	v_exp_f32_e32 v9, v9
	v_rcp_f32_e32 v10, v10
	v_mul_f32_e32 v8, v8, v11
	v_lshlrev_b32_e32 v11, 16, v5
	v_add_f32_e32 v9, 1.0, v9
	v_and_b32_e32 v5, 0xffff0000, v5
	v_mul_f32_e32 v1, v10, v1
	v_rcp_f32_e32 v9, v9
	v_mul_f32_e32 v1, v1, v5
	v_lshlrev_b32_e32 v5, 16, v2
	v_and_b32_e32 v2, 0xffff0000, v2
	v_mul_f32_e32 v10, 0xbfb8aa3b, v2
	v_exp_f32_e32 v10, v10
	v_mul_f32_e32 v4, v9, v4
	v_mul_f32_e32 v9, 0xbfb8aa3b, v5
	v_exp_f32_e32 v9, v9
	v_add_f32_e32 v10, 1.0, v10
	v_rcp_f32_e32 v10, v10
	v_mul_f32_e32 v4, v4, v11
	v_add_f32_e32 v9, 1.0, v9
	v_rcp_f32_e32 v9, v9
	v_lshlrev_b32_e32 v11, 16, v6
	v_and_b32_e32 v6, 0xffff0000, v6
	v_mul_f32_e32 v2, v10, v2
	v_mul_f32_e32 v2, v2, v6
	v_lshlrev_b32_e32 v6, 16, v3
	v_and_b32_e32 v3, 0xffff0000, v3
	v_mul_f32_e32 v10, 0xbfb8aa3b, v3
	v_mul_f32_e32 v5, v9, v5
	v_mul_f32_e32 v9, 0xbfb8aa3b, v6
	v_exp_f32_e32 v10, v10
	v_exp_f32_e32 v9, v9
	v_mul_f32_e32 v5, v5, v11
	v_cvt_pk_bf16_f32 v0, v8, v0
	v_add_f32_e32 v10, 1.0, v10
	v_cvt_pk_bf16_f32 v1, v4, v1
	v_cvt_pk_bf16_f32 v2, v5, v2
	v_or_b32_e32 v4, s9, v156
	v_mov_b32_e32 v5, v129
	v_add_f32_e32 v9, 1.0, v9
	v_rcp_f32_e32 v10, v10
	v_lshlrev_b64 v[4:5], 12, v[4:5]
	v_rcp_f32_e32 v9, v9
	v_lshl_add_u64 v[4:5], s[92:93], 0, v[4:5]
	v_lshl_add_u64 v[4:5], v[4:5], 0, s[2:3]
	v_lshl_add_u64 v[4:5], v[4:5], 0, v[146:147]
	v_lshlrev_b32_e32 v11, 16, v7
	v_and_b32_e32 v7, 0xffff0000, v7
	v_mul_f32_e32 v3, v10, v3
	v_add_co_u32_e32 v4, vcc, 0x11300000, v4
	v_mul_f32_e32 v6, v9, v6
	v_mul_f32_e32 v3, v3, v7
	v_addc_co_u32_e32 v5, vcc, 0, v5, vcc
	v_mul_f32_e32 v6, v6, v11
	v_cvt_pk_bf16_f32 v3, v6, v3
	global_store_dwordx4 v[4:5], v[0:3], off offset:2048
	s_barrier
	s_cbranch_scc1 .LBB0_796

; template <int MODE, bool SAMPLE>
; __device__ __forceinline__ void attn_unit(const Params& p, char* lds, int b, int h, int qb) {
;     ...
;         if (j > jfirst) continue;
;         const int buf = par;
;         WRITET(buf, stg2[NS == 2 ? par : 0]);
;         if (j >= NS) LOADT(j - NS, stg2[NS == 2 ? par : 0]);
.LBB0_757:
	s_cmp_lt_i32 s18, s25
	s_cbranch_scc0 .Lph_2
	v_add_u32_e32 v64, v204, v202
	s_waitcnt vmcnt(7)
	ds_write_b128 v64, v[96:99] offset:16384
	v_add_u32_e32 v64, v205, v202
	s_waitcnt vmcnt(6)
	ds_write_b128 v64, v[100:103] offset:16384
	v_add_u32_e32 v64, v206, v203
	s_waitcnt vmcnt(5)
	ds_write_b128 v64, v[104:107] offset:49152
	v_add_u32_e32 v64, v207, v203
	s_cmp_eq_u32 s15, 0
	s_waitcnt vmcnt(4)
	ds_write_b128 v64, v[108:111] offset:49152
	s_cbranch_scc1 .Lpd_2
	s_add_i32 s2, s14, s26
	s_sub_i32 s2, s2, 64
	s_lshl_b64 s[16:17], s[2:3], 8
	v_lshl_add_u64 v[64:65], v[160:161], 0, s[16:17]
	v_mov_b32_e32 v159, v129
	v_lshl_add_u64 v[66:67], v[64:65], 0, v[128:129]
	v_lshl_add_u64 v[68:69], v[64:65], 0, v[158:159]
	v_lshl_add_u64 v[64:65], v[64:65], 0, s[86:87]
	global_load_dwordx4 v[96:99], v[66:67], off
	global_load_dwordx4 v[100:103], v[68:69], off
	v_lshl_add_u64 v[66:67], v[64:65], 0, v[128:129]
	v_lshl_add_u64 v[64:65], v[64:65], 0, v[158:159]
	global_load_dwordx4 v[104:107], v[66:67], off
	global_load_dwordx4 v[108:111], v[64:65], off
	s_branch .LBB0_760

; template <int MODE, bool SAMPLE>
; __device__ __forceinline__ void attn_unit(const Params& p, char* lds, int b, int h, int qb) {
;     ...
;         if (j > jfirst) continue;
;         const int buf = par;
;         WRITET(buf, stg2[NS == 2 ? par : 0]);
;         if (j >= NS) LOADT(j - NS, stg2[NS == 2 ? par : 0]);
.LBB0_768:
	s_cmp_gt_i32 s18, s25
	s_cbranch_scc1 .LBB0_756
	v_add_u32_e32 v64, v204, v202
	s_waitcnt vmcnt(7)
	ds_write_b128 v64, v[112:115]
	v_add_u32_e32 v64, v205, v202
	s_waitcnt vmcnt(6)
	ds_write_b128 v64, v[116:119]
	v_add_u32_e32 v64, v206, v203
	s_waitcnt vmcnt(5)
	ds_write_b128 v64, v[120:123] offset:32768
	v_add_u32_e32 v64, v207, v203
	s_cmp_eq_u32 s15, 0
	s_waitcnt vmcnt(4)
	ds_write_b128 v64, v[124:127] offset:32768
	s_cbranch_scc1 .LBB0_771
	s_add_i32 s2, s14, s26
	s_addk_i32 s2, 0xff80
	s_lshl_b64 s[16:17], s[2:3], 8
	v_lshl_add_u64 v[64:65], v[160:161], 0, s[16:17]
	v_mov_b32_e32 v159, v129
	v_lshl_add_u64 v[66:67], v[64:65], 0, v[128:129]
	v_lshl_add_u64 v[68:69], v[64:65], 0, v[158:159]
	v_lshl_add_u64 v[64:65], v[64:65], 0, s[86:87]
	global_load_dwordx4 v[112:115], v[66:67], off
	global_load_dwordx4 v[116:119], v[68:69], off
	v_lshl_add_u64 v[66:67], v[64:65], 0, v[128:129]
	v_lshl_add_u64 v[64:65], v[64:65], 0, v[158:159]
	global_load_dwordx4 v[120:123], v[66:67], off
	global_load_dwordx4 v[124:127], v[64:65], off

; __device__ __forceinline__ unsigned cvtpk(float lo, float hi) { unsigned r; asm volatile("v_cvt_pk_bf16_f32 %0, %1, %2" : "=v"(r) : "v"(lo), "v"(hi)); return r; }
; __device__ __forceinline__ int crow(int r, int hi) { return (r & 3) + 8 * (r >> 2) + 4 * hi; }
; template <int MODE, bool SAMPLE>
; __device__ __forceinline__ void attn_unit(const Params& p, char* lds, int b, int h, int qb) {
;     ...
;     if (wact && var < 1) {
;         bf16_t* MIX = (bf16_t*)(p.ws + (var == 0 ? WS_MIX : WS_ACT));
;         const size_t rbase = SAMPLE ? (size_t)(MP + b * TS) : (size_t)(b * SEQ + qb * 256 + wid * 32);
;         constexpr int NIT = SAMPLE ? 4 : 8; const int er = lane >> 4, ec = (lane & 15) * 8;
;         float rli[16];
;         if (MODE == 0) { if (hi == 0) wsc[32 + r32] = l_reg; asm volatile("s_waitcnt lgkmcnt(0)" ::: "memory");
; #pragma unroll
;             for (int r = 0; r < 16; ++r) rli[r] = __builtin_amdgcn_rcpf(wsc[32 + crow(r, hi)]); }
; #pragma unroll
;         for (int r = 0; r < 16; ++r) { const int orow = crow(r, hi);
;             if (!SAMPLE || orow < TS) {
; #pragma unroll
;                 for (int d0 = 0; d0 < 4; ++d0) { float ov = o[d0][r]; if (MODE == 0) ov *= rli[r];
;                     const unsigned pk = cvtpk(ov, 0.f); *(bf16_t*)(Qs + orow * 256 + (d0 * 32 + r32) * 2) = (bf16_t)(pk & 0xffffu); } } }
.LBB0_778:
	s_waitcnt vmcnt(0)
	s_and_saveexec_b64 s[16:17], s[12:13]
	ds_write_b32 v149, v214 offset:128
	s_or_b64 exec, exec, s[16:17]
	s_waitcnt lgkmcnt(0)
	v_add_u32_e32 v72, s10, v137
	ds_read_b128 v[64:67], v72 offset:128
	ds_read_b128 v[68:71], v72 offset:160
	s_ashr_i32 s2, s8, 31
	v_mov_b32_e32 v147, v129
	v_mov_b32_e32 v149, v129
	s_waitcnt lgkmcnt(1)
	v_rcp_f32_e32 v73, v64
	v_rcp_f32_e32 v74, v65
	v_rcp_f32_e32 v75, v66
	v_rcp_f32_e32 v76, v67
	v_mul_f32_e32 v16, v16, v73
	s_waitcnt lgkmcnt(0)
	v_rcp_f32_e32 v77, v68
	ds_read_b128 v[64:67], v72 offset:192
	v_rcp_f32_e32 v78, v69
	v_rcp_f32_e32 v79, v70
	v_rcp_f32_e32 v80, v71
	ds_read_b128 v[68:71], v72 offset:224
	v_add3_u32 v72, s24, v191, v192
	v_cvt_pk_bf16_f32 v16, v16, v129
	ds_write_b16 v72, v16
	v_mul_f32_e32 v16, v48, v73
	v_cvt_pk_bf16_f32 v16, v16, v129
	ds_write_b16 v72, v16 offset:64
	v_mul_f32_e32 v16, v32, v73
	v_mul_f32_e32 v0, v0, v73
	v_cvt_pk_bf16_f32 v16, v16, v129
	ds_write_b16 v72, v16 offset:128
	v_cvt_pk_bf16_f32 v0, v0, v129
	ds_write_b16 v72, v0 offset:192
	v_mul_f32_e32 v0, v17, v74
	v_cvt_pk_bf16_f32 v0, v0, v129
	ds_write_b16 v72, v0 offset:256
	v_mul_f32_e32 v0, v49, v74
	v_cvt_pk_bf16_f32 v0, v0, v129
	ds_write_b16 v72, v0 offset:320
	v_mul_f32_e32 v0, v33, v74
	v_cvt_pk_bf16_f32 v0, v0, v129
	ds_write_b16 v72, v0 offset:384
	v_mul_f32_e32 v0, v1, v74
	v_cvt_pk_bf16_f32 v0, v0, v129
	ds_write_b16 v72, v0 offset:448
	v_mul_f32_e32 v0, v18, v75
	v_cvt_pk_bf16_f32 v0, v0, v129
	ds_write_b16 v72, v0 offset:512
	v_mul_f32_e32 v0, v50, v75
	v_cvt_pk_bf16_f32 v0, v0, v129
	ds_write_b16 v72, v0 offset:576
	v_mul_f32_e32 v0, v34, v75
	v_cvt_pk_bf16_f32 v0, v0, v129
	ds_write_b16 v72, v0 offset:640
	v_mul_f32_e32 v0, v2, v75
	v_cvt_pk_bf16_f32 v0, v0, v129
	ds_write_b16 v72, v0 offset:704
	v_mul_f32_e32 v0, v19, v76
	v_cvt_pk_bf16_f32 v0, v0, v129
	ds_write_b16 v72, v0 offset:768
	v_mul_f32_e32 v0, v51, v76
	v_cvt_pk_bf16_f32 v0, v0, v129
	ds_write_b16 v72, v0 offset:832
	v_mul_f32_e32 v0, v35, v76
	v_cvt_pk_bf16_f32 v0, v0, v129
	ds_write_b16 v72, v0 offset:896
	v_mul_f32_e32 v0, v3, v76
	v_cvt_pk_bf16_f32 v0, v0, v129
	ds_write_b16 v72, v0 offset:960
	v_mul_f32_e32 v0, v20, v77
	v_cvt_pk_bf16_f32 v0, v0, v129
	ds_write_b16 v72, v0 offset:2048
	v_mul_f32_e32 v0, v52, v77
	v_cvt_pk_bf16_f32 v0, v0, v129
	ds_write_b16 v72, v0 offset:2112
	v_mul_f32_e32 v0, v36, v77
	v_cvt_pk_bf16_f32 v0, v0, v129
	ds_write_b16 v72, v0 offset:2176
	v_mul_f32_e32 v0, v4, v77
	v_cvt_pk_bf16_f32 v0, v0, v129
	ds_write_b16 v72, v0 offset:2240
	v_mul_f32_e32 v0, v21, v78
	v_cvt_pk_bf16_f32 v0, v0, v129
	ds_write_b16 v72, v0 offset:2304
	v_mul_f32_e32 v0, v53, v78
	v_cvt_pk_bf16_f32 v0, v0, v129
	ds_write_b16 v72, v0 offset:2368
	v_mul_f32_e32 v0, v37, v78
	v_cvt_pk_bf16_f32 v0, v0, v129
	ds_write_b16 v72, v0 offset:2432
	v_mul_f32_e32 v0, v5, v78
	v_cvt_pk_bf16_f32 v0, v0, v129
	ds_write_b16 v72, v0 offset:2496
	v_mul_f32_e32 v0, v22, v79
	v_cvt_pk_bf16_f32 v0, v0, v129
	ds_write_b16 v72, v0 offset:2560
	v_mul_f32_e32 v0, v54, v79
	v_cvt_pk_bf16_f32 v0, v0, v129
	ds_write_b16 v72, v0 offset:2624
	v_mul_f32_e32 v0, v38, v79
	v_cvt_pk_bf16_f32 v0, v0, v129
	ds_write_b16 v72, v0 offset:2688
	v_mul_f32_e32 v0, v6, v79
	v_cvt_pk_bf16_f32 v0, v0, v129
	ds_write_b16 v72, v0 offset:2752
	v_mul_f32_e32 v0, v23, v80
	v_cvt_pk_bf16_f32 v0, v0, v129
	ds_write_b16 v72, v0 offset:2816
	v_mul_f32_e32 v0, v55, v80
	v_cvt_pk_bf16_f32 v0, v0, v129
	s_waitcnt lgkmcnt(14)
	v_rcp_f32_e32 v64, v64
	ds_write_b16 v72, v0 offset:2880
	v_mul_f32_e32 v0, v39, v80
	v_cvt_pk_bf16_f32 v0, v0, v129
	ds_write_b16 v72, v0 offset:2944
	v_mul_f32_e32 v0, v7, v80
	v_cvt_pk_bf16_f32 v0, v0, v129
	ds_write_b16 v72, v0 offset:3008
	v_mul_f32_e32 v0, v24, v64
	v_cvt_pk_bf16_f32 v0, v0, v129
	ds_write_b16 v72, v0 offset:4096
	v_mul_f32_e32 v0, v56, v64
	v_cvt_pk_bf16_f32 v0, v0, v129
	v_rcp_f32_e32 v65, v65
	ds_write_b16 v72, v0 offset:4160
	v_mul_f32_e32 v0, v40, v64
	v_cvt_pk_bf16_f32 v0, v0, v129
	ds_write_b16 v72, v0 offset:4224
	v_mul_f32_e32 v0, v8, v64
	v_cvt_pk_bf16_f32 v0, v0, v129
	ds_write_b16 v72, v0 offset:4288
	v_mul_f32_e32 v0, v25, v65
	v_cvt_pk_bf16_f32 v0, v0, v129
	ds_write_b16 v72, v0 offset:4352
	v_mul_f32_e32 v0, v57, v65
	v_cvt_pk_bf16_f32 v0, v0, v129
	v_rcp_f32_e32 v66, v66
	ds_write_b16 v72, v0 offset:4416
	v_mul_f32_e32 v0, v41, v65
	v_cvt_pk_bf16_f32 v0, v0, v129
	ds_write_b16 v72, v0 offset:4480
	v_mul_f32_e32 v0, v9, v65
	v_cvt_pk_bf16_f32 v0, v0, v129
	ds_write_b16 v72, v0 offset:4544
	v_mul_f32_e32 v0, v26, v66
	v_cvt_pk_bf16_f32 v0, v0, v129
	ds_write_b16 v72, v0 offset:4608
	v_mul_f32_e32 v0, v58, v66
	v_cvt_pk_bf16_f32 v0, v0, v129
	v_rcp_f32_e32 v67, v67
	ds_write_b16 v72, v0 offset:4672
	v_mul_f32_e32 v0, v42, v66
	v_cvt_pk_bf16_f32 v0, v0, v129
	ds_write_b16 v72, v0 offset:4736
	v_mul_f32_e32 v0, v10, v66
	v_cvt_pk_bf16_f32 v0, v0, v129
	ds_write_b16 v72, v0 offset:4800
	v_mul_f32_e32 v0, v27, v67
	v_cvt_pk_bf16_f32 v0, v0, v129
	ds_write_b16 v72, v0 offset:4864
	v_mul_f32_e32 v0, v59, v67
	v_cvt_pk_bf16_f32 v0, v0, v129
	v_rcp_f32_e32 v68, v68
	ds_write_b16 v72, v0 offset:4928
	v_mul_f32_e32 v0, v43, v67
	v_cvt_pk_bf16_f32 v0, v0, v129
	ds_write_b16 v72, v0 offset:4992
	v_mul_f32_e32 v0, v11, v67
	v_cvt_pk_bf16_f32 v0, v0, v129
	ds_write_b16 v72, v0 offset:5056
	v_mul_f32_e32 v0, v28, v68
	v_cvt_pk_bf16_f32 v0, v0, v129
	ds_write_b16 v72, v0 offset:6144
	v_mul_f32_e32 v0, v60, v68
	v_cvt_pk_bf16_f32 v0, v0, v129
	v_rcp_f32_e32 v69, v69
	ds_write_b16 v72, v0 offset:6208
	v_mul_f32_e32 v0, v44, v68
	v_cvt_pk_bf16_f32 v0, v0, v129
	ds_write_b16 v72, v0 offset:6272
	v_mul_f32_e32 v0, v12, v68
; __device__ __forceinline__ unsigned cvtpk(float lo, float hi) { unsigned r; asm volatile("v_cvt_pk_bf16_f32 %0, %1, %2" : "=v"(r) : "v"(lo), "v"(hi)); return r; }
; __device__ __forceinline__ float bf2f(short s) { return __uint_as_float(((unsigned)(unsigned short)s) << 16); }
; __device__ __forceinline__ float silu_fast(float g) { return g * __builtin_amdgcn_rcpf(1.f + __builtin_amdgcn_exp2f(-g * LOG2E)); }
; __device__ __forceinline__ int crow(int r, int hi) { return (r & 3) + 8 * (r >> 2) + 4 * hi; }
; __device__ __forceinline__ bf16x8 tobf8(f32x8 x) { u32x4 w = {cvtpk(x[0], x[1]), cvtpk(x[2], x[3]), cvtpk(x[4], x[5]), cvtpk(x[6], x[7])}; return *reinterpret_cast<bf16x8*>(&w); }
; template <int MODE, bool SAMPLE>
; __device__ __forceinline__ void attn_unit(const Params& p, char* lds, int b, int h, int qb) {
;     ...
;         for (int r = 0; r < 16; ++r) { const int orow = crow(r, hi);
;             if (!SAMPLE || orow < TS) {
; #pragma unroll
;                 for (int d0 = 0; d0 < 4; ++d0) { float ov = o[d0][r]; if (MODE == 0) ov *= rli[r];
;                     const unsigned pk = cvtpk(ov, 0.f); *(bf16_t*)(Qs + orow * 256 + (d0 * 32 + r32) * 2) = (bf16_t)(pk & 0xffffu); } } }
;         asm volatile("s_waitcnt lgkmcnt(0)" ::: "memory");
;         bf16x8 gt[NIT];
; #pragma unroll
;         for (int it = 0; it < NIT; ++it) gt[it] = __builtin_nontemporal_load((const bf16x8*)(P1q + 24 * HB + (rbase + it * 4 + er) * 128 + ec));
; #pragma unroll
;         for (int it = 0; it < NIT; ++it) { const int row = it * 4 + er; const bf16x8 mx = *(const bf16x8*)(Qs + row * 256 + ec * 2); f32x8 y;
; #pragma unroll
;             for (int i = 0; i < 8; ++i) y[i] = bf2f(mx[i]) * silu_fast(bf2f(gt[it][i]));
;             *(bf16x8*)(MIX + (rbase + row) * DM + MODE * 1024 + h * HD + ec) = tobf8(y); }
	v_cvt_pk_bf16_f32 v0, v0, v129
	ds_write_b16 v72, v0 offset:6336
	v_mul_f32_e32 v0, v29, v69
	v_cvt_pk_bf16_f32 v0, v0, v129
	ds_write_b16 v72, v0 offset:6400
	v_mul_f32_e32 v0, v61, v69
	v_cvt_pk_bf16_f32 v0, v0, v129
	v_rcp_f32_e32 v70, v70
	ds_write_b16 v72, v0 offset:6464
	v_mul_f32_e32 v0, v45, v69
	v_cvt_pk_bf16_f32 v0, v0, v129
	ds_write_b16 v72, v0 offset:6528
	v_mul_f32_e32 v0, v13, v69
	v_cvt_pk_bf16_f32 v0, v0, v129
	ds_write_b16 v72, v0 offset:6592
	v_mul_f32_e32 v0, v30, v70
	v_cvt_pk_bf16_f32 v0, v0, v129
	ds_write_b16 v72, v0 offset:6656
	v_mul_f32_e32 v0, v62, v70
	v_cvt_pk_bf16_f32 v0, v0, v129
	v_rcp_f32_e32 v71, v71
	ds_write_b16 v72, v0 offset:6720
	v_mul_f32_e32 v0, v46, v70
	v_cvt_pk_bf16_f32 v0, v0, v129
	ds_write_b16 v72, v0 offset:6784
	v_mul_f32_e32 v0, v14, v70
	v_cvt_pk_bf16_f32 v0, v0, v129
	ds_write_b16 v72, v0 offset:6848
	v_mul_f32_e32 v0, v31, v71
	v_cvt_pk_bf16_f32 v0, v0, v129
	ds_write_b16 v72, v0 offset:6912
	v_mul_f32_e32 v0, v63, v71
	v_cvt_pk_bf16_f32 v0, v0, v129
	ds_write_b16 v72, v0 offset:6976
	v_mul_f32_e32 v0, v47, v71
	v_cvt_pk_bf16_f32 v0, v0, v129
	ds_write_b16 v72, v0 offset:7040
	v_mul_f32_e32 v0, v15, v71
	v_cvt_pk_bf16_f32 v0, v0, v129
	ds_write_b16 v72, v0 offset:7104
	v_lshl_add_u64 v[0:1], s[0:1], 0, v[146:147]
	s_mov_b64 s[0:1], 0x3300000
	v_mov_b32_e32 v51, s2
	v_or_b32_e32 v50, s8, v132
	v_lshl_add_u64 v[4:5], v[0:1], 0, s[0:1]
	v_lshlrev_b64 v[0:1], 8, v[50:51]
	s_waitcnt lgkmcnt(0)
	v_lshl_add_u64 v[0:1], v[4:5], 0, v[0:1]
	global_load_dwordx4 v[0:3], v[0:1], off nt
	v_mov_b32_e32 v35, s2
	v_or_b32_e32 v34, s8, v138
	v_lshlrev_b64 v[6:7], 8, v[34:35]
	v_lshl_add_u64 v[8:9], v[4:5], 0, v[6:7]
	global_load_dwordx4 v[38:41], v[8:9], off nt
	v_mov_b32_e32 v33, s2
	v_or_b32_e32 v32, s8, v140
	v_lshlrev_b64 v[6:7], 8, v[32:33]
	v_mov_b32_e32 v31, s2
	v_or_b32_e32 v30, s8, v142
	v_lshl_add_u64 v[10:11], v[4:5], 0, v[6:7]
	v_lshlrev_b64 v[6:7], 8, v[30:31]
	v_mov_b32_e32 v29, s2
	v_or_b32_e32 v28, s8, v150
	v_lshl_add_u64 v[12:13], v[4:5], 0, v[6:7]
	v_lshlrev_b64 v[6:7], 8, v[28:29]
	v_mov_b32_e32 v27, s2
	v_or_b32_e32 v26, s8, v152
	v_lshl_add_u64 v[14:15], v[4:5], 0, v[6:7]
	v_lshlrev_b64 v[6:7], 8, v[26:27]
	v_mov_b32_e32 v25, s2
	v_or_b32_e32 v24, s8, v154
	v_lshl_add_u64 v[46:47], v[4:5], 0, v[6:7]
	v_lshlrev_b64 v[6:7], 8, v[24:25]
	v_mov_b32_e32 v21, s2
	v_or_b32_e32 v20, s8, v156
	v_lshl_add_u64 v[48:49], v[4:5], 0, v[6:7]
	v_lshlrev_b64 v[6:7], 8, v[20:21]
	v_add_u32_e32 v36, s24, v134
	v_lshl_add_u64 v[52:53], v[4:5], 0, v[6:7]
	v_add_u32_e32 v4, v36, v193
	ds_read_b128 v[4:7], v4
	s_lshl_b32 s2, s9, 8
	v_lshl_add_u64 v[22:23], v[144:145], 0, s[2:3]
	v_lshlrev_b64 v[50:51], 12, v[50:51]
	v_lshl_add_u64 v[50:51], v[22:23], 0, v[50:51]
	s_waitcnt lgkmcnt(0)
	v_lshlrev_b32_e32 v17, 16, v4
	v_and_b32_e32 v4, 0xffff0000, v4
	v_lshlrev_b64 v[34:35], 12, v[34:35]
	v_lshl_add_u64 v[34:35], v[22:23], 0, v[34:35]
	v_lshlrev_b64 v[32:33], 12, v[32:33]
	v_lshl_add_u64 v[32:33], v[22:23], 0, v[32:33]
	v_lshlrev_b64 v[30:31], 12, v[30:31]
	v_lshl_add_u64 v[30:31], v[22:23], 0, v[30:31]
	v_readfirstlane_b32 s0, v183
	s_lshl_b32 s8, s9, 7
	s_sub_i32 s2, 7, s22
	s_lshr_b32 s10, s0, 6
	s_add_u32 s82, s92, s23
	s_addc_u32 s83, s93, 0
	s_lshl_b32 s15, s2, 8
	s_lshl_b32 s0, s10, 5
	s_add_i32 s18, s0, s15
	s_add_i32 s9, s18, s20
	s_mov_b32 s0, 0xcf00000
	s_lshr_b32 s11, s18, 6
	v_mov_b32_e32 v159, v129
	s_waitcnt vmcnt(1)
	v_lshlrev_b32_e32 v8, 16, v0
	v_and_b32_e32 v0, 0xffff0000, v0
	v_mul_f32_e32 v16, 0xbfb8aa3b, v0
	v_exp_f32_e32 v16, v16
	v_mul_f32_e32 v9, 0xbfb8aa3b, v8
	v_exp_f32_e32 v9, v9
	v_add_f32_e32 v16, 1.0, v16
	v_rcp_f32_e32 v16, v16
	v_add_f32_e32 v9, 1.0, v9
	v_rcp_f32_e32 v9, v9
	v_mul_f32_e32 v0, v16, v0
	v_mul_f32_e32 v54, v0, v4
	v_lshlrev_b32_e32 v0, 16, v1
	v_mul_f32_e32 v8, v9, v8
	v_mul_f32_e32 v4, 0xbfb8aa3b, v0
	v_and_b32_e32 v1, 0xffff0000, v1
	v_mul_f32_e32 v37, v8, v17
	v_exp_f32_e32 v4, v4
	v_mul_f32_e32 v8, 0xbfb8aa3b, v1
	v_exp_f32_e32 v8, v8
	v_lshlrev_b32_e32 v9, 16, v5
	v_add_f32_e32 v4, 1.0, v4
	v_rcp_f32_e32 v4, v4
	v_add_f32_e32 v8, 1.0, v8
	v_rcp_f32_e32 v8, v8
	v_mul_f32_e32 v0, v4, v0
	v_mul_f32_e32 v55, v0, v9
	v_and_b32_e32 v0, 0xffff0000, v5
	v_mul_f32_e32 v1, v8, v1
	v_mul_f32_e32 v56, v1, v0
	v_lshlrev_b32_e32 v0, 16, v2
	v_mul_f32_e32 v1, 0xbfb8aa3b, v0
	v_and_b32_e32 v2, 0xffff0000, v2
	v_exp_f32_e32 v1, v1
	v_mul_f32_e32 v4, 0xbfb8aa3b, v2
	v_exp_f32_e32 v4, v4
	v_lshlrev_b32_e32 v5, 16, v6
	v_add_f32_e32 v1, 1.0, v1
	v_rcp_f32_e32 v1, v1
	v_add_f32_e32 v4, 1.0, v4
	v_rcp_f32_e32 v4, v4
	v_mul_f32_e32 v0, v1, v0
	v_mul_f32_e32 v57, v0, v5
	v_and_b32_e32 v0, 0xffff0000, v6
	v_mul_f32_e32 v1, v4, v2
	v_mul_f32_e32 v58, v1, v0
	v_lshlrev_b32_e32 v0, 16, v3
	v_mul_f32_e32 v1, 0xbfb8aa3b, v0
	v_and_b32_e32 v2, 0xffff0000, v3
	v_exp_f32_e32 v1, v1
	v_mul_f32_e32 v3, 0xbfb8aa3b, v2
	v_exp_f32_e32 v3, v3
	v_lshlrev_b32_e32 v4, 16, v7
	v_add_f32_e32 v1, 1.0, v1
	v_rcp_f32_e32 v1, v1
	v_add_f32_e32 v3, 1.0, v3
	v_rcp_f32_e32 v3, v3
	v_mul_f32_e32 v0, v1, v0
	v_mul_f32_e32 v59, v0, v4
	v_and_b32_e32 v0, 0xffff0000, v7
	v_mul_f32_e32 v1, v3, v2
	v_mul_f32_e32 v60, v1, v0
	global_load_dwordx4 v[42:45], v[10:11], off nt
	global_load_dwordx4 v[16:19], v[12:13], off nt
	s_nop 0
	global_load_dwordx4 v[12:15], v[14:15], off nt
	s_nop 0
	global_load_dwordx4 v[8:11], v[46:47], off nt
	global_load_dwordx4 v[4:7], v[48:49], off nt
	global_load_dwordx4 v[0:3], v[52:53], off nt
	v_cvt_pk_bf16_f32 v46, v37, v54
	v_cvt_pk_bf16_f32 v47, v55, v56
	v_cvt_pk_bf16_f32 v48, v57, v58
	v_cvt_pk_bf16_f32 v49, v59, v60
	v_add_u32_e32 v37, v36, v194
	global_store_dwordx4 v[50:51], v[46:49], off
	ds_read_b128 v[46:49], v37
	s_waitcnt vmcnt(7)
; __device__ __forceinline__ float bf2f(short s) { return __uint_as_float(((unsigned)(unsigned short)s) << 16); }
; __device__ __forceinline__ float silu_fast(float g) { return g * __builtin_amdgcn_rcpf(1.f + __builtin_amdgcn_exp2f(-g * LOG2E)); }
; __device__ __forceinline__ bf16x8 tobf8(f32x8 x) { u32x4 w = {cvtpk(x[0], x[1]), cvtpk(x[2], x[3]), cvtpk(x[4], x[5]), cvtpk(x[6], x[7])}; return *reinterpret_cast<bf16x8*>(&w); }
; template <int MODE, bool SAMPLE>
; __device__ __forceinline__ void attn_unit(const Params& p, char* lds, int b, int h, int qb) {
;     ...
;         for (int it = 0; it < NIT; ++it) { const int row = it * 4 + er; const bf16x8 mx = *(const bf16x8*)(Qs + row * 256 + ec * 2); f32x8 y;
; #pragma unroll
;             for (int i = 0; i < 8; ++i) y[i] = bf2f(mx[i]) * silu_fast(bf2f(gt[it][i]));
;             *(bf16x8*)(MIX + (rbase + row) * DM + MODE * 1024 + h * HD + ec) = tobf8(y); }
	v_lshlrev_b32_e32 v37, 16, v38
	v_and_b32_e32 v38, 0xffff0000, v38
	v_mul_f32_e32 v51, 0xbfb8aa3b, v38
	v_exp_f32_e32 v51, v51
	v_mul_f32_e32 v50, 0xbfb8aa3b, v37
	v_exp_f32_e32 v50, v50
	s_waitcnt lgkmcnt(0)
	v_lshlrev_b32_e32 v52, 16, v46
	v_add_f32_e32 v51, 1.0, v51
	v_rcp_f32_e32 v51, v51
	v_and_b32_e32 v46, 0xffff0000, v46
	v_add_f32_e32 v50, 1.0, v50
	v_rcp_f32_e32 v50, v50
	v_mul_f32_e32 v38, v51, v38
	v_mul_f32_e32 v38, v38, v46
	v_lshlrev_b32_e32 v46, 16, v39
	v_and_b32_e32 v39, 0xffff0000, v39
	v_mul_f32_e32 v51, 0xbfb8aa3b, v39
	v_exp_f32_e32 v51, v51
	v_mul_f32_e32 v37, v50, v37
	v_mul_f32_e32 v50, 0xbfb8aa3b, v46
	v_exp_f32_e32 v50, v50
	v_add_f32_e32 v51, 1.0, v51
	v_rcp_f32_e32 v51, v51
	v_mul_f32_e32 v37, v37, v52
	v_add_f32_e32 v50, 1.0, v50
	v_lshlrev_b32_e32 v52, 16, v47
	v_and_b32_e32 v47, 0xffff0000, v47
	v_mul_f32_e32 v39, v51, v39
	v_rcp_f32_e32 v50, v50
	v_mul_f32_e32 v39, v39, v47
	v_lshlrev_b32_e32 v47, 16, v40
	v_and_b32_e32 v40, 0xffff0000, v40
	v_mul_f32_e32 v51, 0xbfb8aa3b, v40
	v_exp_f32_e32 v51, v51
	v_mul_f32_e32 v46, v50, v46
	v_mul_f32_e32 v50, 0xbfb8aa3b, v47
	v_exp_f32_e32 v50, v50
	v_add_f32_e32 v51, 1.0, v51
	v_rcp_f32_e32 v51, v51
	v_mul_f32_e32 v46, v46, v52
	v_add_f32_e32 v50, 1.0, v50
	v_rcp_f32_e32 v50, v50
	v_lshlrev_b32_e32 v52, 16, v48
	v_and_b32_e32 v48, 0xffff0000, v48
	v_mul_f32_e32 v40, v51, v40
	v_mul_f32_e32 v40, v40, v48
	v_lshlrev_b32_e32 v48, 16, v41
	v_and_b32_e32 v41, 0xffff0000, v41
	v_mul_f32_e32 v51, 0xbfb8aa3b, v41
	v_mul_f32_e32 v47, v50, v47
	v_mul_f32_e32 v50, 0xbfb8aa3b, v48
	v_exp_f32_e32 v51, v51
	v_exp_f32_e32 v50, v50
	v_mul_f32_e32 v47, v47, v52
	v_lshlrev_b32_e32 v52, 16, v49
	v_add_f32_e32 v51, 1.0, v51
	v_add_f32_e32 v50, 1.0, v50
	v_rcp_f32_e32 v51, v51
	v_rcp_f32_e32 v50, v50
	v_and_b32_e32 v49, 0xffff0000, v49
	v_cvt_pk_bf16_f32 v38, v37, v38
	v_mul_f32_e32 v41, v51, v41
	v_mul_f32_e32 v48, v50, v48
	v_mul_f32_e32 v41, v41, v49
	v_mul_f32_e32 v48, v48, v52
	v_cvt_pk_bf16_f32 v39, v46, v39
	v_cvt_pk_bf16_f32 v40, v47, v40
	v_cvt_pk_bf16_f32 v41, v48, v41
	global_store_dwordx4 v[34:35], v[38:41], off
	v_add_u32_e32 v34, v36, v195
	ds_read_b128 v[38:41], v34
	s_waitcnt vmcnt(7)
	v_lshlrev_b32_e32 v34, 16, v42
	v_and_b32_e32 v37, 0xffff0000, v42
	v_mul_f32_e32 v35, 0xbfb8aa3b, v34
	v_mul_f32_e32 v42, 0xbfb8aa3b, v37
	v_exp_f32_e32 v35, v35
	v_exp_f32_e32 v42, v42
	s_waitcnt lgkmcnt(0)
	v_lshlrev_b32_e32 v46, 16, v38
	v_add_f32_e32 v35, 1.0, v35
	v_add_f32_e32 v42, 1.0, v42
	v_rcp_f32_e32 v35, v35
	v_rcp_f32_e32 v42, v42
	v_mul_f32_e32 v34, v35, v34
	v_and_b32_e32 v35, 0xffff0000, v38
	v_mul_f32_e32 v37, v42, v37
	v_mul_f32_e32 v35, v37, v35
	v_lshlrev_b32_e32 v37, 16, v43
	v_and_b32_e32 v42, 0xffff0000, v43
	v_mul_f32_e32 v38, 0xbfb8aa3b, v37
	v_mul_f32_e32 v43, 0xbfb8aa3b, v42
	v_exp_f32_e32 v38, v38
	v_exp_f32_e32 v43, v43
	v_mul_f32_e32 v34, v34, v46
	v_lshlrev_b32_e32 v46, 16, v39
	v_add_f32_e32 v38, 1.0, v38
	v_add_f32_e32 v43, 1.0, v43
	v_rcp_f32_e32 v38, v38
	v_rcp_f32_e32 v43, v43
	v_mul_f32_e32 v37, v38, v37
	v_and_b32_e32 v38, 0xffff0000, v39
	v_mul_f32_e32 v39, v43, v42
	v_mul_f32_e32 v39, v39, v38
	v_lshlrev_b32_e32 v38, 16, v44
	v_mul_f32_e32 v42, 0xbfb8aa3b, v38
	v_and_b32_e32 v43, 0xffff0000, v44
	v_exp_f32_e32 v42, v42
	v_mul_f32_e32 v44, 0xbfb8aa3b, v43
	v_exp_f32_e32 v44, v44
	v_mul_f32_e32 v37, v37, v46
	v_add_f32_e32 v42, 1.0, v42
	v_rcp_f32_e32 v42, v42
	v_add_f32_e32 v44, 1.0, v44
	v_rcp_f32_e32 v44, v44
	v_lshlrev_b32_e32 v46, 16, v40
	v_mul_f32_e32 v38, v42, v38
	v_mul_f32_e32 v42, v38, v46
	v_and_b32_e32 v38, 0xffff0000, v40
	v_mul_f32_e32 v40, v44, v43
	v_mul_f32_e32 v40, v40, v38
	v_lshlrev_b32_e32 v38, 16, v45
	v_mul_f32_e32 v43, 0xbfb8aa3b, v38
	v_and_b32_e32 v44, 0xffff0000, v45
	v_exp_f32_e32 v43, v43
	v_mul_f32_e32 v45, 0xbfb8aa3b, v44
	v_exp_f32_e32 v45, v45
	v_lshlrev_b32_e32 v46, 16, v41
	v_add_f32_e32 v43, 1.0, v43
	v_rcp_f32_e32 v43, v43
	v_add_f32_e32 v45, 1.0, v45
	v_rcp_f32_e32 v45, v45
	v_mul_f32_e32 v38, v43, v38
	v_mul_f32_e32 v43, v38, v46
	v_and_b32_e32 v38, 0xffff0000, v41
	v_mul_f32_e32 v41, v45, v44
	v_mul_f32_e32 v41, v41, v38
	v_cvt_pk_bf16_f32 v38, v34, v35
	v_cvt_pk_bf16_f32 v39, v37, v39
	s_waitcnt vmcnt(6)
	v_lshlrev_b32_e32 v37, 16, v16
	v_and_b32_e32 v16, 0xffff0000, v16
	v_cvt_pk_bf16_f32 v40, v42, v40
	v_cvt_pk_bf16_f32 v41, v43, v41
	global_store_dwordx4 v[32:33], v[38:41], off
	v_add_u32_e32 v32, v36, v196
	ds_read_b128 v[32:35], v32
	v_mul_f32_e32 v39, 0xbfb8aa3b, v16
	v_exp_f32_e32 v39, v39
	v_mul_f32_e32 v38, 0xbfb8aa3b, v37
	v_exp_f32_e32 v38, v38
	s_waitcnt lgkmcnt(0)
	v_lshlrev_b32_e32 v40, 16, v32
	v_add_f32_e32 v39, 1.0, v39
	v_rcp_f32_e32 v39, v39
	v_and_b32_e32 v32, 0xffff0000, v32
	v_add_f32_e32 v38, 1.0, v38
	v_rcp_f32_e32 v38, v38
	v_mul_f32_e32 v16, v39, v16
	v_mul_f32_e32 v16, v16, v32
	v_lshlrev_b32_e32 v32, 16, v17
	v_and_b32_e32 v17, 0xffff0000, v17
	v_mul_f32_e32 v39, 0xbfb8aa3b, v17
	v_exp_f32_e32 v39, v39
	v_mul_f32_e32 v37, v38, v37
	v_mul_f32_e32 v38, 0xbfb8aa3b, v32
	v_exp_f32_e32 v38, v38
	v_add_f32_e32 v39, 1.0, v39
	v_rcp_f32_e32 v39, v39
	v_mul_f32_e32 v37, v37, v40
	v_add_f32_e32 v38, 1.0, v38
	v_lshlrev_b32_e32 v40, 16, v33
	v_and_b32_e32 v33, 0xffff0000, v33
	v_mul_f32_e32 v17, v39, v17
	v_rcp_f32_e32 v38, v38
	v_mul_f32_e32 v17, v17, v33
	v_lshlrev_b32_e32 v33, 16, v18
	v_and_b32_e32 v18, 0xffff0000, v18
	v_mul_f32_e32 v39, 0xbfb8aa3b, v18
	v_exp_f32_e32 v39, v39
	v_mul_f32_e32 v32, v38, v32
	v_mul_f32_e32 v38, 0xbfb8aa3b, v33
	v_exp_f32_e32 v38, v38
	v_add_f32_e32 v39, 1.0, v39
	v_rcp_f32_e32 v39, v39
	v_mul_f32_e32 v32, v32, v40
	v_add_f32_e32 v38, 1.0, v38
	v_rcp_f32_e32 v38, v38
	v_lshlrev_b32_e32 v40, 16, v34
	v_and_b32_e32 v34, 0xffff0000, v34
	v_mul_f32_e32 v18, v39, v18
	v_mul_f32_e32 v18, v18, v34
	v_lshlrev_b32_e32 v34, 16, v19
	v_and_b32_e32 v19, 0xffff0000, v19
	v_mul_f32_e32 v39, 0xbfb8aa3b, v19
	v_mul_f32_e32 v33, v38, v33
	v_mul_f32_e32 v38, 0xbfb8aa3b, v34
	v_exp_f32_e32 v39, v39
	v_exp_f32_e32 v38, v38
	v_mul_f32_e32 v33, v33, v40
	v_lshlrev_b32_e32 v40, 16, v35
	v_add_f32_e32 v39, 1.0, v39
	v_add_f32_e32 v38, 1.0, v38
	v_rcp_f32_e32 v39, v39
	v_rcp_f32_e32 v38, v38
	v_and_b32_e32 v35, 0xffff0000, v35
	v_cvt_pk_bf16_f32 v16, v37, v16
	v_mul_f32_e32 v19, v39, v19
	v_mul_f32_e32 v34, v38, v34
	v_mul_f32_e32 v19, v19, v35
	v_mul_f32_e32 v34, v34, v40
	v_cvt_pk_bf16_f32 v17, v32, v17
	v_cvt_pk_bf16_f32 v18, v33, v18
	v_cvt_pk_bf16_f32 v19, v34, v19
	global_store_dwordx4 v[30:31], v[16:19], off
	s_waitcnt vmcnt(7)
; __device__ __forceinline__ float bf2f(short s) { return __uint_as_float(((unsigned)(unsigned short)s) << 16); }
; __device__ __forceinline__ float silu_fast(float g) { return g * __builtin_amdgcn_rcpf(1.f + __builtin_amdgcn_exp2f(-g * LOG2E)); }
; __device__ __forceinline__ bf16x8 tobf8(f32x8 x) { u32x4 w = {cvtpk(x[0], x[1]), cvtpk(x[2], x[3]), cvtpk(x[4], x[5]), cvtpk(x[6], x[7])}; return *reinterpret_cast<bf16x8*>(&w); }
; template <int MODE, bool SAMPLE>
; __device__ __forceinline__ void attn_unit(const Params& p, char* lds, int b, int h, int qb) {
;     ...
;         for (int it = 0; it < NIT; ++it) { const int row = it * 4 + er; const bf16x8 mx = *(const bf16x8*)(Qs + row * 256 + ec * 2); f32x8 y;
; #pragma unroll
;             for (int i = 0; i < 8; ++i) y[i] = bf2f(mx[i]) * silu_fast(bf2f(gt[it][i]));
;             *(bf16x8*)(MIX + (rbase + row) * DM + MODE * 1024 + h * HD + ec) = tobf8(y); }
	v_lshlrev_b32_e32 v30, 16, v12
	v_and_b32_e32 v12, 0xffff0000, v12
	v_mul_f32_e32 v32, 0xbfb8aa3b, v12
	v_exp_f32_e32 v32, v32
	v_add_u32_e32 v16, v36, v208
	ds_read_b128 v[16:19], v16
	v_mul_f32_e32 v31, 0xbfb8aa3b, v30
	v_add_f32_e32 v32, 1.0, v32
	v_rcp_f32_e32 v32, v32
	v_exp_f32_e32 v31, v31
	s_waitcnt lgkmcnt(0)
	v_lshlrev_b32_e32 v33, 16, v16
	v_and_b32_e32 v16, 0xffff0000, v16
	v_mul_f32_e32 v12, v32, v12
	v_mul_f32_e32 v12, v12, v16
	v_lshlrev_b32_e32 v16, 16, v13
	v_and_b32_e32 v13, 0xffff0000, v13
	v_add_f32_e32 v31, 1.0, v31
	v_mul_f32_e32 v32, 0xbfb8aa3b, v13
	v_rcp_f32_e32 v31, v31
	v_exp_f32_e32 v32, v32
	v_mul_f32_e32 v30, v31, v30
	v_mul_f32_e32 v31, 0xbfb8aa3b, v16
	v_add_f32_e32 v32, 1.0, v32
	v_exp_f32_e32 v31, v31
	v_rcp_f32_e32 v32, v32
	v_mul_f32_e32 v30, v30, v33
	v_lshlrev_b32_e32 v33, 16, v17
	v_add_f32_e32 v31, 1.0, v31
	v_and_b32_e32 v17, 0xffff0000, v17
	v_mul_f32_e32 v13, v32, v13
	v_rcp_f32_e32 v31, v31
	v_mul_f32_e32 v13, v13, v17
	v_lshlrev_b32_e32 v17, 16, v14
	v_and_b32_e32 v14, 0xffff0000, v14
	v_mul_f32_e32 v32, 0xbfb8aa3b, v14
	v_exp_f32_e32 v32, v32
	v_mul_f32_e32 v16, v31, v16
	v_mul_f32_e32 v31, 0xbfb8aa3b, v17
	v_exp_f32_e32 v31, v31
	v_add_f32_e32 v32, 1.0, v32
	v_rcp_f32_e32 v32, v32
	v_mul_f32_e32 v16, v16, v33
	v_add_f32_e32 v31, 1.0, v31
	v_rcp_f32_e32 v31, v31
	v_lshlrev_b32_e32 v33, 16, v18
	v_and_b32_e32 v18, 0xffff0000, v18
	v_mul_f32_e32 v14, v32, v14
	v_mul_f32_e32 v14, v14, v18
	v_lshlrev_b32_e32 v18, 16, v15
	v_and_b32_e32 v15, 0xffff0000, v15
	v_mul_f32_e32 v32, 0xbfb8aa3b, v15
	v_mul_f32_e32 v17, v31, v17
	v_mul_f32_e32 v31, 0xbfb8aa3b, v18
	v_exp_f32_e32 v32, v32
	v_exp_f32_e32 v31, v31
	v_mul_f32_e32 v17, v17, v33
	v_lshlrev_b32_e32 v33, 16, v19
	v_add_f32_e32 v32, 1.0, v32
	v_add_f32_e32 v31, 1.0, v31
	v_rcp_f32_e32 v32, v32
	v_rcp_f32_e32 v31, v31
	v_and_b32_e32 v19, 0xffff0000, v19
	v_cvt_pk_bf16_f32 v12, v30, v12
	v_mul_f32_e32 v15, v32, v15
	v_cvt_pk_bf16_f32 v13, v16, v13
	v_cvt_pk_bf16_f32 v14, v17, v14
	v_lshlrev_b64 v[16:17], 12, v[28:29]
	v_mul_f32_e32 v18, v31, v18
	v_mul_f32_e32 v15, v15, v19
	v_lshl_add_u64 v[16:17], v[22:23], 0, v[16:17]
	v_mul_f32_e32 v18, v18, v33
	v_cvt_pk_bf16_f32 v15, v18, v15
	global_store_dwordx4 v[16:17], v[12:15], off
	s_waitcnt vmcnt(7)
	v_lshlrev_b32_e32 v16, 16, v8
	v_and_b32_e32 v8, 0xffff0000, v8
	v_mul_f32_e32 v18, 0xbfb8aa3b, v8
	v_exp_f32_e32 v18, v18
	v_add_u32_e32 v12, v36, v209
	ds_read_b128 v[12:15], v12
	v_mul_f32_e32 v17, 0xbfb8aa3b, v16
	v_add_f32_e32 v18, 1.0, v18
	v_rcp_f32_e32 v18, v18
	v_exp_f32_e32 v17, v17
	s_waitcnt lgkmcnt(0)
	v_lshlrev_b32_e32 v19, 16, v12
	v_and_b32_e32 v12, 0xffff0000, v12
	v_mul_f32_e32 v8, v18, v8
	v_mul_f32_e32 v8, v8, v12
	v_lshlrev_b32_e32 v12, 16, v9
	v_and_b32_e32 v9, 0xffff0000, v9
	v_add_f32_e32 v17, 1.0, v17
	v_mul_f32_e32 v18, 0xbfb8aa3b, v9
	v_rcp_f32_e32 v17, v17
	v_exp_f32_e32 v18, v18
	v_mul_f32_e32 v16, v17, v16
	v_mul_f32_e32 v17, 0xbfb8aa3b, v12
	v_add_f32_e32 v18, 1.0, v18
	v_exp_f32_e32 v17, v17
	v_rcp_f32_e32 v18, v18
	v_mul_f32_e32 v16, v16, v19
	v_lshlrev_b32_e32 v19, 16, v13
	v_add_f32_e32 v17, 1.0, v17
	v_and_b32_e32 v13, 0xffff0000, v13
	v_mul_f32_e32 v9, v18, v9
	v_rcp_f32_e32 v17, v17
	v_mul_f32_e32 v9, v9, v13
	v_lshlrev_b32_e32 v13, 16, v10
	v_and_b32_e32 v10, 0xffff0000, v10
	v_mul_f32_e32 v18, 0xbfb8aa3b, v10
	v_exp_f32_e32 v18, v18
	v_mul_f32_e32 v12, v17, v12
	v_mul_f32_e32 v17, 0xbfb8aa3b, v13
	v_exp_f32_e32 v17, v17
	v_add_f32_e32 v18, 1.0, v18
	v_rcp_f32_e32 v18, v18
	v_mul_f32_e32 v12, v12, v19
	v_add_f32_e32 v17, 1.0, v17
	v_rcp_f32_e32 v17, v17
	v_lshlrev_b32_e32 v19, 16, v14
	v_and_b32_e32 v14, 0xffff0000, v14
	v_mul_f32_e32 v10, v18, v10
	v_mul_f32_e32 v10, v10, v14
	v_lshlrev_b32_e32 v14, 16, v11
	v_and_b32_e32 v11, 0xffff0000, v11
	v_mul_f32_e32 v18, 0xbfb8aa3b, v11
	v_mul_f32_e32 v13, v17, v13
	v_mul_f32_e32 v17, 0xbfb8aa3b, v14
	v_exp_f32_e32 v18, v18
	v_exp_f32_e32 v17, v17
	v_mul_f32_e32 v13, v13, v19
	v_lshlrev_b32_e32 v19, 16, v15
	v_add_f32_e32 v18, 1.0, v18
	v_add_f32_e32 v17, 1.0, v17
	v_rcp_f32_e32 v18, v18
	v_rcp_f32_e32 v17, v17
	v_and_b32_e32 v15, 0xffff0000, v15
	v_cvt_pk_bf16_f32 v8, v16, v8
	v_mul_f32_e32 v11, v18, v11
	v_cvt_pk_bf16_f32 v9, v12, v9
	v_cvt_pk_bf16_f32 v10, v13, v10
	v_lshlrev_b64 v[12:13], 12, v[26:27]
	v_mul_f32_e32 v14, v17, v14
	v_mul_f32_e32 v11, v11, v15
	v_lshl_add_u64 v[12:13], v[22:23], 0, v[12:13]
	v_mul_f32_e32 v14, v14, v19
	v_cvt_pk_bf16_f32 v11, v14, v11
	global_store_dwordx4 v[12:13], v[8:11], off
	s_waitcnt vmcnt(7)
	v_lshlrev_b32_e32 v12, 16, v4
	v_and_b32_e32 v4, 0xffff0000, v4
	v_mul_f32_e32 v14, 0xbfb8aa3b, v4
	v_exp_f32_e32 v14, v14
	v_add_u32_e32 v8, v36, v210
	ds_read_b128 v[8:11], v8
	v_mul_f32_e32 v13, 0xbfb8aa3b, v12
	v_add_f32_e32 v14, 1.0, v14
	v_rcp_f32_e32 v14, v14
	v_exp_f32_e32 v13, v13
	s_waitcnt lgkmcnt(0)
; __device__ __forceinline__ float bf2f(short s) { return __uint_as_float(((unsigned)(unsigned short)s) << 16); }
; __device__ __forceinline__ float silu_fast(float g) { return g * __builtin_amdgcn_rcpf(1.f + __builtin_amdgcn_exp2f(-g * LOG2E)); }
; __device__ __forceinline__ bf16x8 tobf8(f32x8 x) { u32x4 w = {cvtpk(x[0], x[1]), cvtpk(x[2], x[3]), cvtpk(x[4], x[5]), cvtpk(x[6], x[7])}; return *reinterpret_cast<bf16x8*>(&w); }
; template <int MODE, bool SAMPLE>
; __device__ __forceinline__ void attn_unit(const Params& p, char* lds, int b, int h, int qb) {
;     ...
;         for (int it = 0; it < NIT; ++it) { const int row = it * 4 + er; const bf16x8 mx = *(const bf16x8*)(Qs + row * 256 + ec * 2); f32x8 y;
; #pragma unroll
;             for (int i = 0; i < 8; ++i) y[i] = bf2f(mx[i]) * silu_fast(bf2f(gt[it][i]));
;             *(bf16x8*)(MIX + (rbase + row) * DM + MODE * 1024 + h * HD + ec) = tobf8(y); }
;     }
;     __syncthreads();
	v_lshlrev_b32_e32 v15, 16, v8
	v_and_b32_e32 v8, 0xffff0000, v8
	v_mul_f32_e32 v4, v14, v4
	v_mul_f32_e32 v4, v4, v8
	v_lshlrev_b32_e32 v8, 16, v5
	v_and_b32_e32 v5, 0xffff0000, v5
	v_add_f32_e32 v13, 1.0, v13
	v_mul_f32_e32 v14, 0xbfb8aa3b, v5
	v_rcp_f32_e32 v13, v13
	v_exp_f32_e32 v14, v14
	v_mul_f32_e32 v12, v13, v12
	v_mul_f32_e32 v13, 0xbfb8aa3b, v8
	v_add_f32_e32 v14, 1.0, v14
	v_exp_f32_e32 v13, v13
	v_rcp_f32_e32 v14, v14
	v_mul_f32_e32 v12, v12, v15
	v_lshlrev_b32_e32 v15, 16, v9
	v_add_f32_e32 v13, 1.0, v13
	v_and_b32_e32 v9, 0xffff0000, v9
	v_mul_f32_e32 v5, v14, v5
	v_rcp_f32_e32 v13, v13
	v_mul_f32_e32 v5, v5, v9
	v_lshlrev_b32_e32 v9, 16, v6
	v_and_b32_e32 v6, 0xffff0000, v6
	v_mul_f32_e32 v14, 0xbfb8aa3b, v6
	v_exp_f32_e32 v14, v14
	v_mul_f32_e32 v8, v13, v8
	v_mul_f32_e32 v13, 0xbfb8aa3b, v9
	v_exp_f32_e32 v13, v13
	v_add_f32_e32 v14, 1.0, v14
	v_rcp_f32_e32 v14, v14
	v_mul_f32_e32 v8, v8, v15
	v_add_f32_e32 v13, 1.0, v13
	v_rcp_f32_e32 v13, v13
	v_lshlrev_b32_e32 v15, 16, v10
	v_and_b32_e32 v10, 0xffff0000, v10
	v_mul_f32_e32 v6, v14, v6
	v_mul_f32_e32 v6, v6, v10
	v_lshlrev_b32_e32 v10, 16, v7
	v_and_b32_e32 v7, 0xffff0000, v7
	v_mul_f32_e32 v14, 0xbfb8aa3b, v7
	v_mul_f32_e32 v9, v13, v9
	v_mul_f32_e32 v13, 0xbfb8aa3b, v10
	v_exp_f32_e32 v14, v14
	v_exp_f32_e32 v13, v13
	v_mul_f32_e32 v9, v9, v15
	v_lshlrev_b32_e32 v15, 16, v11
	v_add_f32_e32 v14, 1.0, v14
	v_add_f32_e32 v13, 1.0, v13
	v_rcp_f32_e32 v14, v14
	v_rcp_f32_e32 v13, v13
	v_and_b32_e32 v11, 0xffff0000, v11
	v_cvt_pk_bf16_f32 v4, v12, v4
	v_mul_f32_e32 v7, v14, v7
	v_cvt_pk_bf16_f32 v5, v8, v5
	v_cvt_pk_bf16_f32 v6, v9, v6
	v_lshlrev_b64 v[8:9], 12, v[24:25]
	v_mul_f32_e32 v10, v13, v10
	v_mul_f32_e32 v7, v7, v11
	v_lshl_add_u64 v[8:9], v[22:23], 0, v[8:9]
	v_mul_f32_e32 v10, v10, v15
	v_cvt_pk_bf16_f32 v7, v10, v7
	global_store_dwordx4 v[8:9], v[4:7], off
	s_waitcnt vmcnt(7)
	v_lshlrev_b32_e32 v8, 16, v0
	v_and_b32_e32 v0, 0xffff0000, v0
	v_mul_f32_e32 v10, 0xbfb8aa3b, v0
	v_exp_f32_e32 v10, v10
	v_add_u32_e32 v4, v36, v211
	ds_read_b128 v[4:7], v4
	v_mul_f32_e32 v9, 0xbfb8aa3b, v8
	v_add_f32_e32 v10, 1.0, v10
	v_rcp_f32_e32 v10, v10
	v_exp_f32_e32 v9, v9
	s_waitcnt lgkmcnt(0)
	v_lshlrev_b32_e32 v11, 16, v4
	v_and_b32_e32 v4, 0xffff0000, v4
	v_mul_f32_e32 v0, v10, v0
	v_mul_f32_e32 v0, v0, v4
	v_lshlrev_b32_e32 v4, 16, v1
	v_and_b32_e32 v1, 0xffff0000, v1
	v_add_f32_e32 v9, 1.0, v9
	v_mul_f32_e32 v10, 0xbfb8aa3b, v1
	v_rcp_f32_e32 v9, v9
	v_exp_f32_e32 v10, v10
	v_mul_f32_e32 v8, v9, v8
	v_mul_f32_e32 v9, 0xbfb8aa3b, v4
	v_add_f32_e32 v10, 1.0, v10
	v_exp_f32_e32 v9, v9
	v_rcp_f32_e32 v10, v10
	v_mul_f32_e32 v8, v8, v11
	v_lshlrev_b32_e32 v11, 16, v5
	v_add_f32_e32 v9, 1.0, v9
	v_and_b32_e32 v5, 0xffff0000, v5
	v_mul_f32_e32 v1, v10, v1
	v_rcp_f32_e32 v9, v9
	v_mul_f32_e32 v1, v1, v5
	v_lshlrev_b32_e32 v5, 16, v2
	v_and_b32_e32 v2, 0xffff0000, v2
	v_mul_f32_e32 v10, 0xbfb8aa3b, v2
	v_exp_f32_e32 v10, v10
	v_mul_f32_e32 v4, v9, v4
	v_mul_f32_e32 v9, 0xbfb8aa3b, v5
	v_exp_f32_e32 v9, v9
	v_add_f32_e32 v10, 1.0, v10
	v_rcp_f32_e32 v10, v10
	v_mul_f32_e32 v4, v4, v11
	v_add_f32_e32 v9, 1.0, v9
	v_rcp_f32_e32 v9, v9
	v_lshlrev_b32_e32 v11, 16, v6
	v_and_b32_e32 v6, 0xffff0000, v6
	v_mul_f32_e32 v2, v10, v2
	v_mul_f32_e32 v2, v2, v6
	v_lshlrev_b32_e32 v6, 16, v3
	v_and_b32_e32 v3, 0xffff0000, v3
	v_mul_f32_e32 v10, 0xbfb8aa3b, v3
	v_mul_f32_e32 v5, v9, v5
	v_mul_f32_e32 v9, 0xbfb8aa3b, v6
	v_exp_f32_e32 v10, v10
	v_exp_f32_e32 v9, v9
	v_mul_f32_e32 v5, v5, v11
	v_lshlrev_b32_e32 v11, 16, v7
	v_add_f32_e32 v10, 1.0, v10
	v_add_f32_e32 v9, 1.0, v9
	v_rcp_f32_e32 v10, v10
	v_rcp_f32_e32 v9, v9
	v_and_b32_e32 v7, 0xffff0000, v7
	v_cvt_pk_bf16_f32 v0, v8, v0
	v_mul_f32_e32 v3, v10, v3
	v_cvt_pk_bf16_f32 v1, v4, v1
	v_cvt_pk_bf16_f32 v2, v5, v2
	v_lshlrev_b64 v[4:5], 12, v[20:21]
	v_mul_f32_e32 v6, v9, v6
	v_mul_f32_e32 v3, v3, v7
	v_lshl_add_u64 v[4:5], v[22:23], 0, v[4:5]
	v_mul_f32_e32 v6, v6, v11
	v_cvt_pk_bf16_f32 v3, v6, v3
	global_store_dwordx4 v[4:5], v[0:3], off
	s_barrier
; __device__ __forceinline__ int crow(int r, int hi) { return (r & 3) + 8 * (r >> 2) + 4 * hi; }
; __device__ __forceinline__ int v_st(int k, int c) { const int kk = (k & ~0xC) | ((k & 4) << 1) | ((k & 8) >> 1); return ((kk >> 3) * 4 + (c >> 5)) * 512 + ((kk & 7) * 32 + (c & 31)) * 2; }
; __device__ __forceinline__ int v_rd_base(int lane) { return ((lane & 3) << 3) | (((lane >> 2) & 3) << 6) | (((lane >> 4) & 1) << 5) | (((lane >> 5) & 1) << 8); }
; template <int MODE, bool SAMPLE>
; __device__ __forceinline__ void attn_unit(const Params& p, char* lds, int b, int h, int qb) {
;     ...
;     const bf16_t* P1q = P1 + (size_t)((MODE ? 32 : 0) + h) * HB;
;     const size_t qrow = SAMPLE ? (size_t)(MP + b * TS + (r32 & 15)) : (size_t)(b * SEQ + qb * 256 + wid * 32 + r32);
;     const bf16_t* Qw = P1q + qrow * 128 + hi * 8;
;     char* Qs = lds + AL_Q + wid * 8192;
; #pragma unroll
;     for (int d0 = 0; d0 < 8; ++d0) *reinterpret_cast<bf16x8*>(Qs + KSWZ(r32, (d0 * 16 + hi * 8) * 2)) = *reinterpret_cast<const bf16x8*>(Qw + d0 * 16);
;     const int qw0 = SAMPLE ? PAST : qb * 256 + wid * 32;
;     const int qpos = SAMPLE ? PAST + (r32 & 15) : qw0 + r32;
;     const int jd = SAMPLE ? 16 : (qw0 >> 6);
;     const int jfirst = SAMPLE ? 16 : qb * 4 + 3;
;     const bool wact = SAMPLE ? (wid == 0) : true;
;     const int sr = tid >> 4, sc = (tid & 15) * 8;
;     const int vst0 = v_st(sr, sc), vst1 = v_st(32 + sr, sc), kst0 = KSWZ(sr, sc * 2), kst1 = KSWZ(32 + sr, sc * 2);
;     const int vb0 = (int)(uintptr_t)V_lds + v_rd_base(lane);
;     struct StgT { bf16x8 k0, k1, v0, v1; f32x8 fk0, fk1, fv0, fv1; } stg2[SAMPLE ? 1 : NSP];
;     ...
;     f32x16 o[4] = {};
;     float m_reg = -1e30f, l_reg = 0.f, carry = 1.f;
;     constexpr int NS = SAMPLE ? 1 : NSP;
;     constexpr int PAR0 = SAMPLE ? 0 : 1;
;     LOADT(jfirst, stg2[NS == 2 ? PAR0 : 0]); if (NS == 2) LOADT(jfirst - 1, stg2[NS == 2 ? (PAR0 ^ 1) : 0]);
;     ...
;                 if (j == jd) {
; #pragma unroll
;                     for (int r = 0; r < 16; ++r) { const int kp = j * 64 + crow(r, hi); if (kp >= qpos) p0[r] = -1e30f; if (kp + 32 >= qpos) p1[r] = -1e30f; } }
	s_nop 0
	v_or_b32_e32 v0, s9, v131
	v_mov_b32_e32 v1, v129
	v_lshlrev_b64 v[0:1], 8, v[0:1]
	v_lshl_add_u64 v[0:1], s[82:83], 0, v[0:1]
	v_lshl_add_u64 v[4:5], v[0:1], 0, v[148:149]
	v_add_co_u32_e32 v0, vcc, s0, v4
	s_nop 1
	v_addc_co_u32_e32 v1, vcc, 0, v5, vcc
	global_load_dwordx4 v[0:3], v[0:1], off
	s_mov_b64 s[0:1], 0xcf00000
	v_lshl_add_u64 v[28:29], v[4:5], 0, s[0:1]
	global_load_dwordx4 v[4:7], v[28:29], off offset:32
	global_load_dwordx4 v[8:11], v[28:29], off offset:64
	global_load_dwordx4 v[12:15], v[28:29], off offset:96
	global_load_dwordx4 v[16:19], v[28:29], off offset:128
	global_load_dwordx4 v[20:23], v[28:29], off offset:160
	global_load_dwordx4 v[24:27], v[28:29], off offset:192
	s_nop 0
	global_load_dwordx4 v[28:31], v[28:29], off offset:224
	s_lshl_b32 s0, s10, 13
	s_add_i32 s10, s0, 0
	s_add_i32 s10, s10, 0x13000
	v_add_u32_e32 v32, s10, v133
	v_add_u32_e32 v33, v32, v139
	s_lshl_b32 s0, s2, 2
	s_or_b32 s14, s0, 3
	s_add_u32 s0, s82, 0xe000000
	s_addc_u32 s1, s83, 0
	s_lshl_b32 s2, s14, 6
	s_add_i32 s2, s2, s20
	s_lshl_b64 s[16:17], s[2:3], 8
	s_add_u32 s16, s0, s16
	s_addc_u32 s17, s1, s17
	s_add_i32 s2, s21, s15
	v_lshl_add_u64 v[160:161], s[0:1], 0, v[146:147]
	s_waitcnt vmcnt(7)
	ds_write_b128 v33, v[0:3]
	v_add_u32_e32 v0, v32, v141
	s_waitcnt vmcnt(6)
	ds_write_b128 v0, v[4:7]
	v_add_u32_e32 v0, v32, v143
	s_waitcnt vmcnt(5)
	ds_write_b128 v0, v[8:11]
	v_add_u32_e32 v0, v32, v151
	s_waitcnt vmcnt(4)
	ds_write_b128 v0, v[12:15]
	v_add_u32_e32 v0, v32, v153
	s_waitcnt vmcnt(3)
	ds_write_b128 v0, v[16:19]
	v_add_u32_e32 v0, v32, v170
	s_waitcnt vmcnt(2)
	ds_write_b128 v0, v[20:23]
	v_add_u32_e32 v0, v32, v171
	s_waitcnt vmcnt(1)
	ds_write_b128 v0, v[24:27]
	v_add_u32_e32 v0, v32, v172
	s_waitcnt vmcnt(0)
	ds_write_b128 v0, v[28:31]
	v_lshl_add_u64 v[0:1], s[16:17], 0, v[146:147]
	s_lshl_b64 s[16:17], s[2:3], 8
	v_lshl_add_u64 v[2:3], v[0:1], 0, v[128:129]
	v_lshl_add_u64 v[4:5], v[0:1], 0, v[158:159]
	v_lshl_add_u64 v[0:1], v[0:1], 0, s[86:87]
	s_add_u32 s16, s0, s16
	global_load_dwordx4 v[96:99], v[2:3], off
	global_load_dwordx4 v[100:103], v[4:5], off
	v_lshl_add_u64 v[2:3], v[0:1], 0, v[128:129]
	v_lshl_add_u64 v[0:1], v[0:1], 0, v[158:159]
	s_addc_u32 s17, s1, s17
	global_load_dwordx4 v[104:107], v[2:3], off
	global_load_dwordx4 v[108:111], v[0:1], off
	v_lshl_add_u64 v[0:1], s[16:17], 0, v[146:147]
	v_lshl_add_u64 v[2:3], v[0:1], 0, v[128:129]
	v_lshl_add_u64 v[4:5], v[0:1], 0, v[158:159]
	v_lshl_add_u64 v[0:1], v[0:1], 0, s[86:87]
	global_load_dwordx4 v[112:115], v[2:3], off
	global_load_dwordx4 v[116:119], v[4:5], off
	v_lshl_add_u64 v[2:3], v[0:1], 0, v[128:129]
	v_lshl_add_u64 v[0:1], v[0:1], 0, v[158:159]
	global_load_dwordx4 v[120:123], v[2:3], off
	global_load_dwordx4 v[124:127], v[0:1], off
	v_or_b32_e32 v6, s18, v131
	s_andn2_b32 s18, s18, 63
	v_or_b32_e32 v0, s18, v180
	v_or_b32_e32 v1, 32, v0
	v_cmp_lt_i32_e64 s[0:1], v1, v6
	v_or_b32_e32 v1, 1, v0
	v_cmp_lt_i32_e64 s[16:17], v1, v6
	v_or_b32_e32 v1, 33, v0
	v_cmp_lt_i32_e64 s[18:19], v1, v6
	v_or_b32_e32 v1, 2, v0
	v_cmp_lt_i32_e64 s[20:21], v1, v6
	v_or_b32_e32 v1, 34, v0
	v_cmp_lt_i32_e64 s[22:23], v1, v6
	v_or_b32_e32 v1, 3, v0
	v_cmp_lt_i32_e64 s[24:25], v1, v6
	v_or_b32_e32 v1, 35, v0
	v_cmp_lt_i32_e64 s[26:27], v1, v6
	v_or_b32_e32 v1, 8, v0
	v_cmp_lt_i32_e64 s[28:29], v1, v6
	v_or_b32_e32 v1, 40, v0
	v_cmp_lt_i32_e64 s[30:31], v1, v6
	v_or_b32_e32 v1, 9, v0
	v_cmp_lt_i32_e64 s[34:35], v1, v6
	v_or_b32_e32 v1, 41, v0
	v_cmp_lt_i32_e64 s[36:37], v1, v6
	v_or_b32_e32 v1, 10, v0
	v_cmp_lt_i32_e64 s[38:39], v1, v6
	v_or_b32_e32 v1, 42, v0
	v_cmp_lt_i32_e64 s[40:41], v1, v6
	v_or_b32_e32 v1, 11, v0
	v_cmp_lt_i32_e64 s[42:43], v1, v6
	v_or_b32_e32 v1, 43, v0
	v_cmp_lt_i32_e64 s[44:45], v1, v6
	v_or_b32_e32 v1, 16, v0
	v_cmp_lt_i32_e64 s[46:47], v1, v6
	v_or_b32_e32 v1, 48, v0
	v_cmp_lt_i32_e64 s[48:49], v1, v6
	v_or_b32_e32 v1, 17, v0
	v_cmp_lt_i32_e64 s[50:51], v1, v6
	v_or_b32_e32 v1, 49, v0
	v_cmp_lt_i32_e64 s[52:53], v1, v6
	v_or_b32_e32 v1, 18, v0
	v_cmp_lt_i32_e64 s[54:55], v1, v6
	v_or_b32_e32 v1, 50, v0
	v_cmp_lt_i32_e64 s[56:57], v1, v6
	v_or_b32_e32 v1, 19, v0
	v_cmp_lt_i32_e64 s[58:59], v1, v6
	v_or_b32_e32 v1, 51, v0
	v_cmp_lt_i32_e64 s[60:61], v1, v6
	v_or_b32_e32 v1, 24, v0
	v_cmp_lt_i32_e64 s[62:63], v1, v6
	v_or_b32_e32 v1, 56, v0
	v_cmp_lt_i32_e64 s[64:65], v1, v6
	v_or_b32_e32 v1, 25, v0
	v_cmp_lt_i32_e64 s[66:67], v1, v6
	v_or_b32_e32 v1, 57, v0
	v_cmp_lt_i32_e64 s[68:69], v1, v6
	v_or_b32_e32 v1, 26, v0
	s_lshr_b32 s2, s14, 1
	v_cmp_lt_i32_e64 s[70:71], v1, v6
	v_or_b32_e32 v1, 58, v0
	v_cmp_lt_i32_e32 vcc, v0, v6
	v_cmp_lt_i32_e64 s[72:73], v1, v6
	v_or_b32_e32 v1, 27, v0
	v_or_b32_e32 v0, 59, v0
	s_lshl_b32 s15, s2, 7
	v_mov_b32_e32 v14, v129
	v_mov_b32_e32 v15, v129
	v_cmp_lt_i32_e64 s[74:75], v1, v6
	v_cmp_lt_i32_e64 s[76:77], v0, v6
	s_add_i32 s15, s33, s15
	v_mov_b32_e32 v0, v129
	v_mov_b32_e32 v1, v129
	v_mov_b32_e32 v2, v129
	v_mov_b32_e32 v3, v129
	v_mov_b32_e32 v4, v129
	v_mov_b32_e32 v5, v129
	v_mov_b32_e32 v6, v129
	v_mov_b32_e32 v7, v129
	v_mov_b32_e32 v8, v129
	v_mov_b32_e32 v9, v129
	v_mov_b32_e32 v10, v129
	v_mov_b32_e32 v11, v129
	v_mov_b32_e32 v12, v129
	v_mov_b32_e32 v13, v129
	v_mov_b64_e32 v[30:31], v[14:15]
	v_mov_b64_e32 v[46:47], v[14:15]
	v_mov_b64_e32 v[62:63], v[14:15]
	s_add_i32 s80, s15, 0xffffff80
	s_sub_i32 s15, 0, s2
	s_and_b32 s33, s14, 0x7ffffffe
	s_add_i32 s97, s11, -1
	v_mov_b32_e32 v147, 1.0
	v_mov_b64_e32 v[28:29], v[12:13]
	v_mov_b64_e32 v[26:27], v[10:11]
	v_mov_b64_e32 v[24:25], v[8:9]
	v_mov_b64_e32 v[22:23], v[6:7]
	v_mov_b64_e32 v[20:21], v[4:5]
	v_mov_b64_e32 v[18:19], v[2:3]
	v_mov_b64_e32 v[16:17], v[0:1]
	v_mov_b64_e32 v[44:45], v[12:13]
	v_mov_b64_e32 v[42:43], v[10:11]
	v_mov_b64_e32 v[40:41], v[8:9]
	v_mov_b64_e32 v[38:39], v[6:7]
	v_mov_b64_e32 v[36:37], v[4:5]
	v_mov_b64_e32 v[34:35], v[2:3]
	v_mov_b64_e32 v[32:33], v[0:1]
	v_mov_b64_e32 v[60:61], v[12:13]
	v_mov_b64_e32 v[58:59], v[10:11]
	v_mov_b64_e32 v[56:57], v[8:9]
	v_mov_b64_e32 v[54:55], v[6:7]
	v_mov_b64_e32 v[52:53], v[4:5]
	v_mov_b64_e32 v[50:51], v[2:3]
	v_mov_b64_e32 v[48:49], v[0:1]
	s_branch .LBB0_783

; template <int MODE, bool SAMPLE>
; __device__ __forceinline__ void attn_unit(const Params& p, char* lds, int b, int h, int qb) {
;     ...
;         if (j > jfirst) continue;
;         const int buf = par;
;         WRITET(buf, stg2[NS == 2 ? par : 0]);
;         if (j >= NS) LOADT(j - NS, stg2[NS == 2 ? par : 0]);
.LBB0_783:
	s_cmp_ge_u32 s33, s14
	v_add_u32_e32 v198, v204, v202
	v_add_u32_e32 v199, v205, v202
	v_add_u32_e32 v200, v206, v203
	v_add_u32_e32 v201, v207, v203
	s_cbranch_scc1 .Lph_3
	s_cmp_eq_u32 s15, 0
	s_waitcnt vmcnt(7)
	ds_write_b128 v198, v[96:99] offset:16384
	s_waitcnt vmcnt(6)
	ds_write_b128 v199, v[100:103] offset:16384
	s_waitcnt vmcnt(5)
	ds_write_b128 v200, v[104:107] offset:49152
	s_waitcnt vmcnt(4)
	ds_write_b128 v201, v[108:111] offset:49152
	s_cbranch_scc1 .Lpd_3
	s_add_i32 s2, s80, 64
	s_lshl_b64 s[78:79], s[2:3], 8
	v_lshl_add_u64 v[64:65], v[160:161], 0, s[78:79]
	v_mov_b32_e32 v159, v129
	v_lshl_add_u64 v[66:67], v[64:65], 0, v[128:129]
	v_lshl_add_u64 v[68:69], v[64:65], 0, v[158:159]
	v_lshl_add_u64 v[64:65], v[64:65], 0, s[86:87]
	global_load_dwordx4 v[96:99], v[66:67], off
	global_load_dwordx4 v[100:103], v[68:69], off
	v_lshl_add_u64 v[66:67], v[64:65], 0, v[128:129]
	v_lshl_add_u64 v[64:65], v[64:65], 0, v[158:159]
	global_load_dwordx4 v[104:107], v[66:67], off
	global_load_dwordx4 v[108:111], v[64:65], off
	s_branch .LBB0_786

; template <int MODE, bool SAMPLE>
; __device__ __forceinline__ void attn_unit(const Params& p, char* lds, int b, int h, int qb) {
;     ...
;         if (j > jfirst) continue;
;         const int buf = par;
;         WRITET(buf, stg2[NS == 2 ? par : 0]);
;         if (j >= NS) LOADT(j - NS, stg2[NS == 2 ? par : 0]);
.LBB0_790:
	s_cmp_gt_u32 s33, s14
	s_cbranch_scc1 .LBB0_782
	s_cmp_eq_u32 s15, 0
	s_waitcnt vmcnt(7)
	ds_write_b128 v198, v[112:115]
	s_waitcnt vmcnt(6)
	ds_write_b128 v199, v[116:119]
	s_waitcnt vmcnt(5)
	ds_write_b128 v200, v[120:123] offset:32768
	s_waitcnt vmcnt(4)
	ds_write_b128 v201, v[124:127] offset:32768
	s_cbranch_scc1 .LBB0_793
	s_mov_b32 s81, s3
	s_lshl_b64 s[78:79], s[80:81], 8
	v_lshl_add_u64 v[64:65], v[160:161], 0, s[78:79]
	v_mov_b32_e32 v159, v129
	v_lshl_add_u64 v[66:67], v[64:65], 0, v[128:129]
	v_lshl_add_u64 v[68:69], v[64:65], 0, v[158:159]
	v_lshl_add_u64 v[64:65], v[64:65], 0, s[86:87]
	global_load_dwordx4 v[112:115], v[66:67], off
	global_load_dwordx4 v[116:119], v[68:69], off
	v_lshl_add_u64 v[66:67], v[64:65], 0, v[128:129]
	v_lshl_add_u64 v[64:65], v[64:65], 0, v[158:159]
	global_load_dwordx4 v[120:123], v[66:67], off
	global_load_dwordx4 v[124:127], v[64:65], off
